# combo: EpiUp ACT stores widened to dwordx4, EpiRes ssq atomics coalesced 4to1, first two K-loop vmcnt waits skipped after an epilogue (up/outproj/down)
# speedup vs baseline: 1.0050x; 1.0050x over previous
.LBB0_680:
	s_mov_b32 s98, 0
	s_or_b64 exec, exec, s[2:3]
	v_readlane_b32 s2, v254, 28
	v_readlane_b32 s4, v253, 10
	s_lshl_b32 s80, s2, 16
	s_mov_b64 s[2:3], s[84:85]
	v_mov_b32_e32 v0, v165
	v_mov_b32_e32 v16, v165
	v_readlane_b32 s5, v253, 11
	s_waitcnt lgkmcnt(0)
	s_barrier
	s_and_b64 vcc, exec, s[4:5]
	v_readfirstlane_b32 s6, v16
	s_mov_b32 s77, 0x800000
	s_cbranch_vccz .LBB0_716
	v_lshlrev_b32_e32 v0, 4, v16
	v_add_u32_e32 v2, 0x2000, v0
	v_ashrrev_i32_e32 v3, 31, v2
	v_lshrrev_b32_e32 v3, 22, v3
	v_add_u32_e32 v3, v2, v3
	v_ashrrev_i32_e32 v10, 10, v3
	s_load_dwordx2 s[4:5], s[2:3], 0x90
	v_mul_i32_i24_e32 v3, 0x400, v10
	v_sub_u32_e32 v2, v2, v3
	v_lshrrev_b32_e32 v3, 4, v2
	v_bitop3_b32 v2, v3, v2, 32 bitop3:0x6c
	v_ashrrev_i32_e32 v3, 31, v2
	s_waitcnt lgkmcnt(0)
	s_add_u32 s28, s4, 0x15100000
	v_lshrrev_b32_e32 v3, 26, v3
	s_addc_u32 s29, s5, 0
	s_lshl_b32 s2, s33, 1
	v_add_u32_e32 v3, v2, v3
	v_lshlrev_b32_e32 v4, 3, v10
	s_add_u32 s2, s4, s2
	v_ashrrev_i32_e32 v11, 6, v3
	v_and_b32_e32 v4, -16, v4
	s_addc_u32 s3, s5, 0
	v_add_u32_e32 v4, v11, v4
	s_add_u32 s30, s2, 0xd00000
	v_and_b32_e32 v5, 3, v11
	s_mov_b32 s2, 0x1fffe0
	v_lshrrev_b32_e32 v6, 2, v4
	v_lshlrev_b32_e32 v7, 1, v4
	v_and_or_b32 v5, v4, s2, v5
	v_and_b32_e32 v6, 4, v6
	v_and_b32_e32 v7, 24, v7
	v_and_b32_e32 v3, 0xc0, v3
	v_or3_b32 v5, v5, v6, v7
	v_sub_u32_e32 v2, v2, v3
	v_mov_b32_e32 v7, 1
	v_lshlrev_b32_e32 v6, 5, v10
	v_ashrrev_i16_sdwa v2, v7, sext(v2) dst_sel:DWORD dst_unused:UNUSED_PAD src0_sel:DWORD src1_sel:BYTE_0
	v_and_b32_e32 v6, 32, v6
	v_bfe_i32 v12, v2, 0, 16
	v_add_lshl_u32 v2, v6, v12, 1
	v_lshl_add_u32 v154, v5, 11, v2
	v_lshl_add_u32 v156, v4, 11, v2
	v_bfe_i32 v2, v16, 27, 1
	v_lshrrev_b32_e32 v2, 22, v2
	v_add_u32_e32 v2, v0, v2
	v_and_b32_e32 v2, 0xfffffc00, v2
	v_sub_u32_e32 v0, v0, v2
	v_lshrrev_b32_e32 v2, 4, v0
	v_bitop3_b32 v2, v2, v0, 32 bitop3:0x6c
	v_ashrrev_i32_e32 v0, 31, v0
	v_lshrrev_b32_e32 v0, 26, v0
	v_add_u32_e32 v0, v2, v0
	v_ashrrev_i32_e32 v13, 6, v0
	v_ashrrev_i32_e32 v0, 31, v16
	v_lshrrev_b32_e32 v0, 26, v0
	v_add_u32_e32 v0, v16, v0
	v_ashrrev_i32_e32 v14, 6, v0
	v_lshlrev_b32_e32 v0, 3, v14
	v_and_b32_e32 v0, -16, v0
	v_add_u32_e32 v3, v13, v0
	v_and_b32_e32 v0, 3, v13
	v_lshrrev_b32_e32 v4, 2, v3
	v_lshlrev_b32_e32 v5, 1, v3
	v_and_or_b32 v0, v3, s2, v0
	v_and_b32_e32 v4, 4, v4
	v_and_b32_e32 v5, 24, v5
	v_or3_b32 v0, v0, v4, v5
	v_mul_i32_i24_e32 v5, 64, v13
	s_addc_u32 s31, s3, 0
	s_ashr_i32 s7, s6, 6
	v_sub_u32_e32 v2, v2, v5
	s_ashr_i32 s12, s6, 8
	s_lshl_b32 s33, s7, 10
	v_lshlrev_b32_e32 v4, 5, v14
	v_ashrrev_i16_sdwa v2, v7, sext(v2) dst_sel:DWORD dst_unused:UNUSED_PAD src0_sel:DWORD src1_sel:BYTE_0
	v_readlane_b32 s2, v253, 41
	v_and_b32_e32 v4, 32, v4
	v_bfe_i32 v15, v2, 0, 16
	v_readlane_b32 s3, v253, 42
	s_add_u32 s24, s30, s2
	v_add_lshl_u32 v2, v4, v15, 1
	s_addc_u32 s25, s31, s3
	s_add_i32 s34, s33, 0
	v_lshl_add_u32 v0, v0, 11, v2
	s_add_i32 m0, s34, 0x10000
	v_lshl_add_u32 v166, v3, 11, v2
	global_load_lds_dwordx4 v0, s[24:25]
	s_add_i32 m0, s34, 0x12000
	s_add_u32 s2, s24, 0x40000
	global_load_lds_dwordx4 v154, s[24:25]
	s_addc_u32 s3, s25, 0
	s_add_i32 m0, s34, 0x14000
	v_mov_b32_e32 v155, v1
	global_load_lds_dwordx4 v0, s[2:3]
	s_add_i32 m0, s34, 0x16000
	v_mov_b32_e32 v167, v1
	global_load_lds_dwordx4 v154, s[2:3]
	v_readlane_b32 s2, v253, 39
	v_readlane_b32 s3, v253, 40
	s_add_u32 s22, s28, s2
	s_addc_u32 s23, s29, s3
	s_add_i32 s35, s34, 0x2000
	s_mov_b32 m0, s34
	s_add_u32 s2, s22, 0x40000
	global_load_lds_dwordx4 v166, s[22:23]
	s_mov_b32 m0, s35
	s_addc_u32 s3, s23, 0
	s_add_i32 s36, s34, 0x4000
	global_load_lds_dwordx4 v156, s[22:23]
	s_mov_b32 m0, s36
	s_add_i32 s37, s34, 0x6000
	global_load_lds_dwordx4 v166, s[2:3]
	s_mov_b32 m0, s37
	v_mov_b32_e32 v157, v1
	global_load_lds_dwordx4 v156, s[2:3]
	s_cmp_eq_u32 s12, 1
	v_mov_b32_e32 v252, 1
	v_lshl_add_u64 v[8:9], s[24:25], 0, v[0:1]
	v_lshl_add_u64 v[6:7], s[24:25], 0, v[154:155]
	v_lshl_add_u64 v[2:3], s[22:23], 0, v[166:167]
	s_cselect_b64 s[2:3], -1, 0
	s_cmp_lg_u32 s12, 1
	v_lshl_add_u64 v[4:5], s[22:23], 0, v[156:157]
	s_cbranch_scc1 .LBB0_683
	s_barrier

.LBB0_692:
	s_ashr_i32 s17, s16, 31
	s_lshl_b64 s[18:19], s[16:17], 19
	s_add_u32 s18, s28, s18
	s_addc_u32 s19, s29, s19
	s_and_b64 s[20:21], s[6:7], exec
	s_cselect_b32 s17, s19, s23
	s_cselect_b32 s43, s18, s22
	s_ashr_i32 s15, s14, 31
	s_lshl_b64 s[20:21], s[14:15], 19
	s_add_u32 s20, s30, s20
	s_addc_u32 s21, s31, s21
	s_and_b64 s[26:27], s[6:7], exec
	s_cselect_b32 s15, s21, s25
	s_cselect_b32 s44, s20, s24
	s_add_u32 s22, s22, 0x40080
	s_addc_u32 s23, s23, 0
	s_add_u32 s45, s24, 0x100
	v_mov_b32_e32 v2, 0
	s_addc_u32 s46, s25, 0
	s_mov_b32 s47, -2
	v_mov_b32_e32 v3, v2
	v_mov_b32_e32 v4, v2
	v_mov_b32_e32 v5, v2
	v_mov_b32_e32 v6, v2
	v_mov_b32_e32 v7, v2
	v_mov_b32_e32 v8, v2
	v_mov_b32_e32 v9, v2
	v_mov_b32_e32 v18, v2
	v_mov_b32_e32 v19, v2
	v_mov_b32_e32 v20, v2
	v_mov_b32_e32 v21, v2
	v_mov_b32_e32 v22, v2
	v_mov_b32_e32 v23, v2
	v_mov_b32_e32 v24, v2
	v_mov_b32_e32 v25, v2
	v_mov_b32_e32 v34, v2
	v_mov_b32_e32 v35, v2
	v_mov_b32_e32 v36, v2
	v_mov_b32_e32 v37, v2
	v_mov_b32_e32 v38, v2
	v_mov_b32_e32 v39, v2
	v_mov_b32_e32 v40, v2
	v_mov_b32_e32 v41, v2
	v_mov_b32_e32 v50, v2
	v_mov_b32_e32 v51, v2
	v_mov_b32_e32 v52, v2
	v_mov_b32_e32 v53, v2
	v_mov_b32_e32 v54, v2
	v_mov_b32_e32 v55, v2
	v_mov_b32_e32 v56, v2
	v_mov_b32_e32 v57, v2
	v_mov_b32_e32 v10, v2
	v_mov_b32_e32 v11, v2
	v_mov_b32_e32 v12, v2
	v_mov_b32_e32 v13, v2
	v_mov_b32_e32 v14, v2
	v_mov_b32_e32 v15, v2
	v_mov_b32_e32 v16, v2
	v_mov_b32_e32 v17, v2
	v_mov_b32_e32 v26, v2
	v_mov_b32_e32 v27, v2
	v_mov_b32_e32 v28, v2
	v_mov_b32_e32 v29, v2
	v_mov_b32_e32 v30, v2
	v_mov_b32_e32 v31, v2
	v_mov_b32_e32 v32, v2
	v_mov_b32_e32 v33, v2
	v_mov_b32_e32 v42, v2
	v_mov_b32_e32 v43, v2
	v_mov_b32_e32 v44, v2
	v_mov_b32_e32 v45, v2
	v_mov_b32_e32 v46, v2
	v_mov_b32_e32 v47, v2
	v_mov_b32_e32 v48, v2
	v_mov_b32_e32 v49, v2
	v_mov_b32_e32 v58, v2
	v_mov_b32_e32 v59, v2
	v_mov_b32_e32 v60, v2
	v_mov_b32_e32 v61, v2
	v_mov_b32_e32 v62, v2
	v_mov_b32_e32 v63, v2
	v_mov_b32_e32 v64, v2
	v_mov_b32_e32 v65, v2
	v_mov_b32_e32 v66, v2
	v_mov_b32_e32 v67, v2
	v_mov_b32_e32 v68, v2
	v_mov_b32_e32 v69, v2
	v_mov_b32_e32 v70, v2
	v_mov_b32_e32 v71, v2
	v_mov_b32_e32 v72, v2
	v_mov_b32_e32 v73, v2
	v_mov_b32_e32 v82, v2
	v_mov_b32_e32 v83, v2
	v_mov_b32_e32 v84, v2
	v_mov_b32_e32 v85, v2
	v_mov_b32_e32 v86, v2
	v_mov_b32_e32 v87, v2
	v_mov_b32_e32 v88, v2
	v_mov_b32_e32 v89, v2
	v_mov_b32_e32 v98, v2
	v_mov_b32_e32 v99, v2
	v_mov_b32_e32 v100, v2
	v_mov_b32_e32 v101, v2
	v_mov_b32_e32 v102, v2
	v_mov_b32_e32 v103, v2
	v_mov_b32_e32 v104, v2
	v_mov_b32_e32 v105, v2
	v_mov_b32_e32 v126, v2
	v_mov_b32_e32 v127, v2
	v_mov_b32_e32 v128, v2
	v_mov_b32_e32 v129, v2
	v_mov_b32_e32 v130, v2
	v_mov_b32_e32 v131, v2
	v_mov_b32_e32 v132, v2
	v_mov_b32_e32 v133, v2
	v_mov_b32_e32 v74, v2
	v_mov_b32_e32 v75, v2
	v_mov_b32_e32 v76, v2
	v_mov_b32_e32 v77, v2
	v_mov_b32_e32 v78, v2
	v_mov_b32_e32 v79, v2
	v_mov_b32_e32 v80, v2
	v_mov_b32_e32 v81, v2
	v_mov_b32_e32 v90, v2
	v_mov_b32_e32 v91, v2
	v_mov_b32_e32 v92, v2
	v_mov_b32_e32 v93, v2
	v_mov_b32_e32 v94, v2
	v_mov_b32_e32 v95, v2
	v_mov_b32_e32 v96, v2
	v_mov_b32_e32 v97, v2
	v_mov_b32_e32 v106, v2
	v_mov_b32_e32 v107, v2
	v_mov_b32_e32 v108, v2
	v_mov_b32_e32 v109, v2
	v_mov_b32_e32 v110, v2
	v_mov_b32_e32 v111, v2
	v_mov_b32_e32 v112, v2
	v_mov_b32_e32 v113, v2
	v_mov_b32_e32 v138, v2
	v_mov_b32_e32 v139, v2
	v_mov_b32_e32 v140, v2
	v_mov_b32_e32 v141, v2
	v_mov_b32_e32 v142, v2
	v_mov_b32_e32 v143, v2
	v_mov_b32_e32 v144, v2
	v_mov_b32_e32 v145, v2
.LBB0_693:
	s_add_u32 s24, s22, 0xfffc0080
	s_addc_u32 s25, s23, -1
	s_add_i32 s48, 0, 0x10000
	s_cmp_eq_u32 s47, 12
	s_cselect_b32 s27, s17, s25
	s_cselect_b32 s26, s43, s24
	s_cselect_b32 s25, s15, s46
	s_cselect_b32 s24, s44, s45
	s_add_i32 s50, 0, 0x14000
	v_add_u32_e32 v134, s48, v191
	v_add_u32_e32 v158, s50, v191
	ds_read_b128 v[114:117], v134
	ds_read_b128 v[118:121], v134 offset:1024
	ds_read_b128 v[122:125], v134 offset:2048
	ds_read_b128 v[134:137], v134 offset:3072
	ds_read_b128 v[146:149], v158
	ds_read_b128 v[150:153], v158 offset:1024
	ds_read_b128 v[172:175], v158 offset:2048
	ds_read_b128 v[176:179], v158 offset:3072
	v_lshl_add_u64 v[158:159], s[22:23], 0, v[168:169]
	s_add_i32 m0, s34, 0xc000
	ds_read_b128 v[180:183], v193
	ds_read_b128 v[184:187], v193 offset:1024
	ds_read_b128 v[194:197], v193 offset:2048
	ds_read_b128 v[198:201], v193 offset:3072
	ds_read_b128 v[202:205], v193 offset:4096
	ds_read_b128 v[206:209], v193 offset:5120
	ds_read_b128 v[210:213], v193 offset:6144
	ds_read_b128 v[214:217], v193 offset:7168
	global_load_lds_dwordx4 v[158:159], off
	v_lshl_add_u64 v[158:159], s[22:23], 0, v[170:171]
	s_add_i32 m0, s34, 0xe000
	s_nop 0
	global_load_lds_dwordx4 v[158:159], off
	s_cmp_lg_u32 s98, 0
	s_cbranch_scc1 .Lrx_o_1
	s_waitcnt vmcnt(8)
.Lrx_o_1:
	s_waitcnt lgkmcnt(0)
	s_barrier
	s_setprio 1
	s_waitcnt lgkmcnt(0)
	v_mfma_f32_16x16x32_bf16 v[142:145], v[114:117], v[180:183], v[142:145]
	v_mfma_f32_16x16x32_bf16 v[138:141], v[122:125], v[180:183], v[138:141]
	v_mfma_f32_16x16x32_bf16 v[110:113], v[114:117], v[194:197], v[110:113]
	v_mfma_f32_16x16x32_bf16 v[106:109], v[122:125], v[194:197], v[106:109]
	v_mfma_f32_16x16x32_bf16 v[94:97], v[114:117], v[202:205], v[94:97]
	v_mfma_f32_16x16x32_bf16 v[90:93], v[122:125], v[202:205], v[90:93]
	v_mfma_f32_16x16x32_bf16 v[78:81], v[114:117], v[210:213], v[78:81]
	v_mfma_f32_16x16x32_bf16 v[74:77], v[122:125], v[210:213], v[74:77]
	v_mfma_f32_16x16x32_bf16 v[142:145], v[118:121], v[184:187], v[142:145]
	v_mfma_f32_16x16x32_bf16 v[138:141], v[134:137], v[184:187], v[138:141]
	v_mfma_f32_16x16x32_bf16 v[110:113], v[118:121], v[198:201], v[110:113]
	v_mfma_f32_16x16x32_bf16 v[106:109], v[134:137], v[198:201], v[106:109]
	v_mfma_f32_16x16x32_bf16 v[94:97], v[118:121], v[206:209], v[94:97]
	v_mfma_f32_16x16x32_bf16 v[90:93], v[134:137], v[206:209], v[90:93]
	v_mfma_f32_16x16x32_bf16 v[78:81], v[118:121], v[214:217], v[78:81]
	v_mfma_f32_16x16x32_bf16 v[74:77], v[134:137], v[214:217], v[74:77]
	s_setprio 0
	s_setprio 1
	v_mfma_f32_16x16x32_bf16 v[130:133], v[146:149], v[180:183], v[130:133]
	v_mfma_f32_16x16x32_bf16 v[126:129], v[172:175], v[180:183], v[126:129]
	v_mfma_f32_16x16x32_bf16 v[102:105], v[146:149], v[194:197], v[102:105]
	v_mfma_f32_16x16x32_bf16 v[98:101], v[172:175], v[194:197], v[98:101]
	v_mfma_f32_16x16x32_bf16 v[86:89], v[146:149], v[202:205], v[86:89]
	v_mfma_f32_16x16x32_bf16 v[82:85], v[172:175], v[202:205], v[82:85]
	v_mfma_f32_16x16x32_bf16 v[70:73], v[146:149], v[210:213], v[70:73]
	v_mfma_f32_16x16x32_bf16 v[66:69], v[172:175], v[210:213], v[66:69]
	v_mfma_f32_16x16x32_bf16 v[130:133], v[150:153], v[184:187], v[130:133]
	v_mfma_f32_16x16x32_bf16 v[126:129], v[176:179], v[184:187], v[126:129]
	v_mfma_f32_16x16x32_bf16 v[102:105], v[150:153], v[198:201], v[102:105]
	v_mfma_f32_16x16x32_bf16 v[98:101], v[176:179], v[198:201], v[98:101]
	v_mfma_f32_16x16x32_bf16 v[86:89], v[150:153], v[206:209], v[86:89]
	v_mfma_f32_16x16x32_bf16 v[82:85], v[176:179], v[206:209], v[82:85]
	v_mfma_f32_16x16x32_bf16 v[70:73], v[150:153], v[214:217], v[70:73]
	v_mfma_f32_16x16x32_bf16 v[66:69], v[176:179], v[214:217], v[66:69]
	s_setprio 0
	s_barrier
	s_add_i32 s48, s48, s33
	v_lshl_add_u64 v[158:159], s[24:25], 0, v[0:1]
	s_mov_b32 m0, s48
	ds_read_b128 v[180:183], v193 offset:16384
	ds_read_b128 v[184:187], v193 offset:17408
	ds_read_b128 v[194:197], v193 offset:18432
	ds_read_b128 v[198:201], v193 offset:19456
	ds_read_b128 v[202:205], v193 offset:20480
	ds_read_b128 v[206:209], v193 offset:21504
	ds_read_b128 v[210:213], v193 offset:22528
	ds_read_b128 v[214:217], v193 offset:23552
	global_load_lds_dwordx4 v[158:159], off
	s_add_i32 m0, s48, 0x2000
	s_add_u32 s48, s24, 0x40000
	v_lshl_add_u64 v[162:163], s[24:25], 0, v[154:155]
	s_addc_u32 s49, s25, 0
	s_add_i32 s50, s50, s33
	global_load_lds_dwordx4 v[162:163], off
	v_lshl_add_u64 v[188:189], s[48:49], 0, v[0:1]
	s_mov_b32 m0, s50
	v_lshl_add_u64 v[218:219], s[26:27], 0, v[156:157]
	global_load_lds_dwordx4 v[188:189], off
	v_lshl_add_u64 v[188:189], s[48:49], 0, v[154:155]
	s_add_i32 m0, s50, 0x2000
	s_nop 0
	global_load_lds_dwordx4 v[188:189], off
	v_lshl_add_u64 v[188:189], s[26:27], 0, v[166:167]
	s_mov_b32 m0, s34
	s_nop 0
	global_load_lds_dwordx4 v[188:189], off
	s_mov_b32 m0, s35
	s_nop 0
	global_load_lds_dwordx4 v[218:219], off
	s_cmp_lg_u32 s98, 0
	s_cbranch_scc1 .Lrx_o_2
	s_waitcnt vmcnt(8)
.Lrx_o_2:
	s_mov_b32 s98, 0
	s_waitcnt lgkmcnt(0)
	s_barrier
	s_setprio 1
	s_waitcnt lgkmcnt(0)
	v_mfma_f32_16x16x32_bf16 v[62:65], v[114:117], v[180:183], v[62:65]
	v_mfma_f32_16x16x32_bf16 v[58:61], v[122:125], v[180:183], v[58:61]
	v_mfma_f32_16x16x32_bf16 v[46:49], v[114:117], v[194:197], v[46:49]
	v_mfma_f32_16x16x32_bf16 v[42:45], v[122:125], v[194:197], v[42:45]
	v_mfma_f32_16x16x32_bf16 v[30:33], v[114:117], v[202:205], v[30:33]
	v_mfma_f32_16x16x32_bf16 v[26:29], v[122:125], v[202:205], v[26:29]
	v_mfma_f32_16x16x32_bf16 v[14:17], v[114:117], v[210:213], v[14:17]
	v_mfma_f32_16x16x32_bf16 v[10:13], v[122:125], v[210:213], v[10:13]
	v_mfma_f32_16x16x32_bf16 v[62:65], v[118:121], v[184:187], v[62:65]
	v_mfma_f32_16x16x32_bf16 v[58:61], v[134:137], v[184:187], v[58:61]
	v_mfma_f32_16x16x32_bf16 v[46:49], v[118:121], v[198:201], v[46:49]
	v_mfma_f32_16x16x32_bf16 v[42:45], v[134:137], v[198:201], v[42:45]
	v_mfma_f32_16x16x32_bf16 v[30:33], v[118:121], v[206:209], v[30:33]
	v_mfma_f32_16x16x32_bf16 v[26:29], v[134:137], v[206:209], v[26:29]
	v_mfma_f32_16x16x32_bf16 v[14:17], v[118:121], v[214:217], v[14:17]
	v_mfma_f32_16x16x32_bf16 v[10:13], v[134:137], v[214:217], v[10:13]
	s_setprio 0
	s_setprio 1
	v_mfma_f32_16x16x32_bf16 v[54:57], v[146:149], v[180:183], v[54:57]
	v_mfma_f32_16x16x32_bf16 v[50:53], v[172:175], v[180:183], v[50:53]
	v_mfma_f32_16x16x32_bf16 v[38:41], v[146:149], v[194:197], v[38:41]
	v_mfma_f32_16x16x32_bf16 v[34:37], v[172:175], v[194:197], v[34:37]
	v_mfma_f32_16x16x32_bf16 v[22:25], v[146:149], v[202:205], v[22:25]
	v_mfma_f32_16x16x32_bf16 v[18:21], v[172:175], v[202:205], v[18:21]
	v_mfma_f32_16x16x32_bf16 v[6:9], v[146:149], v[210:213], v[6:9]
	v_mfma_f32_16x16x32_bf16 v[2:5], v[172:175], v[210:213], v[2:5]
	v_mfma_f32_16x16x32_bf16 v[54:57], v[150:153], v[184:187], v[54:57]
	v_mfma_f32_16x16x32_bf16 v[50:53], v[176:179], v[184:187], v[50:53]
	v_mfma_f32_16x16x32_bf16 v[38:41], v[150:153], v[198:201], v[38:41]
	v_mfma_f32_16x16x32_bf16 v[34:37], v[176:179], v[198:201], v[34:37]
	v_mfma_f32_16x16x32_bf16 v[22:25], v[150:153], v[206:209], v[22:25]
	v_mfma_f32_16x16x32_bf16 v[18:21], v[176:179], v[206:209], v[18:21]
	v_mfma_f32_16x16x32_bf16 v[6:9], v[150:153], v[214:217], v[6:9]
	v_mfma_f32_16x16x32_bf16 v[2:5], v[176:179], v[214:217], v[2:5]
	s_setprio 0
	s_barrier
	s_add_i32 s48, 0, 0x18000
	s_add_i32 s49, 0, 0x1c000
	v_add_u32_e32 v134, s48, v191
	v_add_u32_e32 v176, s49, v191
	ds_read_b128 v[114:117], v134
	ds_read_b128 v[118:121], v134 offset:1024
	ds_read_b128 v[122:125], v134 offset:2048
	ds_read_b128 v[134:137], v134 offset:3072
	ds_read_b128 v[146:149], v176
	ds_read_b128 v[150:153], v176 offset:1024
	ds_read_b128 v[172:175], v176 offset:2048
	ds_read_b128 v[176:179], v176 offset:3072
	s_add_u32 s26, s26, 0x40000
	s_addc_u32 s27, s27, 0
	s_mov_b32 m0, s36
	v_lshl_add_u64 v[220:221], s[26:27], 0, v[166:167]
	ds_read_b128 v[180:183], v193 offset:32768
	ds_read_b128 v[184:187], v193 offset:33792
	ds_read_b128 v[194:197], v193 offset:34816
	ds_read_b128 v[198:201], v193 offset:35840
	ds_read_b128 v[202:205], v193 offset:36864
	ds_read_b128 v[206:209], v193 offset:37888
	ds_read_b128 v[210:213], v193 offset:38912
	ds_read_b128 v[214:217], v193 offset:39936
	global_load_lds_dwordx4 v[220:221], off
	v_lshl_add_u64 v[220:221], s[26:27], 0, v[156:157]
	s_mov_b32 m0, s37
	s_nop 0
	global_load_lds_dwordx4 v[220:221], off
	s_waitcnt vmcnt(8)
	s_waitcnt lgkmcnt(0)
	s_barrier
	s_setprio 1
	s_waitcnt lgkmcnt(0)
	v_mfma_f32_16x16x32_bf16 v[142:145], v[114:117], v[180:183], v[142:145]
	v_mfma_f32_16x16x32_bf16 v[138:141], v[122:125], v[180:183], v[138:141]
	v_mfma_f32_16x16x32_bf16 v[110:113], v[114:117], v[194:197], v[110:113]
	v_mfma_f32_16x16x32_bf16 v[106:109], v[122:125], v[194:197], v[106:109]
	v_mfma_f32_16x16x32_bf16 v[94:97], v[114:117], v[202:205], v[94:97]
	v_mfma_f32_16x16x32_bf16 v[90:93], v[122:125], v[202:205], v[90:93]
	v_mfma_f32_16x16x32_bf16 v[78:81], v[114:117], v[210:213], v[78:81]
	v_mfma_f32_16x16x32_bf16 v[74:77], v[122:125], v[210:213], v[74:77]
	v_mfma_f32_16x16x32_bf16 v[142:145], v[118:121], v[184:187], v[142:145]
	v_mfma_f32_16x16x32_bf16 v[138:141], v[134:137], v[184:187], v[138:141]
	v_mfma_f32_16x16x32_bf16 v[110:113], v[118:121], v[198:201], v[110:113]
	v_mfma_f32_16x16x32_bf16 v[106:109], v[134:137], v[198:201], v[106:109]
	v_mfma_f32_16x16x32_bf16 v[94:97], v[118:121], v[206:209], v[94:97]
	v_mfma_f32_16x16x32_bf16 v[90:93], v[134:137], v[206:209], v[90:93]
	v_mfma_f32_16x16x32_bf16 v[78:81], v[118:121], v[214:217], v[78:81]
	v_mfma_f32_16x16x32_bf16 v[74:77], v[134:137], v[214:217], v[74:77]
	s_setprio 0
	s_setprio 1
	v_mfma_f32_16x16x32_bf16 v[130:133], v[146:149], v[180:183], v[130:133]
	v_mfma_f32_16x16x32_bf16 v[126:129], v[172:175], v[180:183], v[126:129]
	v_mfma_f32_16x16x32_bf16 v[102:105], v[146:149], v[194:197], v[102:105]
	v_mfma_f32_16x16x32_bf16 v[98:101], v[172:175], v[194:197], v[98:101]
	v_mfma_f32_16x16x32_bf16 v[86:89], v[146:149], v[202:205], v[86:89]
	v_mfma_f32_16x16x32_bf16 v[82:85], v[172:175], v[202:205], v[82:85]
	v_mfma_f32_16x16x32_bf16 v[70:73], v[146:149], v[210:213], v[70:73]
	v_mfma_f32_16x16x32_bf16 v[66:69], v[172:175], v[210:213], v[66:69]
	v_mfma_f32_16x16x32_bf16 v[130:133], v[150:153], v[184:187], v[130:133]
	v_mfma_f32_16x16x32_bf16 v[126:129], v[176:179], v[184:187], v[126:129]
	v_mfma_f32_16x16x32_bf16 v[102:105], v[150:153], v[198:201], v[102:105]
	v_mfma_f32_16x16x32_bf16 v[98:101], v[176:179], v[198:201], v[98:101]
	v_mfma_f32_16x16x32_bf16 v[86:89], v[150:153], v[206:209], v[86:89]
	v_mfma_f32_16x16x32_bf16 v[82:85], v[176:179], v[206:209], v[82:85]
	v_mfma_f32_16x16x32_bf16 v[70:73], v[150:153], v[214:217], v[70:73]
	v_mfma_f32_16x16x32_bf16 v[66:69], v[176:179], v[214:217], v[66:69]
	s_setprio 0
	s_barrier
	s_add_i32 s26, s48, s33
	v_lshl_add_u64 v[158:159], v[158:159], 0, s[82:83]
	s_mov_b32 m0, s26
	ds_read_b128 v[180:183], v193 offset:49152
	ds_read_b128 v[184:187], v193 offset:50176
	ds_read_b128 v[194:197], v193 offset:51200
	ds_read_b128 v[198:201], v193 offset:52224
	ds_read_b128 v[202:205], v193 offset:53248
	ds_read_b128 v[206:209], v193 offset:54272
	ds_read_b128 v[210:213], v193 offset:55296
	ds_read_b128 v[214:217], v193 offset:56320
	global_load_lds_dwordx4 v[158:159], off
	s_add_i32 m0, s26, 0x2000
	s_add_u32 s24, s24, 0x40080
	v_lshl_add_u64 v[158:159], v[162:163], 0, s[82:83]
	s_addc_u32 s25, s25, 0
	s_add_i32 s26, s49, s33
	global_load_lds_dwordx4 v[158:159], off
	v_lshl_add_u64 v[158:159], s[24:25], 0, v[0:1]
	s_mov_b32 m0, s26
	s_nop 0
	global_load_lds_dwordx4 v[158:159], off
	v_lshl_add_u64 v[158:159], s[24:25], 0, v[154:155]
	s_add_i32 m0, s26, 0x2000
	s_nop 0
	global_load_lds_dwordx4 v[158:159], off
	v_lshl_add_u64 v[158:159], v[188:189], 0, s[82:83]
	s_mov_b32 m0, s38
	s_nop 0
	global_load_lds_dwordx4 v[158:159], off
	v_lshl_add_u64 v[158:159], v[218:219], 0, s[82:83]
	s_mov_b32 m0, s39
	s_nop 0
	global_load_lds_dwordx4 v[158:159], off
	s_waitcnt vmcnt(8)
	s_waitcnt lgkmcnt(0)
	s_barrier
	s_setprio 1
	s_waitcnt lgkmcnt(0)
	v_mfma_f32_16x16x32_bf16 v[62:65], v[114:117], v[180:183], v[62:65]
	v_mfma_f32_16x16x32_bf16 v[58:61], v[122:125], v[180:183], v[58:61]
	v_mfma_f32_16x16x32_bf16 v[46:49], v[114:117], v[194:197], v[46:49]
	v_mfma_f32_16x16x32_bf16 v[42:45], v[122:125], v[194:197], v[42:45]
	v_mfma_f32_16x16x32_bf16 v[30:33], v[114:117], v[202:205], v[30:33]
	v_mfma_f32_16x16x32_bf16 v[26:29], v[122:125], v[202:205], v[26:29]
	v_mfma_f32_16x16x32_bf16 v[14:17], v[114:117], v[210:213], v[14:17]
	v_mfma_f32_16x16x32_bf16 v[10:13], v[122:125], v[210:213], v[10:13]
	v_mfma_f32_16x16x32_bf16 v[62:65], v[118:121], v[184:187], v[62:65]
	v_mfma_f32_16x16x32_bf16 v[58:61], v[134:137], v[184:187], v[58:61]
	v_mfma_f32_16x16x32_bf16 v[46:49], v[118:121], v[198:201], v[46:49]
	v_mfma_f32_16x16x32_bf16 v[42:45], v[134:137], v[198:201], v[42:45]
	v_mfma_f32_16x16x32_bf16 v[30:33], v[118:121], v[206:209], v[30:33]
	v_mfma_f32_16x16x32_bf16 v[26:29], v[134:137], v[206:209], v[26:29]
	v_mfma_f32_16x16x32_bf16 v[14:17], v[118:121], v[214:217], v[14:17]
	v_mfma_f32_16x16x32_bf16 v[10:13], v[134:137], v[214:217], v[10:13]
	s_setprio 0
	s_setprio 1
	v_mfma_f32_16x16x32_bf16 v[54:57], v[146:149], v[180:183], v[54:57]
	v_mfma_f32_16x16x32_bf16 v[50:53], v[172:175], v[180:183], v[50:53]
	v_mfma_f32_16x16x32_bf16 v[38:41], v[146:149], v[194:197], v[38:41]
	v_mfma_f32_16x16x32_bf16 v[34:37], v[172:175], v[194:197], v[34:37]
	v_mfma_f32_16x16x32_bf16 v[22:25], v[146:149], v[202:205], v[22:25]
	v_mfma_f32_16x16x32_bf16 v[18:21], v[172:175], v[202:205], v[18:21]
	v_mfma_f32_16x16x32_bf16 v[6:9], v[146:149], v[210:213], v[6:9]
	v_mfma_f32_16x16x32_bf16 v[2:5], v[172:175], v[210:213], v[2:5]
	v_mfma_f32_16x16x32_bf16 v[54:57], v[150:153], v[184:187], v[54:57]
	v_mfma_f32_16x16x32_bf16 v[50:53], v[176:179], v[184:187], v[50:53]
	v_mfma_f32_16x16x32_bf16 v[38:41], v[150:153], v[198:201], v[38:41]
	v_mfma_f32_16x16x32_bf16 v[34:37], v[176:179], v[198:201], v[34:37]
	v_mfma_f32_16x16x32_bf16 v[22:25], v[150:153], v[206:209], v[22:25]
	v_mfma_f32_16x16x32_bf16 v[18:21], v[176:179], v[206:209], v[18:21]
	v_mfma_f32_16x16x32_bf16 v[6:9], v[150:153], v[214:217], v[6:9]
	v_mfma_f32_16x16x32_bf16 v[2:5], v[176:179], v[214:217], v[2:5]
	s_setprio 0
	s_barrier
	s_add_i32 s47, s47, 2
	s_add_u32 s22, s22, 0x100
	s_addc_u32 s23, s23, 0
	s_add_u32 s45, s45, 0x100
	s_addc_u32 s46, s46, 0
	s_cmp_gt_u32 s47, 13
	s_cbranch_scc0 .LBB0_693
	s_and_b64 vcc, exec, s[12:13]
	s_cbranch_vccz .LBB0_696
	s_barrier
.LBB0_696:
	v_lshl_or_b32 v172, s41, 8, v192
	v_lshl_add_u32 v176, s42, 8, v190
	v_ashrrev_i32_e32 v173, 31, v172
	v_lshlrev_b64 v[158:159], 1, v[172:173]
	v_ashrrev_i32_e32 v177, 31, v176
	v_lshl_add_u64 v[174:175], s[8:9], 0, v[158:159]
	v_lshlrev_b64 v[162:163], 11, v[176:177]
	v_lshl_add_u64 v[114:115], v[174:175], 0, v[162:163]
	global_load_dwordx4 v[194:197], v[114:115], off
	global_load_dwordx4 v[198:201], v[114:115], off offset:256
	v_or_b32_e32 v186, 16, v176
	v_ashrrev_i32_e32 v187, 31, v186
	v_or_b32_e32 v182, 32, v176
	v_lshlrev_b64 v[188:189], 11, v[186:187]
	v_ashrrev_i32_e32 v183, 31, v182
	v_or_b32_e32 v178, 48, v176
	v_lshl_add_u64 v[114:115], v[174:175], 0, v[188:189]
	v_lshlrev_b64 v[184:185], 11, v[182:183]
	v_ashrrev_i32_e32 v179, 31, v178
	global_load_dwordx4 v[150:153], v[114:115], off
	global_load_dwordx4 v[146:149], v[114:115], off offset:256
	v_lshl_add_u64 v[114:115], v[174:175], 0, v[184:185]
	v_lshlrev_b64 v[180:181], 11, v[178:179]
	global_load_dwordx4 v[134:137], v[114:115], off
	global_load_dwordx4 v[122:125], v[114:115], off offset:256
	v_lshl_add_u64 v[114:115], v[174:175], 0, v[180:181]
	global_load_dwordx4 v[118:121], v[114:115], off
	s_nop 0
	global_load_dwordx4 v[114:117], v[114:115], off offset:256
	s_waitcnt vmcnt(0)
	v_lshlrev_b32_e32 v202, 16, v194
	v_and_b32_e32 v203, 0xffff0000, v194
	v_lshlrev_b32_e32 v194, 16, v195
	v_and_b32_e32 v195, 0xffff0000, v195
	v_lshlrev_b32_e32 v204, 16, v196
	v_and_b32_e32 v205, 0xffff0000, v196
	v_lshlrev_b32_e32 v196, 16, v197
	v_and_b32_e32 v197, 0xffff0000, v197
	v_pk_add_f32 v[144:145], v[144:145], v[194:195]
	v_pk_add_f32 v[142:143], v[142:143], v[202:203]
	v_pk_add_f32 v[194:195], v[140:141], v[196:197]
	v_pk_add_f32 v[140:141], v[138:139], v[204:205]
	v_mul_f32_e32 v138, v143, v143
	v_mul_f32_e32 v139, v145, v145
	v_fmac_f32_e32 v138, v142, v142
	v_fmac_f32_e32 v139, v144, v144
	v_add_f32_e32 v138, v138, v139
	v_mul_f32_e32 v139, v141, v141
	v_mul_f32_e32 v196, v195, v195
	v_fmac_f32_e32 v139, v140, v140
	v_fmac_f32_e32 v196, v194, v194
	v_add_f32_e32 v139, v139, v196
	v_add_f32_e32 v196, v138, v139
	v_cvt_pk_bf16_f32 v138, v142, v143
	v_lshl_add_u64 v[142:143], s[8:9], 0, v[162:163]
	v_cvt_pk_bf16_f32 v139, v144, v145
	v_cvt_pk_bf16_f32 v140, v140, v141
	v_cvt_pk_bf16_f32 v141, v194, v195
	v_lshl_add_u64 v[142:143], v[142:143], 0, v[158:159]
	global_store_dwordx4 v[142:143], v[138:141], off
	v_lshlrev_b32_e32 v144, 16, v200
	v_and_b32_e32 v145, 0xffff0000, v200
	v_lshlrev_b32_e32 v138, 16, v198
	v_and_b32_e32 v139, 0xffff0000, v198
	v_lshlrev_b32_e32 v140, 16, v199
	v_and_b32_e32 v141, 0xffff0000, v199
	v_lshlrev_b32_e32 v158, 16, v201
	v_and_b32_e32 v159, 0xffff0000, v201
	v_pk_add_f32 v[132:133], v[132:133], v[140:141]
	v_pk_add_f32 v[130:131], v[130:131], v[138:139]
	v_pk_add_f32 v[138:139], v[128:129], v[158:159]
	v_pk_add_f32 v[128:129], v[126:127], v[144:145]
	v_mul_f32_e32 v126, v131, v131
	v_mul_f32_e32 v127, v133, v133
	v_fmac_f32_e32 v126, v130, v130
	v_fmac_f32_e32 v127, v132, v132
	v_add_f32_e32 v126, v126, v127
	v_mul_f32_e32 v127, v129, v129
	v_mul_f32_e32 v140, v139, v139
	v_fmac_f32_e32 v127, v128, v128
	v_fmac_f32_e32 v140, v138, v138
	v_add_f32_e32 v127, v127, v140
	v_add_f32_e32 v126, v126, v127
	v_add_f32_e32 v140, v196, v126
	v_cvt_pk_bf16_f32 v126, v130, v131
	v_cvt_pk_bf16_f32 v127, v132, v133
	v_cvt_pk_bf16_f32 v128, v128, v129
	v_cvt_pk_bf16_f32 v129, v138, v139
	global_store_dwordx4 v[142:143], v[126:129], off offset:256
	s_nop 1
	v_and_b32_e32 v127, 64, v222
	v_xor_b32_e32 v126, 16, v222
	v_add_u32_e32 v127, 64, v127
	v_cmp_lt_i32_e32 vcc, v126, v127
	v_xor_b32_e32 v129, 32, v222
	s_nop 0
	v_cndmask_b32_e32 v126, v222, v126, vcc
	v_lshlrev_b32_e32 v126, 2, v126
	ds_bpermute_b32 v128, v126, v140
	v_cmp_lt_i32_e32 vcc, v129, v127
	s_waitcnt lgkmcnt(0)
	v_add_f32_e32 v128, v140, v128
	v_cndmask_b32_e32 v127, v222, v129, vcc
	v_lshlrev_b32_e32 v127, 2, v127
	ds_bpermute_b32 v129, v127, v128
	s_waitcnt lgkmcnt(0)
	v_add_f32_e32 v226, v128, v129
.LBB0_698:
	v_lshlrev_b32_e32 v128, 16, v150
	s_waitcnt lgkmcnt(0)
	v_and_b32_e32 v129, 0xffff0000, v150
	v_lshlrev_b32_e32 v130, 16, v151
	v_and_b32_e32 v131, 0xffff0000, v151
	v_lshlrev_b32_e32 v132, 16, v152
	v_and_b32_e32 v133, 0xffff0000, v152
	v_lshlrev_b32_e32 v138, 16, v153
	v_and_b32_e32 v139, 0xffff0000, v153
	v_pk_add_f32 v[112:113], v[112:113], v[130:131]
	v_pk_add_f32 v[110:111], v[110:111], v[128:129]
	v_pk_add_f32 v[128:129], v[108:109], v[138:139]
	v_pk_add_f32 v[108:109], v[106:107], v[132:133]
	v_mul_f32_e32 v106, v111, v111
	v_mul_f32_e32 v107, v113, v113
	v_fmac_f32_e32 v106, v110, v110
	v_fmac_f32_e32 v107, v112, v112
	v_add_f32_e32 v106, v106, v107
	v_mul_f32_e32 v107, v109, v109
	v_mul_f32_e32 v130, v129, v129
	v_fmac_f32_e32 v107, v108, v108
	v_fmac_f32_e32 v130, v128, v128
	v_add_f32_e32 v107, v107, v130
	v_add_f32_e32 v132, v106, v107
	v_cvt_pk_bf16_f32 v106, v110, v111
	v_cvt_pk_bf16_f32 v107, v112, v113
	v_lshlrev_b32_e32 v110, 16, v146
	v_and_b32_e32 v111, 0xffff0000, v146
	v_lshlrev_b32_e32 v112, 16, v147
	v_and_b32_e32 v113, 0xffff0000, v147
	v_cvt_pk_bf16_f32 v108, v108, v109
	v_cvt_pk_bf16_f32 v109, v128, v129
	v_lshlrev_b32_e32 v128, 16, v148
	v_and_b32_e32 v129, 0xffff0000, v148
	v_pk_add_f32 v[104:105], v[104:105], v[112:113]
	v_pk_add_f32 v[102:103], v[102:103], v[110:111]
	v_lshlrev_b32_e32 v130, 16, v149
	v_and_b32_e32 v131, 0xffff0000, v149
	v_pk_add_f32 v[112:113], v[98:99], v[128:129]
	v_mul_f32_e32 v98, v103, v103
	v_mul_f32_e32 v99, v105, v105
	v_pk_add_f32 v[110:111], v[100:101], v[130:131]
	v_fmac_f32_e32 v98, v102, v102
	v_fmac_f32_e32 v99, v104, v104
	v_add_f32_e32 v98, v98, v99
	v_mul_f32_e32 v99, v113, v113
	v_mul_f32_e32 v100, v111, v111
	v_fmac_f32_e32 v99, v112, v112
	v_fmac_f32_e32 v100, v110, v110
	v_add_f32_e32 v99, v99, v100
	v_add_f32_e32 v98, v98, v99
	v_add_f32_e32 v101, v132, v98
	ds_bpermute_b32 v130, v126, v101
	v_lshl_add_u64 v[98:99], s[8:9], 0, v[188:189]
	v_lshl_add_u64 v[128:129], v[172:173], 1, v[98:99]
	global_store_dwordx4 v[128:129], v[106:109], off
	v_cvt_pk_bf16_f32 v100, v102, v103
	s_waitcnt lgkmcnt(0)
	v_add_f32_e32 v98, v101, v130
	ds_bpermute_b32 v99, v127, v98
	v_cvt_pk_bf16_f32 v101, v104, v105
	v_cvt_pk_bf16_f32 v102, v112, v113
	v_cvt_pk_bf16_f32 v103, v110, v111
	global_store_dwordx4 v[128:129], v[100:103], off offset:256
	s_waitcnt lgkmcnt(0)
	v_add_f32_e32 v227, v98, v99
.LBB0_700:
	v_lshlrev_b32_e32 v98, 16, v134
	s_waitcnt lgkmcnt(0)
	v_and_b32_e32 v99, 0xffff0000, v134
	v_lshlrev_b32_e32 v100, 16, v135
	v_and_b32_e32 v101, 0xffff0000, v135
	v_lshlrev_b32_e32 v102, 16, v136
	v_and_b32_e32 v103, 0xffff0000, v136
	v_lshlrev_b32_e32 v104, 16, v137
	v_and_b32_e32 v105, 0xffff0000, v137
	v_pk_add_f32 v[96:97], v[96:97], v[100:101]
	v_pk_add_f32 v[94:95], v[94:95], v[98:99]
	v_pk_add_f32 v[98:99], v[92:93], v[104:105]
	v_pk_add_f32 v[92:93], v[90:91], v[102:103]
	v_mul_f32_e32 v90, v95, v95
	v_mul_f32_e32 v91, v97, v97
	v_fmac_f32_e32 v90, v94, v94
	v_fmac_f32_e32 v91, v96, v96
	v_add_f32_e32 v90, v90, v91
	v_mul_f32_e32 v91, v93, v93
	v_mul_f32_e32 v100, v99, v99
	v_fmac_f32_e32 v91, v92, v92
	v_fmac_f32_e32 v100, v98, v98
	v_add_f32_e32 v91, v91, v100
	v_add_f32_e32 v102, v90, v91
	v_cvt_pk_bf16_f32 v90, v94, v95
	v_cvt_pk_bf16_f32 v91, v96, v97
	v_lshlrev_b32_e32 v94, 16, v122
	v_and_b32_e32 v95, 0xffff0000, v122
	v_lshlrev_b32_e32 v96, 16, v123
	v_and_b32_e32 v97, 0xffff0000, v123
	v_cvt_pk_bf16_f32 v92, v92, v93
	v_cvt_pk_bf16_f32 v93, v98, v99
	v_lshlrev_b32_e32 v98, 16, v124
	v_and_b32_e32 v99, 0xffff0000, v124
	v_pk_add_f32 v[88:89], v[88:89], v[96:97]
	v_pk_add_f32 v[86:87], v[86:87], v[94:95]
	v_lshlrev_b32_e32 v100, 16, v125
	v_and_b32_e32 v101, 0xffff0000, v125
	v_pk_add_f32 v[96:97], v[82:83], v[98:99]
	v_mul_f32_e32 v82, v87, v87
	v_mul_f32_e32 v83, v89, v89
	v_pk_add_f32 v[94:95], v[84:85], v[100:101]
	v_fmac_f32_e32 v82, v86, v86
	v_fmac_f32_e32 v83, v88, v88
	v_add_f32_e32 v82, v82, v83
	v_mul_f32_e32 v83, v97, v97
	v_mul_f32_e32 v84, v95, v95
	v_fmac_f32_e32 v83, v96, v96
	v_fmac_f32_e32 v84, v94, v94
	v_add_f32_e32 v83, v83, v84
	v_add_f32_e32 v82, v82, v83
	v_add_f32_e32 v85, v102, v82
	ds_bpermute_b32 v100, v126, v85
	v_lshl_add_u64 v[82:83], s[8:9], 0, v[184:185]
	v_lshl_add_u64 v[98:99], v[172:173], 1, v[82:83]
	global_store_dwordx4 v[98:99], v[90:93], off
	v_cvt_pk_bf16_f32 v84, v86, v87
	s_waitcnt lgkmcnt(0)
	v_add_f32_e32 v82, v85, v100
	ds_bpermute_b32 v83, v127, v82
	v_cvt_pk_bf16_f32 v85, v88, v89
	v_cvt_pk_bf16_f32 v86, v96, v97
	v_cvt_pk_bf16_f32 v87, v94, v95
	global_store_dwordx4 v[98:99], v[84:87], off offset:256
	s_waitcnt lgkmcnt(0)
	v_add_f32_e32 v228, v82, v83
.LBB0_702:
	v_lshlrev_b32_e32 v82, 16, v118
	s_waitcnt lgkmcnt(0)
	v_and_b32_e32 v83, 0xffff0000, v118
	v_lshlrev_b32_e32 v84, 16, v119
	v_and_b32_e32 v85, 0xffff0000, v119
	v_lshlrev_b32_e32 v86, 16, v120
	v_and_b32_e32 v87, 0xffff0000, v120
	v_lshlrev_b32_e32 v88, 16, v121
	v_and_b32_e32 v89, 0xffff0000, v121
	v_pk_add_f32 v[80:81], v[80:81], v[84:85]
	v_pk_add_f32 v[78:79], v[78:79], v[82:83]
	v_pk_add_f32 v[82:83], v[76:77], v[88:89]
	v_pk_add_f32 v[76:77], v[74:75], v[86:87]
	v_mul_f32_e32 v74, v79, v79
	v_mul_f32_e32 v75, v81, v81
	v_fmac_f32_e32 v74, v78, v78
	v_fmac_f32_e32 v75, v80, v80
	v_add_f32_e32 v74, v74, v75
	v_mul_f32_e32 v75, v77, v77
	v_mul_f32_e32 v84, v83, v83
	v_fmac_f32_e32 v75, v76, v76
	v_fmac_f32_e32 v84, v82, v82
	v_add_f32_e32 v75, v75, v84
	v_add_f32_e32 v86, v74, v75
	v_cvt_pk_bf16_f32 v74, v78, v79
	v_cvt_pk_bf16_f32 v75, v80, v81
	v_lshlrev_b32_e32 v78, 16, v114
	v_and_b32_e32 v79, 0xffff0000, v114
	v_lshlrev_b32_e32 v80, 16, v115
	v_and_b32_e32 v81, 0xffff0000, v115
	v_cvt_pk_bf16_f32 v76, v76, v77
	v_cvt_pk_bf16_f32 v77, v82, v83
	v_lshlrev_b32_e32 v82, 16, v116
	v_and_b32_e32 v83, 0xffff0000, v116
	v_pk_add_f32 v[72:73], v[72:73], v[80:81]
	v_pk_add_f32 v[70:71], v[70:71], v[78:79]
	v_lshlrev_b32_e32 v84, 16, v117
	v_and_b32_e32 v85, 0xffff0000, v117
	v_pk_add_f32 v[80:81], v[66:67], v[82:83]
	v_mul_f32_e32 v66, v71, v71
	v_mul_f32_e32 v67, v73, v73
	v_pk_add_f32 v[78:79], v[68:69], v[84:85]
	v_fmac_f32_e32 v66, v70, v70
	v_fmac_f32_e32 v67, v72, v72
	v_add_f32_e32 v66, v66, v67
	v_mul_f32_e32 v67, v81, v81
	v_mul_f32_e32 v68, v79, v79
	v_fmac_f32_e32 v67, v80, v80
	v_fmac_f32_e32 v68, v78, v78
	v_add_f32_e32 v67, v67, v68
	v_add_f32_e32 v66, v66, v67
	v_add_f32_e32 v69, v86, v66
	ds_bpermute_b32 v84, v126, v69
	v_lshl_add_u64 v[66:67], s[8:9], 0, v[180:181]
	v_lshl_add_u64 v[82:83], v[172:173], 1, v[66:67]
	global_store_dwordx4 v[82:83], v[74:77], off
	v_cvt_pk_bf16_f32 v68, v70, v71
	s_waitcnt lgkmcnt(0)
	v_add_f32_e32 v66, v69, v84
	ds_bpermute_b32 v67, v127, v66
	v_cvt_pk_bf16_f32 v69, v72, v73
	v_cvt_pk_bf16_f32 v70, v80, v81
	v_cvt_pk_bf16_f32 v71, v78, v79
	global_store_dwordx4 v[82:83], v[68:71], off offset:256
	s_waitcnt lgkmcnt(0)
	v_add_f32_e32 v229, v66, v67
	v_mbcnt_lo_u32_b32 v230, -1, 0
	v_mbcnt_hi_u32_b32 v230, -1, v230
	v_bfe_u32 v230, v230, 4, 2
	v_cmp_eq_u32_e64 s[22:23], 0, v230
	v_lshl_add_u32 v232, v230, 4, v178
	v_subrev_u32_e32 v232, 48, v232
	v_cndmask_b32_e64 v229, v229, v226, s[22:23]
	v_cmp_eq_u32_e64 s[22:23], 1, v230
	v_ashrrev_i32_e32 v233, 31, v232
	v_lshl_add_u64 v[234:235], v[232:233], 2, s[10:11]
	v_cndmask_b32_e64 v229, v229, v227, s[22:23]
	v_cmp_eq_u32_e64 s[22:23], 2, v230
	s_nop 1
	v_cndmask_b32_e64 v229, v229, v228, s[22:23]
	global_atomic_add_f32 v[234:235], v229, off
.LBB0_704:
	v_add_u32_e32 v106, 0x80, v176
	v_ashrrev_i32_e32 v107, 31, v106
	v_lshlrev_b64 v[112:113], 11, v[106:107]
	s_waitcnt lgkmcnt(0)
	v_lshl_add_u64 v[66:67], v[174:175], 0, v[112:113]
	global_load_dwordx4 v[108:111], v[66:67], off
	global_load_dwordx4 v[90:93], v[66:67], off offset:256
	v_add_u32_e32 v102, 0x90, v176
	v_ashrrev_i32_e32 v103, 31, v102
	v_add_u32_e32 v98, 0xa0, v176
	v_lshlrev_b64 v[104:105], 11, v[102:103]
	v_ashrrev_i32_e32 v99, 31, v98
	v_add_u32_e32 v94, 0xb0, v176
	v_lshl_add_u64 v[66:67], v[174:175], 0, v[104:105]
	v_lshlrev_b64 v[100:101], 11, v[98:99]
	v_ashrrev_i32_e32 v95, 31, v94
	global_load_dwordx4 v[86:89], v[66:67], off
	global_load_dwordx4 v[82:85], v[66:67], off offset:256
	v_lshl_add_u64 v[66:67], v[174:175], 0, v[100:101]
	v_lshlrev_b64 v[96:97], 11, v[94:95]
	global_load_dwordx4 v[78:81], v[66:67], off
	global_load_dwordx4 v[74:77], v[66:67], off offset:256
	v_lshl_add_u64 v[66:67], v[174:175], 0, v[96:97]
	global_load_dwordx4 v[70:73], v[66:67], off
	s_nop 0
	global_load_dwordx4 v[66:69], v[66:67], off offset:256
	s_waitcnt vmcnt(7)
	v_lshlrev_b32_e32 v114, 16, v108
	v_and_b32_e32 v115, 0xffff0000, v108
	v_lshlrev_b32_e32 v108, 16, v109
	v_and_b32_e32 v109, 0xffff0000, v109
	v_lshlrev_b32_e32 v116, 16, v110
	v_and_b32_e32 v117, 0xffff0000, v110
	v_lshlrev_b32_e32 v110, 16, v111
	v_and_b32_e32 v111, 0xffff0000, v111
	v_pk_add_f32 v[64:65], v[64:65], v[108:109]
	v_pk_add_f32 v[62:63], v[62:63], v[114:115]
	v_pk_add_f32 v[108:109], v[60:61], v[110:111]
	v_mul_f32_e32 v60, v63, v63
	v_mul_f32_e32 v61, v65, v65
	v_pk_add_f32 v[58:59], v[58:59], v[116:117]
	v_fmac_f32_e32 v60, v62, v62
	v_fmac_f32_e32 v61, v64, v64
	v_add_f32_e32 v60, v60, v61
	v_mul_f32_e32 v61, v59, v59
	v_mul_f32_e32 v110, v109, v109
	v_fmac_f32_e32 v61, v58, v58
	v_fmac_f32_e32 v110, v108, v108
	v_add_f32_e32 v61, v61, v110
	v_add_f32_e32 v110, v60, v61
	v_cvt_pk_bf16_f32 v60, v62, v63
	v_cvt_pk_bf16_f32 v61, v64, v65
	v_cvt_pk_bf16_f32 v62, v58, v59
	v_lshl_add_u64 v[58:59], s[8:9], 0, v[112:113]
	v_cvt_pk_bf16_f32 v63, v108, v109
	v_lshl_add_u64 v[58:59], v[172:173], 1, v[58:59]
	global_store_dwordx4 v[58:59], v[60:63], off
	s_waitcnt vmcnt(7)
	v_lshlrev_b32_e32 v64, 16, v92
	v_and_b32_e32 v65, 0xffff0000, v92
	v_lshlrev_b32_e32 v60, 16, v90
	v_and_b32_e32 v61, 0xffff0000, v90
	v_lshlrev_b32_e32 v62, 16, v91
	v_and_b32_e32 v63, 0xffff0000, v91
	v_lshlrev_b32_e32 v90, 16, v93
	v_and_b32_e32 v91, 0xffff0000, v93
	v_pk_add_f32 v[56:57], v[56:57], v[62:63]
	v_pk_add_f32 v[54:55], v[54:55], v[60:61]
	v_pk_add_f32 v[60:61], v[52:53], v[90:91]
	v_pk_add_f32 v[52:53], v[50:51], v[64:65]
	v_mul_f32_e32 v50, v55, v55
	v_mul_f32_e32 v51, v57, v57
	v_fmac_f32_e32 v50, v54, v54
	v_fmac_f32_e32 v51, v56, v56
	v_add_f32_e32 v50, v50, v51
	v_mul_f32_e32 v51, v53, v53
	v_mul_f32_e32 v62, v61, v61
	v_fmac_f32_e32 v51, v52, v52
	v_fmac_f32_e32 v62, v60, v60
	v_add_f32_e32 v51, v51, v62
	v_add_f32_e32 v50, v50, v51
	v_add_f32_e32 v62, v110, v50
	v_cvt_pk_bf16_f32 v50, v54, v55
	v_cvt_pk_bf16_f32 v51, v56, v57
	v_cvt_pk_bf16_f32 v52, v52, v53
	v_cvt_pk_bf16_f32 v53, v60, v61
	global_store_dwordx4 v[58:59], v[50:53], off offset:256
	ds_bpermute_b32 v50, v126, v62
	s_waitcnt lgkmcnt(0)
	v_add_f32_e32 v50, v62, v50
	ds_bpermute_b32 v51, v127, v50
	s_waitcnt lgkmcnt(0)
	v_add_f32_e32 v226, v50, v51
.LBB0_706:
	s_waitcnt vmcnt(7)
	v_lshlrev_b32_e32 v50, 16, v86
	s_waitcnt lgkmcnt(0)
	v_and_b32_e32 v51, 0xffff0000, v86
	v_lshlrev_b32_e32 v52, 16, v87
	v_and_b32_e32 v53, 0xffff0000, v87
	v_lshlrev_b32_e32 v54, 16, v88
	v_and_b32_e32 v55, 0xffff0000, v88
	v_lshlrev_b32_e32 v56, 16, v89
	v_and_b32_e32 v57, 0xffff0000, v89
	v_pk_add_f32 v[48:49], v[48:49], v[52:53]
	v_pk_add_f32 v[46:47], v[46:47], v[50:51]
	v_pk_add_f32 v[50:51], v[44:45], v[56:57]
	v_pk_add_f32 v[44:45], v[42:43], v[54:55]
	v_mul_f32_e32 v42, v47, v47
	v_mul_f32_e32 v43, v49, v49
	v_fmac_f32_e32 v42, v46, v46
	v_fmac_f32_e32 v43, v48, v48
	v_add_f32_e32 v42, v42, v43
	v_mul_f32_e32 v43, v45, v45
	v_mul_f32_e32 v52, v51, v51
	v_fmac_f32_e32 v43, v44, v44
	v_fmac_f32_e32 v52, v50, v50
	v_add_f32_e32 v43, v43, v52
	v_add_f32_e32 v54, v42, v43
	v_cvt_pk_bf16_f32 v42, v46, v47
	v_cvt_pk_bf16_f32 v43, v48, v49
	s_waitcnt vmcnt(6)
	v_lshlrev_b32_e32 v46, 16, v82
	v_and_b32_e32 v47, 0xffff0000, v82
	v_lshlrev_b32_e32 v48, 16, v83
	v_and_b32_e32 v49, 0xffff0000, v83
	v_cvt_pk_bf16_f32 v44, v44, v45
	v_cvt_pk_bf16_f32 v45, v50, v51
	v_lshlrev_b32_e32 v50, 16, v84
	v_and_b32_e32 v51, 0xffff0000, v84
	v_pk_add_f32 v[40:41], v[40:41], v[48:49]
	v_pk_add_f32 v[38:39], v[38:39], v[46:47]
	v_lshlrev_b32_e32 v52, 16, v85
	v_and_b32_e32 v53, 0xffff0000, v85
	v_pk_add_f32 v[48:49], v[34:35], v[50:51]
	v_mul_f32_e32 v34, v39, v39
	v_mul_f32_e32 v35, v41, v41
	v_pk_add_f32 v[46:47], v[36:37], v[52:53]
	v_fmac_f32_e32 v34, v38, v38
	v_fmac_f32_e32 v35, v40, v40
	v_add_f32_e32 v34, v34, v35
	v_mul_f32_e32 v35, v49, v49
	v_mul_f32_e32 v36, v47, v47
	v_fmac_f32_e32 v35, v48, v48
	v_fmac_f32_e32 v36, v46, v46
	v_add_f32_e32 v35, v35, v36
	v_add_f32_e32 v34, v34, v35
	v_add_f32_e32 v37, v54, v34
	ds_bpermute_b32 v52, v126, v37
	v_lshl_add_u64 v[34:35], s[8:9], 0, v[104:105]
	v_lshl_add_u64 v[50:51], v[172:173], 1, v[34:35]
	global_store_dwordx4 v[50:51], v[42:45], off
	v_cvt_pk_bf16_f32 v36, v38, v39
	s_waitcnt lgkmcnt(0)
	v_add_f32_e32 v34, v37, v52
	ds_bpermute_b32 v35, v127, v34
	v_cvt_pk_bf16_f32 v37, v40, v41
	v_cvt_pk_bf16_f32 v38, v48, v49
	v_cvt_pk_bf16_f32 v39, v46, v47
	global_store_dwordx4 v[50:51], v[36:39], off offset:256
	s_waitcnt lgkmcnt(0)
	v_add_f32_e32 v227, v34, v35
.LBB0_708:
	s_waitcnt vmcnt(7)
	v_lshlrev_b32_e32 v34, 16, v78
	s_waitcnt lgkmcnt(0)
	v_and_b32_e32 v35, 0xffff0000, v78
	v_lshlrev_b32_e32 v36, 16, v79
	v_and_b32_e32 v37, 0xffff0000, v79
	v_lshlrev_b32_e32 v38, 16, v80
	v_and_b32_e32 v39, 0xffff0000, v80
	v_lshlrev_b32_e32 v40, 16, v81
	v_and_b32_e32 v41, 0xffff0000, v81
	v_pk_add_f32 v[32:33], v[32:33], v[36:37]
	v_pk_add_f32 v[30:31], v[30:31], v[34:35]
	v_pk_add_f32 v[34:35], v[28:29], v[40:41]
	v_pk_add_f32 v[28:29], v[26:27], v[38:39]
	v_mul_f32_e32 v26, v31, v31
	v_mul_f32_e32 v27, v33, v33
	v_fmac_f32_e32 v26, v30, v30
	v_fmac_f32_e32 v27, v32, v32
	v_add_f32_e32 v26, v26, v27
	v_mul_f32_e32 v27, v29, v29
	v_mul_f32_e32 v36, v35, v35
	v_fmac_f32_e32 v27, v28, v28
	v_fmac_f32_e32 v36, v34, v34
	v_add_f32_e32 v27, v27, v36
	v_add_f32_e32 v38, v26, v27
	v_cvt_pk_bf16_f32 v26, v30, v31
	v_cvt_pk_bf16_f32 v27, v32, v33
	s_waitcnt vmcnt(6)
	v_lshlrev_b32_e32 v30, 16, v74
	v_and_b32_e32 v31, 0xffff0000, v74
	v_lshlrev_b32_e32 v32, 16, v75
	v_and_b32_e32 v33, 0xffff0000, v75
	v_cvt_pk_bf16_f32 v28, v28, v29
	v_cvt_pk_bf16_f32 v29, v34, v35
	v_lshlrev_b32_e32 v34, 16, v76
	v_and_b32_e32 v35, 0xffff0000, v76
	v_pk_add_f32 v[24:25], v[24:25], v[32:33]
	v_pk_add_f32 v[22:23], v[22:23], v[30:31]
	v_lshlrev_b32_e32 v36, 16, v77
	v_and_b32_e32 v37, 0xffff0000, v77
	v_pk_add_f32 v[32:33], v[18:19], v[34:35]
	v_mul_f32_e32 v18, v23, v23
	v_mul_f32_e32 v19, v25, v25
	v_pk_add_f32 v[30:31], v[20:21], v[36:37]
	v_fmac_f32_e32 v18, v22, v22
	v_fmac_f32_e32 v19, v24, v24
	v_add_f32_e32 v18, v18, v19
	v_mul_f32_e32 v19, v33, v33
	v_mul_f32_e32 v20, v31, v31
	v_fmac_f32_e32 v19, v32, v32
	v_fmac_f32_e32 v20, v30, v30
	v_add_f32_e32 v19, v19, v20
	v_add_f32_e32 v18, v18, v19
	v_add_f32_e32 v21, v38, v18
	ds_bpermute_b32 v36, v126, v21
	v_lshl_add_u64 v[18:19], s[8:9], 0, v[100:101]
	v_lshl_add_u64 v[34:35], v[172:173], 1, v[18:19]
	global_store_dwordx4 v[34:35], v[26:29], off
	v_cvt_pk_bf16_f32 v20, v22, v23
	s_waitcnt lgkmcnt(0)
	v_add_f32_e32 v18, v21, v36
	ds_bpermute_b32 v19, v127, v18
	v_cvt_pk_bf16_f32 v21, v24, v25
	v_cvt_pk_bf16_f32 v22, v32, v33
	v_cvt_pk_bf16_f32 v23, v30, v31
	global_store_dwordx4 v[34:35], v[20:23], off offset:256
	s_waitcnt lgkmcnt(0)
	v_add_f32_e32 v228, v18, v19
.LBB0_710:
	s_waitcnt vmcnt(7)
	v_lshlrev_b32_e32 v18, 16, v70
	s_waitcnt lgkmcnt(0)
	v_and_b32_e32 v19, 0xffff0000, v70
	v_lshlrev_b32_e32 v20, 16, v71
	v_and_b32_e32 v21, 0xffff0000, v71
	v_lshlrev_b32_e32 v22, 16, v72
	v_and_b32_e32 v23, 0xffff0000, v72
	v_lshlrev_b32_e32 v24, 16, v73
	v_and_b32_e32 v25, 0xffff0000, v73
	v_pk_add_f32 v[16:17], v[16:17], v[20:21]
	v_pk_add_f32 v[14:15], v[14:15], v[18:19]
	v_pk_add_f32 v[18:19], v[12:13], v[24:25]
	v_pk_add_f32 v[12:13], v[10:11], v[22:23]
	v_mul_f32_e32 v10, v15, v15
	v_mul_f32_e32 v11, v17, v17
	v_fmac_f32_e32 v10, v14, v14
	v_fmac_f32_e32 v11, v16, v16
	v_add_f32_e32 v10, v10, v11
	v_mul_f32_e32 v11, v13, v13
	v_mul_f32_e32 v20, v19, v19
	v_fmac_f32_e32 v11, v12, v12
	v_fmac_f32_e32 v20, v18, v18
	v_add_f32_e32 v11, v11, v20
	v_add_f32_e32 v22, v10, v11
	v_cvt_pk_bf16_f32 v10, v14, v15
	v_cvt_pk_bf16_f32 v11, v16, v17
	s_waitcnt vmcnt(6)
	v_lshlrev_b32_e32 v14, 16, v66
	v_and_b32_e32 v15, 0xffff0000, v66
	v_lshlrev_b32_e32 v16, 16, v67
	v_and_b32_e32 v17, 0xffff0000, v67
	v_cvt_pk_bf16_f32 v12, v12, v13
	v_cvt_pk_bf16_f32 v13, v18, v19
	v_lshlrev_b32_e32 v18, 16, v68
	v_and_b32_e32 v19, 0xffff0000, v68
	v_pk_add_f32 v[8:9], v[8:9], v[16:17]
	v_pk_add_f32 v[6:7], v[6:7], v[14:15]
	v_lshlrev_b32_e32 v20, 16, v69
	v_and_b32_e32 v21, 0xffff0000, v69
	v_pk_add_f32 v[16:17], v[2:3], v[18:19]
	v_mul_f32_e32 v2, v7, v7
	v_mul_f32_e32 v3, v9, v9
	v_pk_add_f32 v[14:15], v[4:5], v[20:21]
	v_fmac_f32_e32 v2, v6, v6
	v_fmac_f32_e32 v3, v8, v8
	v_add_f32_e32 v2, v2, v3
	v_mul_f32_e32 v3, v17, v17
	v_mul_f32_e32 v4, v15, v15
	v_fmac_f32_e32 v3, v16, v16
	v_fmac_f32_e32 v4, v14, v14
	v_add_f32_e32 v3, v3, v4
	v_add_f32_e32 v2, v2, v3
	v_add_f32_e32 v5, v22, v2
	ds_bpermute_b32 v20, v126, v5
	v_lshl_add_u64 v[2:3], s[8:9], 0, v[96:97]
	v_lshl_add_u64 v[18:19], v[172:173], 1, v[2:3]
	global_store_dwordx4 v[18:19], v[10:13], off
	v_cvt_pk_bf16_f32 v4, v6, v7
	s_waitcnt lgkmcnt(0)
	v_add_f32_e32 v2, v5, v20
	ds_bpermute_b32 v3, v127, v2
	v_cvt_pk_bf16_f32 v5, v8, v9
	v_cvt_pk_bf16_f32 v6, v16, v17
	v_cvt_pk_bf16_f32 v7, v14, v15
	global_store_dwordx4 v[18:19], v[4:7], off offset:256
	s_waitcnt lgkmcnt(0)
	v_add_f32_e32 v229, v2, v3
	v_mbcnt_lo_u32_b32 v230, -1, 0
	v_mbcnt_hi_u32_b32 v230, -1, v230
	v_bfe_u32 v230, v230, 4, 2
	v_cmp_eq_u32_e64 s[22:23], 0, v230
	v_lshl_add_u32 v232, v230, 4, v94
	v_subrev_u32_e32 v232, 48, v232
	v_cndmask_b32_e64 v229, v229, v226, s[22:23]
	v_cmp_eq_u32_e64 s[22:23], 1, v230
	v_ashrrev_i32_e32 v233, 31, v232
	v_lshl_add_u64 v[234:235], v[232:233], 2, s[10:11]
	v_cndmask_b32_e64 v229, v229, v227, s[22:23]
	v_cmp_eq_u32_e64 s[22:23], 2, v230
	s_nop 1
	v_cndmask_b32_e64 v229, v229, v228, s[22:23]
	global_atomic_add_f32 v[234:235], v229, off
.LBB0_712:
	s_mov_b32 s98, 1
	s_andn2_b64 vcc, exec, s[6:7]
	s_mov_b64 s[6:7], -1
	s_cbranch_vccnz .LBB0_685
	s_andn2_b64 vcc, exec, s[2:3]
	s_cbranch_vccnz .LBB0_684
	s_barrier
	s_branch .LBB0_684

.LBB0_769:
	s_mov_b32 s98, 0
	s_or_b64 exec, exec, s[2:3]
	v_readlane_b32 s2, v254, 28
	v_readlane_b32 s4, v253, 12
	s_mul_i32 s48, s2, 0x10800
	s_mul_i32 s33, s2, 0x5800
	s_mov_b64 s[2:3], s[84:85]
	v_mov_b32_e32 v0, v165
	v_mov_b32_e32 v10, v165
	v_readlane_b32 s5, v253, 13
	s_waitcnt lgkmcnt(0)
	s_barrier
	s_and_b64 vcc, exec, s[4:5]
	v_readfirstlane_b32 s6, v10
	s_cbranch_vccz .LBB0_827
	s_load_dwordx2 s[4:5], s[2:3], 0x90
	s_lshl_b64 s[8:9], s[80:81], 2
	v_mov_b32_e32 v0, v165
	s_waitcnt lgkmcnt(0)
	s_add_u32 s7, s4, s8
	s_addc_u32 s8, s5, s9
	s_add_u32 s40, s7, 0x3220000
	s_addc_u32 s41, s8, 0
	v_readfirstlane_b32 s8, v0
	v_and_b32_e32 v2, 63, v0
	s_ashr_i32 s7, s8, 6
	s_cmp_gt_i32 s7, 3
	v_lshlrev_b32_e32 v0, 2, v2
	s_cbranch_scc1 .LBB0_772
	s_lshl_b32 s9, s7, 8
	s_add_i32 s9, s9, 0
	s_add_i32 m0, s9, 0x20400
	v_readlane_b32 s10, v253, 49
	v_readlane_b32 s11, v253, 50
	s_add_u32 s9, s40, s10
	s_addc_u32 s12, s41, s11
	s_and_b32 s10, s8, 0xffffffc0
	s_ashr_i32 s11, s10, 31
	s_lshl_b64 s[10:11], s[10:11], 2
	s_add_u32 s10, s9, s10
	s_addc_u32 s11, s12, s11
	global_load_lds_dword v0, s[10:11]

.LBB0_787:
	s_add_u32 s34, s8, 0x100
	s_addc_u32 s35, s9, 0
	s_and_b64 s[36:37], s[36:37], exec
	s_cselect_b32 s39, s64, s35
	s_cselect_b32 s38, s65, s34
	s_cselect_b32 s37, s25, s69
	s_cselect_b32 s36, s66, s68
	s_add_i32 s71, 0, 0x10000
	v_add_u32_e32 v0, s71, v228
	s_add_i32 s74, 0, 0x14000
	ds_read_b128 v[130:133], v0
	ds_read_b128 v[134:137], v0 offset:1024
	ds_read_b128 v[138:141], v0 offset:2048
	ds_read_b128 v[154:157], v0 offset:3072
	v_add_u32_e32 v0, s74, v228
	ds_read_b128 v[166:169], v0
	ds_read_b128 v[170:173], v0 offset:1024
	ds_read_b128 v[174:177], v0 offset:2048
	ds_read_b128 v[178:181], v0 offset:3072
	v_lshl_add_u64 v[158:159], s[8:9], 0, v[150:151]
	s_add_i32 m0, s52, 0xc000
	ds_read_b128 v[182:185], v233
	ds_read_b128 v[186:189], v233 offset:1024
	ds_read_b128 v[190:193], v233 offset:2048
	ds_read_b128 v[194:197], v233 offset:3072
	ds_read_b128 v[198:201], v233 offset:4096
	ds_read_b128 v[202:205], v233 offset:5120
	ds_read_b128 v[206:209], v233 offset:6144
	ds_read_b128 v[210:213], v233 offset:7168
	global_load_lds_dwordx4 v[158:159], off
	v_lshl_add_u64 v[158:159], s[8:9], 0, v[152:153]
	s_add_i32 m0, s52, 0xe000
	s_nop 0
	global_load_lds_dwordx4 v[158:159], off
	s_cmp_lg_u32 s98, 0
	s_cbranch_scc1 .Lrx_u_1
	s_waitcnt vmcnt(8)
.Lrx_u_1:
	s_waitcnt lgkmcnt(0)
	s_barrier
	s_setprio 1
	s_waitcnt lgkmcnt(0)
	v_mfma_f32_16x16x32_bf16 v[118:121], v[130:133], v[182:185], v[118:121]
	v_mfma_f32_16x16x32_bf16 v[54:57], v[138:141], v[182:185], v[54:57]
	v_mfma_f32_16x16x32_bf16 v[114:117], v[130:133], v[190:193], v[114:117]
	v_mfma_f32_16x16x32_bf16 v[50:53], v[138:141], v[190:193], v[50:53]
	v_mfma_f32_16x16x32_bf16 v[126:129], v[130:133], v[198:201], v[126:129]
	v_mfma_f32_16x16x32_bf16 v[62:65], v[138:141], v[198:201], v[62:65]
	v_mfma_f32_16x16x32_bf16 v[122:125], v[130:133], v[206:209], v[122:125]
	v_mfma_f32_16x16x32_bf16 v[58:61], v[138:141], v[206:209], v[58:61]
	v_mfma_f32_16x16x32_bf16 v[118:121], v[134:137], v[186:189], v[118:121]
	v_mfma_f32_16x16x32_bf16 v[54:57], v[154:157], v[186:189], v[54:57]
	v_mfma_f32_16x16x32_bf16 v[114:117], v[134:137], v[194:197], v[114:117]
	v_mfma_f32_16x16x32_bf16 v[50:53], v[154:157], v[194:197], v[50:53]
	v_mfma_f32_16x16x32_bf16 v[126:129], v[134:137], v[202:205], v[126:129]
	v_mfma_f32_16x16x32_bf16 v[62:65], v[154:157], v[202:205], v[62:65]
	v_mfma_f32_16x16x32_bf16 v[122:125], v[134:137], v[210:213], v[122:125]
	v_mfma_f32_16x16x32_bf16 v[58:61], v[154:157], v[210:213], v[58:61]
	s_setprio 0
	s_setprio 1
	v_mfma_f32_16x16x32_bf16 v[102:105], v[166:169], v[182:185], v[102:105]
	v_mfma_f32_16x16x32_bf16 v[38:41], v[174:177], v[182:185], v[38:41]
	v_mfma_f32_16x16x32_bf16 v[98:101], v[166:169], v[190:193], v[98:101]
	v_mfma_f32_16x16x32_bf16 v[34:37], v[174:177], v[190:193], v[34:37]
	v_mfma_f32_16x16x32_bf16 v[110:113], v[166:169], v[198:201], v[110:113]
	v_mfma_f32_16x16x32_bf16 v[46:49], v[174:177], v[198:201], v[46:49]
	v_mfma_f32_16x16x32_bf16 v[106:109], v[166:169], v[206:209], v[106:109]
	v_mfma_f32_16x16x32_bf16 v[42:45], v[174:177], v[206:209], v[42:45]
	v_mfma_f32_16x16x32_bf16 v[102:105], v[170:173], v[186:189], v[102:105]
	v_mfma_f32_16x16x32_bf16 v[38:41], v[178:181], v[186:189], v[38:41]
	v_mfma_f32_16x16x32_bf16 v[98:101], v[170:173], v[194:197], v[98:101]
	v_mfma_f32_16x16x32_bf16 v[34:37], v[178:181], v[194:197], v[34:37]
	v_mfma_f32_16x16x32_bf16 v[110:113], v[170:173], v[202:205], v[110:113]
	v_mfma_f32_16x16x32_bf16 v[46:49], v[178:181], v[202:205], v[46:49]
	v_mfma_f32_16x16x32_bf16 v[106:109], v[170:173], v[210:213], v[106:109]
	v_mfma_f32_16x16x32_bf16 v[42:45], v[178:181], v[210:213], v[42:45]
	s_setprio 0
	s_barrier
	s_add_i32 s8, s71, s51
	v_lshl_add_u64 v[158:159], s[36:37], 0, v[144:145]
	s_mov_b32 m0, s8
	ds_read_b128 v[182:185], v233 offset:16384
	ds_read_b128 v[186:189], v233 offset:17408
	ds_read_b128 v[190:193], v233 offset:18432
	ds_read_b128 v[194:197], v233 offset:19456
	ds_read_b128 v[198:201], v233 offset:20480
	ds_read_b128 v[202:205], v233 offset:21504
	ds_read_b128 v[206:209], v233 offset:22528
	ds_read_b128 v[210:213], v233 offset:23552
	global_load_lds_dwordx4 v[158:159], off
	s_add_i32 m0, s8, 0x2000
	s_add_u32 s8, s36, 0x40000
	v_lshl_add_u64 v[162:163], s[36:37], 0, v[148:149]
	s_addc_u32 s9, s37, 0
	s_add_i32 s71, s74, s51
	global_load_lds_dwordx4 v[162:163], off
	v_lshl_add_u64 v[214:215], s[8:9], 0, v[144:145]
	s_mov_b32 m0, s71
	v_lshl_add_u64 v[216:217], s[38:39], 0, v[146:147]
	global_load_lds_dwordx4 v[214:215], off
	v_lshl_add_u64 v[214:215], s[8:9], 0, v[148:149]
	s_add_i32 m0, s71, 0x2000
	s_nop 0
	global_load_lds_dwordx4 v[214:215], off
	v_lshl_add_u64 v[214:215], s[38:39], 0, v[142:143]
	s_mov_b32 m0, s52
	s_nop 0
	global_load_lds_dwordx4 v[214:215], off
	s_mov_b32 m0, s53
	s_nop 0
	global_load_lds_dwordx4 v[216:217], off
	s_cmp_lg_u32 s98, 0
	s_cbranch_scc1 .Lrx_u_2
	s_waitcnt vmcnt(8)
.Lrx_u_2:
	s_mov_b32 s98, 0
	s_waitcnt lgkmcnt(0)
	s_barrier
	s_setprio 1
	s_waitcnt lgkmcnt(0)
	v_mfma_f32_16x16x32_bf16 v[86:89], v[130:133], v[182:185], v[86:89]
	v_mfma_f32_16x16x32_bf16 v[22:25], v[138:141], v[182:185], v[22:25]
	v_mfma_f32_16x16x32_bf16 v[82:85], v[130:133], v[190:193], v[82:85]
	v_mfma_f32_16x16x32_bf16 v[18:21], v[138:141], v[190:193], v[18:21]
	v_mfma_f32_16x16x32_bf16 v[94:97], v[130:133], v[198:201], v[94:97]
	v_mfma_f32_16x16x32_bf16 v[30:33], v[138:141], v[198:201], v[30:33]
	v_mfma_f32_16x16x32_bf16 v[90:93], v[130:133], v[206:209], v[90:93]
	v_mfma_f32_16x16x32_bf16 v[26:29], v[138:141], v[206:209], v[26:29]
	v_mfma_f32_16x16x32_bf16 v[86:89], v[134:137], v[186:189], v[86:89]
	v_mfma_f32_16x16x32_bf16 v[22:25], v[154:157], v[186:189], v[22:25]
	v_mfma_f32_16x16x32_bf16 v[82:85], v[134:137], v[194:197], v[82:85]
	v_mfma_f32_16x16x32_bf16 v[18:21], v[154:157], v[194:197], v[18:21]
	v_mfma_f32_16x16x32_bf16 v[94:97], v[134:137], v[202:205], v[94:97]
	v_mfma_f32_16x16x32_bf16 v[30:33], v[154:157], v[202:205], v[30:33]
	v_mfma_f32_16x16x32_bf16 v[90:93], v[134:137], v[210:213], v[90:93]
	v_mfma_f32_16x16x32_bf16 v[26:29], v[154:157], v[210:213], v[26:29]
	s_setprio 0
	s_setprio 1
	v_mfma_f32_16x16x32_bf16 v[70:73], v[166:169], v[182:185], v[70:73]
	v_mfma_f32_16x16x32_bf16 v[6:9], v[174:177], v[182:185], v[6:9]
	v_mfma_f32_16x16x32_bf16 v[66:69], v[166:169], v[190:193], v[66:69]
	v_mfma_f32_16x16x32_bf16 v[2:5], v[174:177], v[190:193], v[2:5]
	v_mfma_f32_16x16x32_bf16 v[78:81], v[166:169], v[198:201], v[78:81]
	v_mfma_f32_16x16x32_bf16 v[14:17], v[174:177], v[198:201], v[14:17]
	v_mfma_f32_16x16x32_bf16 v[74:77], v[166:169], v[206:209], v[74:77]
	v_mfma_f32_16x16x32_bf16 v[10:13], v[174:177], v[206:209], v[10:13]
	v_mfma_f32_16x16x32_bf16 v[70:73], v[170:173], v[186:189], v[70:73]
	v_mfma_f32_16x16x32_bf16 v[6:9], v[178:181], v[186:189], v[6:9]
	v_mfma_f32_16x16x32_bf16 v[66:69], v[170:173], v[194:197], v[66:69]
	v_mfma_f32_16x16x32_bf16 v[2:5], v[178:181], v[194:197], v[2:5]
	v_mfma_f32_16x16x32_bf16 v[78:81], v[170:173], v[202:205], v[78:81]
	v_mfma_f32_16x16x32_bf16 v[14:17], v[178:181], v[202:205], v[14:17]
	v_mfma_f32_16x16x32_bf16 v[74:77], v[170:173], v[210:213], v[74:77]
	v_mfma_f32_16x16x32_bf16 v[10:13], v[178:181], v[210:213], v[10:13]
	s_setprio 0
	s_barrier
	s_add_i32 s71, 0, 0x18000
	v_add_u32_e32 v0, s71, v228
	s_add_i32 s74, 0, 0x1c000
	ds_read_b128 v[130:133], v0
	ds_read_b128 v[134:137], v0 offset:1024
	ds_read_b128 v[138:141], v0 offset:2048
	ds_read_b128 v[154:157], v0 offset:3072
	v_add_u32_e32 v0, s74, v228
	ds_read_b128 v[166:169], v0
	ds_read_b128 v[170:173], v0 offset:1024
	ds_read_b128 v[174:177], v0 offset:2048
	ds_read_b128 v[178:181], v0 offset:3072
	s_add_u32 s8, s38, 0x40000
	s_addc_u32 s9, s39, 0
	s_mov_b32 m0, s54
	v_lshl_add_u64 v[218:219], s[8:9], 0, v[142:143]
	ds_read_b128 v[182:185], v233 offset:32768
	ds_read_b128 v[186:189], v233 offset:33792
	ds_read_b128 v[190:193], v233 offset:34816
	ds_read_b128 v[194:197], v233 offset:35840
	ds_read_b128 v[198:201], v233 offset:36864
	ds_read_b128 v[202:205], v233 offset:37888
	ds_read_b128 v[206:209], v233 offset:38912
	ds_read_b128 v[210:213], v233 offset:39936
	global_load_lds_dwordx4 v[218:219], off
	v_lshl_add_u64 v[218:219], s[8:9], 0, v[146:147]
	s_mov_b32 m0, s55
	s_nop 0
	global_load_lds_dwordx4 v[218:219], off
	s_waitcnt vmcnt(8)
	s_waitcnt lgkmcnt(0)
	s_barrier
	s_setprio 1
	s_waitcnt lgkmcnt(0)
	v_mfma_f32_16x16x32_bf16 v[118:121], v[130:133], v[182:185], v[118:121]
	v_mfma_f32_16x16x32_bf16 v[54:57], v[138:141], v[182:185], v[54:57]
	v_mfma_f32_16x16x32_bf16 v[114:117], v[130:133], v[190:193], v[114:117]
	v_mfma_f32_16x16x32_bf16 v[50:53], v[138:141], v[190:193], v[50:53]
	v_mfma_f32_16x16x32_bf16 v[126:129], v[130:133], v[198:201], v[126:129]
	v_mfma_f32_16x16x32_bf16 v[62:65], v[138:141], v[198:201], v[62:65]
	v_mfma_f32_16x16x32_bf16 v[122:125], v[130:133], v[206:209], v[122:125]
	v_mfma_f32_16x16x32_bf16 v[58:61], v[138:141], v[206:209], v[58:61]
	v_mfma_f32_16x16x32_bf16 v[118:121], v[134:137], v[186:189], v[118:121]
	v_mfma_f32_16x16x32_bf16 v[54:57], v[154:157], v[186:189], v[54:57]
	v_mfma_f32_16x16x32_bf16 v[114:117], v[134:137], v[194:197], v[114:117]
	v_mfma_f32_16x16x32_bf16 v[50:53], v[154:157], v[194:197], v[50:53]
	v_mfma_f32_16x16x32_bf16 v[126:129], v[134:137], v[202:205], v[126:129]
	v_mfma_f32_16x16x32_bf16 v[62:65], v[154:157], v[202:205], v[62:65]
	v_mfma_f32_16x16x32_bf16 v[122:125], v[134:137], v[210:213], v[122:125]
	v_mfma_f32_16x16x32_bf16 v[58:61], v[154:157], v[210:213], v[58:61]
	s_setprio 0
	s_setprio 1
	v_mfma_f32_16x16x32_bf16 v[102:105], v[166:169], v[182:185], v[102:105]
	v_mfma_f32_16x16x32_bf16 v[38:41], v[174:177], v[182:185], v[38:41]
	v_mfma_f32_16x16x32_bf16 v[98:101], v[166:169], v[190:193], v[98:101]
	v_mfma_f32_16x16x32_bf16 v[34:37], v[174:177], v[190:193], v[34:37]
	v_mfma_f32_16x16x32_bf16 v[110:113], v[166:169], v[198:201], v[110:113]
	v_mfma_f32_16x16x32_bf16 v[46:49], v[174:177], v[198:201], v[46:49]
	v_mfma_f32_16x16x32_bf16 v[106:109], v[166:169], v[206:209], v[106:109]
	v_mfma_f32_16x16x32_bf16 v[42:45], v[174:177], v[206:209], v[42:45]
	v_mfma_f32_16x16x32_bf16 v[102:105], v[170:173], v[186:189], v[102:105]
	v_mfma_f32_16x16x32_bf16 v[38:41], v[178:181], v[186:189], v[38:41]
	v_mfma_f32_16x16x32_bf16 v[98:101], v[170:173], v[194:197], v[98:101]
	v_mfma_f32_16x16x32_bf16 v[34:37], v[178:181], v[194:197], v[34:37]
	v_mfma_f32_16x16x32_bf16 v[110:113], v[170:173], v[202:205], v[110:113]
	v_mfma_f32_16x16x32_bf16 v[46:49], v[178:181], v[202:205], v[46:49]
	v_mfma_f32_16x16x32_bf16 v[106:109], v[170:173], v[210:213], v[106:109]
	v_mfma_f32_16x16x32_bf16 v[42:45], v[178:181], v[210:213], v[42:45]
	s_setprio 0
	s_barrier
	s_add_i32 s8, s71, s51
	v_lshl_add_u64 v[158:159], v[158:159], 0, s[82:83]
	s_mov_b32 m0, s8
	ds_read_b128 v[182:185], v233 offset:49152
	ds_read_b128 v[186:189], v233 offset:50176
	ds_read_b128 v[190:193], v233 offset:51200
	ds_read_b128 v[194:197], v233 offset:52224
	ds_read_b128 v[198:201], v233 offset:53248
	ds_read_b128 v[202:205], v233 offset:54272
	ds_read_b128 v[206:209], v233 offset:55296
	ds_read_b128 v[210:213], v233 offset:56320
	global_load_lds_dwordx4 v[158:159], off
	s_add_i32 m0, s8, 0x2000
	s_add_u32 s8, s36, 0x40080
	v_lshl_add_u64 v[158:159], v[162:163], 0, s[82:83]
	s_addc_u32 s9, s37, 0
	s_add_i32 s36, s74, s51
	global_load_lds_dwordx4 v[158:159], off
	v_lshl_add_u64 v[158:159], s[8:9], 0, v[144:145]
	s_mov_b32 m0, s36
	s_nop 0
	global_load_lds_dwordx4 v[158:159], off
	v_lshl_add_u64 v[158:159], s[8:9], 0, v[148:149]
	s_add_i32 m0, s36, 0x2000
	s_nop 0
	global_load_lds_dwordx4 v[158:159], off
	v_lshl_add_u64 v[158:159], v[214:215], 0, s[82:83]
	s_mov_b32 m0, s58
	s_nop 0
	global_load_lds_dwordx4 v[158:159], off
	v_lshl_add_u64 v[158:159], v[216:217], 0, s[82:83]
	s_mov_b32 m0, s59
	s_nop 0
	global_load_lds_dwordx4 v[158:159], off
	s_waitcnt vmcnt(8)
	s_waitcnt lgkmcnt(0)
	s_barrier
	s_setprio 1
	s_waitcnt lgkmcnt(0)
	v_mfma_f32_16x16x32_bf16 v[86:89], v[130:133], v[182:185], v[86:89]
	v_mfma_f32_16x16x32_bf16 v[22:25], v[138:141], v[182:185], v[22:25]
	v_mfma_f32_16x16x32_bf16 v[82:85], v[130:133], v[190:193], v[82:85]
	v_mfma_f32_16x16x32_bf16 v[18:21], v[138:141], v[190:193], v[18:21]
	v_mfma_f32_16x16x32_bf16 v[94:97], v[130:133], v[198:201], v[94:97]
	v_mfma_f32_16x16x32_bf16 v[30:33], v[138:141], v[198:201], v[30:33]
	v_mfma_f32_16x16x32_bf16 v[90:93], v[130:133], v[206:209], v[90:93]
	v_mfma_f32_16x16x32_bf16 v[26:29], v[138:141], v[206:209], v[26:29]
	v_mfma_f32_16x16x32_bf16 v[86:89], v[134:137], v[186:189], v[86:89]
	v_mfma_f32_16x16x32_bf16 v[22:25], v[154:157], v[186:189], v[22:25]
	v_mfma_f32_16x16x32_bf16 v[82:85], v[134:137], v[194:197], v[82:85]
	v_mfma_f32_16x16x32_bf16 v[18:21], v[154:157], v[194:197], v[18:21]
	v_mfma_f32_16x16x32_bf16 v[94:97], v[134:137], v[202:205], v[94:97]
	v_mfma_f32_16x16x32_bf16 v[30:33], v[154:157], v[202:205], v[30:33]
	v_mfma_f32_16x16x32_bf16 v[90:93], v[134:137], v[210:213], v[90:93]
	v_mfma_f32_16x16x32_bf16 v[26:29], v[154:157], v[210:213], v[26:29]
	s_setprio 0
	s_setprio 1
	v_mfma_f32_16x16x32_bf16 v[70:73], v[166:169], v[182:185], v[70:73]
	v_mfma_f32_16x16x32_bf16 v[6:9], v[174:177], v[182:185], v[6:9]
	v_mfma_f32_16x16x32_bf16 v[66:69], v[166:169], v[190:193], v[66:69]
	v_mfma_f32_16x16x32_bf16 v[2:5], v[174:177], v[190:193], v[2:5]
	v_mfma_f32_16x16x32_bf16 v[78:81], v[166:169], v[198:201], v[78:81]
	v_mfma_f32_16x16x32_bf16 v[14:17], v[174:177], v[198:201], v[14:17]
	v_mfma_f32_16x16x32_bf16 v[74:77], v[166:169], v[206:209], v[74:77]
	v_mfma_f32_16x16x32_bf16 v[10:13], v[174:177], v[206:209], v[10:13]
	v_mfma_f32_16x16x32_bf16 v[70:73], v[170:173], v[186:189], v[70:73]
	v_mfma_f32_16x16x32_bf16 v[6:9], v[178:181], v[186:189], v[6:9]
	v_mfma_f32_16x16x32_bf16 v[66:69], v[170:173], v[194:197], v[66:69]
	v_mfma_f32_16x16x32_bf16 v[2:5], v[178:181], v[194:197], v[2:5]
	v_mfma_f32_16x16x32_bf16 v[78:81], v[170:173], v[202:205], v[78:81]
	v_mfma_f32_16x16x32_bf16 v[14:17], v[178:181], v[202:205], v[14:17]
	v_mfma_f32_16x16x32_bf16 v[74:77], v[170:173], v[210:213], v[74:77]
	v_mfma_f32_16x16x32_bf16 v[10:13], v[178:181], v[210:213], v[10:13]
	s_setprio 0
	s_barrier
	s_add_i32 s70, s70, 2
	s_add_u32 s68, s68, 0x100
	s_addc_u32 s69, s69, 0
	s_cmp_gt_u32 s70, 13
	s_cbranch_scc1 .LBB0_789
	s_mov_b64 s[8:9], s[34:35]
	s_branch .LBB0_782

.LBB0_799:
	s_or_b64 exec, exec, s[8:9]
	s_waitcnt lgkmcnt(0)
	v_pk_fma_f32 v[162:163], v[114:115], v[198:199], v[118:119]
	v_pk_fma_f32 v[158:159], v[116:117], v[216:217], v[120:121]
	v_pk_fma_f32 v[162:163], v[110:111], v[178:179], v[162:163]
	v_pk_fma_f32 v[178:179], v[114:115], v[178:179], v[118:119]
	v_pk_fma_f32 v[162:163], v[102:103], v[106:107], v[162:163]
	v_pk_fma_f32 v[178:179], v[102:103], v[110:111], v[178:179]
	v_pk_fma_f32 v[102:103], v[102:103], v[114:115], v[118:119]
	v_pk_fma_f32 v[158:159], v[112:113], v[188:189], v[158:159]
	v_pk_fma_f32 v[188:189], v[116:117], v[188:189], v[120:121]
	v_pk_fma_f32 v[198:199], v[98:99], v[106:107], v[178:179]
	v_pk_fma_f32 v[102:103], v[98:99], v[110:111], v[102:103]
	v_pk_fma_f32 v[98:99], v[98:99], v[114:115], v[118:119]
	v_pk_fma_f32 v[158:159], v[104:105], v[108:109], v[158:159]
	v_pk_fma_f32 v[188:189], v[104:105], v[112:113], v[188:189]
	v_pk_fma_f32 v[104:105], v[104:105], v[116:117], v[120:121]
	v_pk_fma_f32 v[178:179], v[208:209], v[106:107], v[102:103]
	v_pk_fma_f32 v[102:103], v[208:209], v[110:111], v[98:99]
	v_pk_fma_f32 v[110:111], v[134:135], v[194:195], v[138:139]
	v_pk_fma_f32 v[188:189], v[100:101], v[108:109], v[188:189]
	v_pk_fma_f32 v[104:105], v[100:101], v[112:113], v[104:105]
	v_pk_fma_f32 v[100:101], v[100:101], v[116:117], v[120:121]
	v_pk_fma_f32 v[110:111], v[130:131], v[190:191], v[110:111]
	v_pk_fma_f32 v[100:101], v[210:211], v[112:113], v[100:101]
	v_pk_fma_f32 v[110:111], v[126:127], v[206:207], v[110:111]
	v_pk_fma_f32 v[98:99], v[214:215], v[108:109], v[100:101]
	v_pk_fma_f32 v[100:101], v[212:213], v[106:107], v[102:103]
	v_mul_f32_e32 v107, 0xbfb8aa3b, v110
	v_pk_fma_f32 v[104:105], v[210:211], v[108:109], v[104:105]
	v_exp_f32_e32 v107, v107
	v_mul_f32_e32 v109, 0xbfb8aa3b, v111
	v_pk_fma_f32 v[102:103], v[124:125], s[66:67], v[164:165] op_sel_hi:[1,0,0]
	v_exp_f32_e32 v109, v109
	v_mul_f32_e32 v106, 0x4b800000, v102
	v_cmp_gt_f32_e64 s[8:9], s77, v102
	v_add_f32_e32 v107, 1.0, v107
	v_pk_fma_f32 v[112:113], v[134:135], v[190:191], v[138:139]
	v_cndmask_b32_e64 v102, v102, v106, s[8:9]
	v_rsq_f32_e32 v102, v102
	v_rcp_f32_e32 v107, v107
	v_add_f32_e32 v109, 1.0, v109
	v_pk_fma_f32 v[114:115], v[130:131], v[206:207], v[112:113]
	v_rcp_f32_e32 v109, v109
	v_pk_fma_f32 v[124:125], v[126:127], v[202:203], v[114:115]
	v_pk_fma_f32 v[114:115], v[134:135], v[206:207], v[138:139]
	v_mul_f32_e32 v106, 0x45800000, v102
	v_pk_fma_f32 v[114:115], v[130:131], v[202:203], v[114:115]
	v_cmp_gt_f32_e32 vcc, s77, v103
	v_cndmask_b32_e64 v106, v102, v106, s[8:9]
	v_mul_f32_e32 v102, 0x4b800000, v103
	v_pk_fma_f32 v[118:119], v[126:127], v[180:181], v[114:115]
	v_pk_fma_f32 v[114:115], v[134:135], v[202:203], v[138:139]
	v_mul_f32_e32 v107, v110, v107
	v_cndmask_b32_e32 v102, v103, v102, vcc
	v_pk_fma_f32 v[114:115], v[130:131], v[180:181], v[114:115]
	v_mul_f32_e32 v107, v107, v162
	v_mul_f32_e32 v109, v111, v109
	v_rsq_f32_e32 v102, v102
	v_pk_fma_f32 v[114:115], v[126:127], v[184:185], v[114:115]
	v_mul_f32_e32 v109, v109, v163
	v_cvt_pk_bf16_f32 v126, v107, v109
	v_mul_f32_e32 v107, 0xbfb8aa3b, v124
	v_exp_f32_e32 v107, v107
	v_mul_f32_e32 v103, 0x45800000, v102
	v_cndmask_b32_e32 v108, v102, v103, vcc
	v_pk_fma_f32 v[102:103], v[136:137], v[196:197], v[140:141]
	v_add_f32_e32 v107, 1.0, v107
	v_pk_fma_f32 v[102:103], v[132:133], v[192:193], v[102:103]
	v_rcp_f32_e32 v107, v107
	v_pk_fma_f32 v[120:121], v[128:129], v[204:205], v[102:103]
	v_pk_fma_f32 v[102:103], v[136:137], v[192:193], v[140:141]
	v_mul_f32_e32 v110, 0xbfb8aa3b, v120
	v_pk_fma_f32 v[102:103], v[132:133], v[204:205], v[102:103]
	v_mul_f32_e32 v107, v124, v107
	v_pk_fma_f32 v[112:113], v[128:129], v[200:201], v[102:103]
	v_mul_f32_e32 v111, 0xbfb8aa3b, v121
	v_mul_f32_e32 v124, 0xbfb8aa3b, v112
	v_exp_f32_e32 v124, v124
	v_exp_f32_e32 v110, v110
	v_exp_f32_e32 v111, v111
	v_mul_f32_e32 v109, 0xbfb8aa3b, v125
	v_add_f32_e32 v124, 1.0, v124
	v_rcp_f32_e32 v124, v124
	v_exp_f32_e32 v109, v109
	v_add_f32_e32 v110, 1.0, v110
	v_add_f32_e32 v111, 1.0, v111
	v_mul_f32_e32 v112, v112, v124
	v_mul_f32_e32 v124, 0xbfb8aa3b, v113
	v_exp_f32_e32 v124, v124
	v_rcp_f32_e32 v110, v110
	v_rcp_f32_e32 v111, v111
	v_pk_fma_f32 v[102:103], v[136:137], v[204:205], v[140:141]
	v_add_f32_e32 v109, 1.0, v109
	v_add_f32_e32 v124, 1.0, v124
	v_pk_fma_f32 v[102:103], v[132:133], v[200:201], v[102:103]
	v_rcp_f32_e32 v109, v109
	v_rcp_f32_e32 v124, v124
	v_pk_fma_f32 v[116:117], v[128:129], v[182:183], v[102:103]
	v_pk_fma_f32 v[102:103], v[136:137], v[200:201], v[140:141]
	v_mul_f32_e32 v110, v120, v110
	v_mul_f32_e32 v111, v121, v111
	v_lshl_add_u32 v208, s62, 8, v229
	v_pk_fma_f32 v[102:103], v[132:133], v[182:183], v[102:103]
	v_mul_f32_e32 v110, v110, v158
	v_mul_f32_e32 v111, v111, v159
	v_mov_b64_e32 v[120:121], s[16:17]
	s_movk_i32 s10, 0x1600
	v_pk_fma_f32 v[102:103], v[128:129], v[186:187], v[102:103]
	v_cvt_pk_bf16_f32 v127, v110, v111
	v_mad_i64_i32 v[110:111], s[8:9], v208, s10, v[120:121]
	v_lshlrev_b64 v[128:129], 1, v[176:177]
	v_lshl_add_u64 v[110:111], v[110:111], 0, v[128:129]
	v_mul_f32_e32 v107, v107, v198
	v_mul_f32_e32 v109, v125, v109
	v_mul_f32_e32 v113, v113, v124
	v_mov_b32_e32 v238, v126
	v_mov_b32_e32 v239, v127
	v_mul_f32_e32 v109, v109, v199
	v_mul_f32_e32 v112, v112, v188
	v_mul_f32_e32 v113, v113, v189
	v_cvt_pk_bf16_f32 v124, v107, v109
	v_or_b32_e32 v107, 1, v208
	v_cvt_pk_bf16_f32 v125, v112, v113
	v_mad_i64_i32 v[112:113], s[8:9], v107, s10, v[120:121]
	v_mul_f32_e32 v107, 0xbfb8aa3b, v118
	v_exp_f32_e32 v107, v107
	v_mul_f32_e32 v109, 0xbfb8aa3b, v119
	v_exp_f32_e32 v109, v109
	v_lshl_add_u64 v[112:113], v[112:113], 0, v[128:129]
	v_add_f32_e32 v107, 1.0, v107
	v_rcp_f32_e32 v107, v107
	v_add_f32_e32 v109, 1.0, v109
	v_rcp_f32_e32 v109, v109
	v_mov_b32_e32 v240, v124
	v_mov_b32_e32 v241, v125
	v_mul_f32_e32 v107, v118, v107
	v_mul_f32_e32 v118, 0xbfb8aa3b, v116
	v_exp_f32_e32 v118, v118
	v_mul_f32_e32 v107, v107, v178
	v_mul_f32_e32 v109, v119, v109
	v_mul_f32_e32 v109, v109, v179
	v_add_f32_e32 v118, 1.0, v118
	v_rcp_f32_e32 v118, v118
	s_mov_b64 s[34:35], -1
	v_mul_f32_e32 v116, v116, v118
	v_mul_f32_e32 v116, v116, v104
	v_mul_f32_e32 v104, 0xbfb8aa3b, v117
	v_exp_f32_e32 v104, v104
	s_nop 0
	v_add_f32_e32 v104, 1.0, v104
	v_rcp_f32_e32 v104, v104
	s_nop 0
	v_mul_f32_e32 v104, v117, v104
	v_mul_f32_e32 v105, v104, v105
	v_cvt_pk_bf16_f32 v104, v107, v109
	v_or_b32_e32 v107, 2, v208
	v_cvt_pk_bf16_f32 v105, v116, v105
	v_mad_i64_i32 v[116:117], s[8:9], v107, s10, v[120:121]
	v_lshl_add_u64 v[118:119], v[116:117], 0, v[128:129]
	v_mov_b32_e32 v242, v104
	v_mov_b32_e32 v243, v105
	v_mul_f32_e32 v104, 0xbfb8aa3b, v114
	v_exp_f32_e32 v104, v104
	v_mov_b32_e32 v107, v106
	v_mov_b32_e32 v109, v108
	v_pk_mul_f32 v[132:133], v[96:97], v[106:107] op_sel_hi:[1,0]
	v_add_f32_e32 v104, 1.0, v104
	v_rcp_f32_e32 v104, v104
	v_pk_mul_f32 v[130:131], v[94:95], v[106:107] op_sel_hi:[1,0]
	v_pk_mul_f32 v[136:137], v[92:93], v[108:109] op_sel_hi:[1,0]
	v_pk_mul_f32 v[134:135], v[90:91], v[108:109] op_sel_hi:[1,0]
	v_mul_f32_e32 v104, v114, v104
	v_mul_f32_e32 v100, v104, v100
	v_mul_f32_e32 v104, 0xbfb8aa3b, v115
	v_exp_f32_e32 v104, v104
	v_mov_b32_dpp v138, v134 row_shr:1 row_mask:0xf bank_mask:0xf bound_ctrl:1
	v_mov_b32_dpp v178, v130 row_shr:1 row_mask:0xf bank_mask:0xf bound_ctrl:1
	v_mov_b32_dpp v139, v135 row_shr:1 row_mask:0xf bank_mask:0xf bound_ctrl:1
	v_add_f32_e32 v104, 1.0, v104
	v_rcp_f32_e32 v104, v104
	v_mov_b32_dpp v179, v131 row_shr:1 row_mask:0xf bank_mask:0xf bound_ctrl:1
	v_mov_b32_dpp v140, v136 row_shr:1 row_mask:0xf bank_mask:0xf bound_ctrl:1
	v_mov_b32_dpp v180, v132 row_shr:1 row_mask:0xf bank_mask:0xf bound_ctrl:1
	v_mul_f32_e32 v104, v115, v104
	v_mul_f32_e32 v101, v104, v101
	v_mul_f32_e32 v104, 0xbfb8aa3b, v102
	v_exp_f32_e32 v104, v104
	v_mov_b32_dpp v141, v137 row_shr:1 row_mask:0xf bank_mask:0xf bound_ctrl:1
	v_mov_b32_dpp v181, v133 row_shr:1 row_mask:0xf bank_mask:0xf bound_ctrl:1
	v_mov_b32_e32 v114, v106
	v_add_f32_e32 v104, 1.0, v104
	v_rcp_f32_e32 v104, v104
	v_mov_b32_e32 v115, v106
	v_mov_b32_e32 v116, v108
	v_mov_b32_e32 v117, v108
	v_mul_f32_e32 v102, v102, v104
	v_mul_f32_e32 v102, v102, v98
	v_mul_f32_e32 v98, 0xbfb8aa3b, v103
	v_exp_f32_e32 v98, v98
	s_nop 0
	v_add_f32_e32 v98, 1.0, v98
	v_rcp_f32_e32 v98, v98
	s_nop 0
	v_mul_f32_e32 v98, v103, v98
	v_mul_f32_e32 v99, v98, v99
	v_cvt_pk_bf16_f32 v98, v100, v101
	v_or_b32_e32 v100, 3, v208
	v_mad_i64_i32 v[100:101], s[8:9], v100, s10, v[120:121]
	v_lshl_add_u64 v[124:125], v[100:101], 0, v[128:129]
	v_cvt_pk_bf16_f32 v99, v102, v99
	v_mov_b32_e32 v244, v98
	v_mov_b32_e32 v245, v99
	ds_read_b128 v[98:101], v0 offset:1024
	ds_read_b128 v[94:97], v0 offset:1536
	ds_read_b128 v[90:93], v0 offset:2048
	ds_read_b128 v[102:105], v0 offset:2560
	v_pk_fma_f32 v[120:121], v[122:123], s[66:67], v[164:165] op_sel_hi:[1,0,0]
	v_cmp_gt_i32_e64 s[10:11], 15, v225
	v_cmp_gt_f32_e32 vcc, s77, v121
	v_cmp_gt_f32_e64 s[8:9], s77, v120
	s_and_saveexec_b64 s[36:37], s[10:11]
	v_cmp_eq_u32_e64 s[10:11], 0, v225
	s_orn2_b64 s[34:35], s[10:11], exec
	s_or_b64 exec, exec, s[36:37]
	v_mul_f32_e32 v122, 0x4b800000, v120
	v_cndmask_b32_e64 v120, v120, v122, s[8:9]
	v_mul_f32_e32 v122, 0x4b800000, v121
	v_rsq_f32_e32 v120, v120
	v_cndmask_b32_e32 v121, v121, v122, vcc
	v_rsq_f32_e32 v121, v121
	v_mov_b64_e32 v[126:127], s[14:15]
	v_mul_f32_e32 v122, 0x45800000, v120
	v_cndmask_b32_e64 v122, v120, v122, s[8:9]
	v_mul_f32_e32 v120, 0x45800000, v121
	v_cndmask_b32_e32 v120, v121, v120, vcc
	v_add_u32_e32 v121, s25, v231
	s_movk_i32 s8, 0x5800
	v_mad_i64_i32 v[126:127], s[8:9], v121, s8, v[126:127]
	v_pk_mul_f32 v[186:187], v[88:89], v[122:123] op_sel_hi:[1,0]
	v_pk_mul_f32 v[188:189], v[86:87], v[122:123] op_sel_hi:[1,0]
	v_pk_mul_f32 v[182:183], v[84:85], v[120:121] op_sel_hi:[1,0]
	v_pk_mul_f32 v[184:185], v[82:83], v[120:121] op_sel_hi:[1,0]
	v_lshl_add_u64 v[126:127], v[176:177], 2, v[126:127]
	s_and_saveexec_b64 s[8:9], s[34:35]
	s_cbranch_execz .LBB0_803
	v_cndmask_b32_e64 v85, v133, v187, s[4:5]
	v_cndmask_b32_e64 v84, v132, v186, s[4:5]
	v_cndmask_b32_e64 v83, v131, v189, s[4:5]
	v_cndmask_b32_e64 v82, v130, v188, s[4:5]
	v_add_co_u32_e32 v86, vcc, 0x5000, v126
	global_store_dwordx4 v[126:127], v[82:85], off
	s_nop 0
	v_addc_co_u32_e32 v87, vcc, 0, v127, vcc
	v_cndmask_b32_e64 v85, v137, v183, s[4:5]
	v_cndmask_b32_e64 v84, v136, v182, s[4:5]
	v_cndmask_b32_e64 v83, v135, v185, s[4:5]
	v_cndmask_b32_e64 v82, v134, v184, s[4:5]
	global_store_dwordx4 v[86:87], v[82:85], off offset:2048

.LBB0_807:
	s_or_b64 exec, exec, s[8:9]
	s_waitcnt lgkmcnt(0)
	v_pk_fma_f32 v[158:159], v[84:85], v[202:203], v[88:89]
	v_pk_fma_f32 v[162:163], v[82:83], v[200:201], v[86:87]
	v_pk_fma_f32 v[158:159], v[80:81], v[198:199], v[158:159]
	v_pk_fma_f32 v[198:199], v[84:85], v[198:199], v[88:89]
	v_pk_fma_f32 v[158:159], v[72:73], v[76:77], v[158:159]
	v_pk_fma_f32 v[198:199], v[72:73], v[80:81], v[198:199]
	v_pk_fma_f32 v[72:73], v[72:73], v[84:85], v[88:89]
	v_pk_fma_f32 v[162:163], v[78:79], v[196:197], v[162:163]
	v_pk_fma_f32 v[196:197], v[82:83], v[196:197], v[86:87]
	v_pk_fma_f32 v[198:199], v[68:69], v[76:77], v[198:199]
	v_pk_fma_f32 v[72:73], v[68:69], v[80:81], v[72:73]
	v_pk_fma_f32 v[68:69], v[68:69], v[84:85], v[88:89]
	v_pk_fma_f32 v[162:163], v[70:71], v[74:75], v[162:163]
	v_pk_fma_f32 v[196:197], v[70:71], v[78:79], v[196:197]
	v_pk_fma_f32 v[70:71], v[70:71], v[82:83], v[86:87]
	v_pk_fma_f32 v[68:69], v[190:191], v[80:81], v[68:69]
	v_pk_fma_f32 v[196:197], v[66:67], v[74:75], v[196:197]
	v_pk_fma_f32 v[70:71], v[66:67], v[78:79], v[70:71]
	v_pk_fma_f32 v[72:73], v[190:191], v[76:77], v[72:73]
	v_pk_fma_f32 v[66:67], v[66:67], v[82:83], v[86:87]
	v_pk_fma_f32 v[68:69], v[194:195], v[76:77], v[68:69]
	v_pk_fma_f32 v[76:77], v[98:99], v[178:179], v[102:103]
	v_pk_fma_f32 v[66:67], v[176:177], v[78:79], v[66:67]
	v_pk_fma_f32 v[76:77], v[94:95], v[138:139], v[76:77]
	v_pk_fma_f32 v[70:71], v[176:177], v[74:75], v[70:71]
	v_pk_fma_f32 v[66:67], v[192:193], v[74:75], v[66:67]
	v_pk_fma_f32 v[74:75], v[100:101], v[180:181], v[104:105]
	v_pk_fma_f32 v[76:77], v[188:189], v[90:91], v[76:77]
	v_pk_fma_f32 v[78:79], v[100:101], v[140:141], v[104:105]
	v_pk_fma_f32 v[82:83], v[186:187], v[100:101], v[104:105]
	v_pk_fma_f32 v[86:87], v[182:183], v[100:101], v[104:105]
	v_pk_fma_f32 v[74:75], v[96:97], v[140:141], v[74:75]
	v_pk_fma_f32 v[78:79], v[186:187], v[96:97], v[78:79]
	v_pk_fma_f32 v[82:83], v[182:183], v[96:97], v[82:83]
	v_pk_fma_f32 v[86:87], v[132:133], v[96:97], v[86:87]
	v_mul_f32_e32 v96, 0xbfb8aa3b, v76
	v_exp_f32_e32 v96, v96
	v_pk_fma_f32 v[80:81], v[98:99], v[138:139], v[102:103]
	v_pk_fma_f32 v[84:85], v[188:189], v[98:99], v[102:103]
	v_pk_fma_f32 v[88:89], v[184:185], v[98:99], v[102:103]
	v_pk_fma_f32 v[80:81], v[188:189], v[94:95], v[80:81]
	v_pk_fma_f32 v[84:85], v[184:185], v[94:95], v[84:85]
	v_pk_fma_f32 v[88:89], v[130:131], v[94:95], v[88:89]
	v_pk_fma_f32 v[80:81], v[184:185], v[90:91], v[80:81]
	v_pk_fma_f32 v[84:85], v[130:131], v[90:91], v[84:85]
	v_pk_fma_f32 v[88:89], v[134:135], v[90:91], v[88:89]
	v_add_f32_e32 v90, 1.0, v96
	v_mul_f32_e32 v91, 0xbfb8aa3b, v77
	v_rcp_f32_e32 v90, v90
	v_exp_f32_e32 v91, v91
	v_pk_fma_f32 v[74:75], v[186:187], v[92:93], v[74:75]
	v_pk_fma_f32 v[78:79], v[182:183], v[92:93], v[78:79]
	v_mul_f32_e32 v76, v76, v90
	v_add_f32_e32 v90, 1.0, v91
	v_mul_f32_e32 v91, 0xbfb8aa3b, v74
	v_pk_fma_f32 v[82:83], v[132:133], v[92:93], v[82:83]
	v_pk_fma_f32 v[86:87], v[136:137], v[92:93], v[86:87]
	v_rcp_f32_e32 v90, v90
	v_exp_f32_e32 v91, v91
	v_mul_f32_e32 v93, 0xbfb8aa3b, v75
	v_exp_f32_e32 v93, v93
	v_mul_f32_e32 v77, v77, v90
	v_add_f32_e32 v90, 1.0, v91
	v_rcp_f32_e32 v90, v90
	v_add_f32_e32 v91, 1.0, v93
	v_rcp_f32_e32 v91, v91
	v_mul_f32_e32 v76, v76, v162
	v_mul_f32_e32 v74, v74, v90
	v_mul_f32_e32 v77, v77, v163
	v_mul_f32_e32 v74, v74, v158
	v_mul_f32_e32 v75, v75, v91
	v_mul_f32_e32 v75, v75, v159
	v_cvt_pk_bf16_f32 v76, v76, v77
	v_cvt_pk_bf16_f32 v77, v74, v75
	v_mul_f32_e32 v74, 0xbfb8aa3b, v80
	v_exp_f32_e32 v93, v74
	v_add_u32_e32 v92, 0x80, v208
	v_mov_b64_e32 v[90:91], s[16:17]
	s_movk_i32 s10, 0x1600
	v_mad_i64_i32 v[74:75], s[8:9], v92, s10, v[90:91]
	v_add_f32_e32 v92, 1.0, v93
	v_rcp_f32_e32 v92, v92
	v_mul_f32_e32 v93, 0xbfb8aa3b, v81
	v_exp_f32_e32 v93, v93
	v_lshl_add_u64 v[74:75], v[74:75], 0, v[128:129]
	v_mov_b32_e32 v246, v76
	v_mov_b32_e32 v247, v77
	v_mul_f32_e32 v76, v80, v92
	v_mul_f32_e32 v80, 0xbfb8aa3b, v78
	v_add_f32_e32 v77, 1.0, v93
	v_exp_f32_e32 v80, v80
	v_mul_f32_e32 v92, 0xbfb8aa3b, v79
	v_rcp_f32_e32 v77, v77
	v_exp_f32_e32 v92, v92
	v_add_f32_e32 v80, 1.0, v80
	v_rcp_f32_e32 v80, v80
	v_mul_f32_e32 v77, v81, v77
	v_add_f32_e32 v81, 1.0, v92
	v_rcp_f32_e32 v81, v81
	v_mul_f32_e32 v78, v78, v80
	v_mul_f32_e32 v77, v77, v197
	v_mul_f32_e32 v80, v78, v198
	v_mul_f32_e32 v78, v79, v81
	v_mul_f32_e32 v76, v76, v196
	v_mul_f32_e32 v79, v78, v199
	v_cvt_pk_bf16_f32 v78, v76, v77
	v_mul_f32_e32 v77, 0xbfb8aa3b, v84
	v_cvt_pk_bf16_f32 v79, v80, v79
	v_exp_f32_e32 v80, v77
	v_add_u32_e32 v76, 0x81, v208
	v_mad_i64_i32 v[76:77], s[8:9], v76, s10, v[90:91]
	v_add_f32_e32 v80, 1.0, v80
	v_rcp_f32_e32 v80, v80
	v_lshl_add_u64 v[76:77], v[76:77], 0, v[128:129]
	v_mul_f32_e32 v81, 0xbfb8aa3b, v85
	v_exp_f32_e32 v81, v81
	v_mov_b32_e32 v248, v78
	v_mov_b32_e32 v249, v79
	v_mul_f32_e32 v79, 0xbfb8aa3b, v82
	v_mul_f32_e32 v78, v84, v80
	v_exp_f32_e32 v79, v79
	v_mul_f32_e32 v80, 0xbfb8aa3b, v83
	v_exp_f32_e32 v80, v80
	v_mul_f32_e32 v70, v78, v70
	v_add_f32_e32 v78, 1.0, v81
	v_rcp_f32_e32 v78, v78
	v_add_f32_e32 v79, 1.0, v79
	v_rcp_f32_e32 v79, v79
	v_add_f32_e32 v80, 1.0, v80
	v_rcp_f32_e32 v80, v80
	v_mul_f32_e32 v78, v85, v78
	v_mul_f32_e32 v71, v78, v71
	v_mul_f32_e32 v78, v82, v79
	v_mul_f32_e32 v72, v78, v72
	v_mul_f32_e32 v78, v83, v80
	v_mul_f32_e32 v73, v78, v73
	v_cvt_pk_bf16_f32 v70, v70, v71
	v_cvt_pk_bf16_f32 v71, v72, v73
	v_mul_f32_e32 v73, 0xbfb8aa3b, v88
	v_exp_f32_e32 v80, v73
	v_add_u32_e32 v72, 0x82, v208
	v_mad_i64_i32 v[72:73], s[8:9], v72, s10, v[90:91]
	v_lshl_add_u64 v[78:79], v[72:73], 0, v[128:129]
	v_add_f32_e32 v72, 1.0, v80
	v_rcp_f32_e32 v72, v72
	v_mul_f32_e32 v73, 0xbfb8aa3b, v89
	v_exp_f32_e32 v73, v73
	v_mov_b32_e32 v250, v70
	v_mov_b32_e32 v251, v71
	v_mul_f32_e32 v71, 0xbfb8aa3b, v86
	v_mul_f32_e32 v70, v88, v72
	v_exp_f32_e32 v71, v71
	v_mul_f32_e32 v72, 0xbfb8aa3b, v87
	v_exp_f32_e32 v72, v72
	v_mul_f32_e32 v66, v70, v66
	v_add_f32_e32 v70, 1.0, v73
	v_rcp_f32_e32 v70, v70
	v_add_f32_e32 v71, 1.0, v71
	v_rcp_f32_e32 v71, v71
	v_add_f32_e32 v72, 1.0, v72
	v_rcp_f32_e32 v72, v72
	v_mul_f32_e32 v70, v89, v70
	v_mul_f32_e32 v67, v70, v67
	v_mul_f32_e32 v70, v86, v71
	v_mul_f32_e32 v68, v70, v68
	v_mul_f32_e32 v70, v87, v72
	v_mul_f32_e32 v69, v70, v69
	v_cvt_pk_bf16_f32 v66, v66, v67
	v_cvt_pk_bf16_f32 v67, v68, v69
	v_add_u32_e32 v68, 0x83, v208
	v_mad_i64_i32 v[68:69], s[8:9], v68, s10, v[90:91]
	v_lshl_add_u64 v[80:81], v[68:69], 0, v[128:129]
	v_mov_b32_e32 v236, v66
	v_mov_b32_e32 v237, v67
	v_pk_mul_f32 v[84:85], v[64:65], v[166:167]
	v_pk_mul_f32 v[82:83], v[62:63], v[156:157]
	v_pk_mul_f32 v[88:89], v[60:61], v[168:169]
	v_pk_mul_f32 v[86:87], v[58:59], v[154:155]
	ds_read_b128 v[66:69], v0 offset:1040
	ds_read_b128 v[62:65], v0 offset:1552
	ds_read_b128 v[58:61], v0 offset:2064
	ds_read_b128 v[70:73], v0 offset:2576
	v_mov_b32_dpp v90, v86 row_shr:1 row_mask:0xf bank_mask:0xf bound_ctrl:1
	v_mov_b32_dpp v94, v82 row_shr:1 row_mask:0xf bank_mask:0xf bound_ctrl:1
	v_mov_b32_dpp v91, v87 row_shr:1 row_mask:0xf bank_mask:0xf bound_ctrl:1
	v_mov_b32_dpp v95, v83 row_shr:1 row_mask:0xf bank_mask:0xf bound_ctrl:1
	v_mov_b32_dpp v92, v88 row_shr:1 row_mask:0xf bank_mask:0xf bound_ctrl:1
	v_mov_b32_dpp v96, v84 row_shr:1 row_mask:0xf bank_mask:0xf bound_ctrl:1
	v_mov_b32_dpp v93, v89 row_shr:1 row_mask:0xf bank_mask:0xf bound_ctrl:1
	v_mov_b32_dpp v97, v85 row_shr:1 row_mask:0xf bank_mask:0xf bound_ctrl:1
	v_cmp_gt_i32_e32 vcc, 15, v225
	s_mov_b64 s[10:11], -1
	s_and_saveexec_b64 s[8:9], vcc
	v_cmp_eq_u32_e32 vcc, 0, v225
	s_orn2_b64 s[10:11], vcc, exec
	s_or_b64 exec, exec, s[8:9]
	v_mov_b32_e32 v98, v172
	v_mov_b32_e32 v99, v172
	v_pk_mul_f32 v[104:105], v[54:55], v[172:173]
	v_mov_b32_e32 v54, v170
	v_mov_b32_e32 v55, v170
	v_pk_mul_f32 v[100:101], v[56:57], v[98:99]
	v_pk_mul_f32 v[98:99], v[52:53], v[54:55]
	v_pk_mul_f32 v[102:103], v[50:51], v[170:171]
	v_lshl_add_u64 v[136:137], v[174:175], 0, 16
	s_and_saveexec_b64 s[8:9], s[10:11]
	s_cbranch_execz .LBB0_811
	v_cndmask_b32_e64 v53, v85, v101, s[4:5]
	v_cndmask_b32_e64 v52, v84, v100, s[4:5]
	v_cndmask_b32_e64 v51, v83, v105, s[4:5]
	v_cndmask_b32_e64 v50, v82, v104, s[4:5]
	v_add_co_u32_e32 v54, vcc, 0x5000, v136
	global_store_dwordx4 v[136:137], v[50:53], off
	s_nop 0
	v_addc_co_u32_e32 v55, vcc, 0, v137, vcc
	v_cndmask_b32_e64 v53, v89, v99, s[4:5]
	v_cndmask_b32_e64 v52, v88, v98, s[4:5]
	v_cndmask_b32_e64 v51, v87, v103, s[4:5]
	v_cndmask_b32_e64 v50, v86, v102, s[4:5]
	global_store_dwordx4 v[54:55], v[50:53], off offset:2048

.LBB0_815:
	s_or_b64 exec, exec, s[8:9]
	s_waitcnt lgkmcnt(0)
	v_pk_fma_f32 v[136:137], v[52:53], v[156:157], v[56:57]
	v_pk_fma_f32 v[154:155], v[50:51], v[154:155], v[54:55]
	v_pk_fma_f32 v[136:137], v[48:49], v[140:141], v[136:137]
	v_pk_fma_f32 v[140:141], v[52:53], v[140:141], v[56:57]
	v_pk_fma_f32 v[136:137], v[40:41], v[44:45], v[136:137]
	v_pk_fma_f32 v[140:141], v[40:41], v[48:49], v[140:141]
	v_pk_fma_f32 v[40:41], v[40:41], v[52:53], v[56:57]
	v_pk_fma_f32 v[140:141], v[36:37], v[44:45], v[140:141]
	v_pk_fma_f32 v[40:41], v[36:37], v[48:49], v[40:41]
	v_pk_fma_f32 v[36:37], v[36:37], v[52:53], v[56:57]
	v_pk_fma_f32 v[40:41], v[130:131], v[44:45], v[40:41]
	v_pk_fma_f32 v[36:37], v[130:131], v[48:49], v[36:37]
	v_pk_fma_f32 v[154:155], v[46:47], v[138:139], v[154:155]
	v_pk_fma_f32 v[36:37], v[134:135], v[44:45], v[36:37]
	v_pk_fma_f32 v[44:45], v[66:67], v[94:95], v[70:71]
	v_pk_fma_f32 v[138:139], v[50:51], v[138:139], v[54:55]
	v_pk_fma_f32 v[44:45], v[62:63], v[90:91], v[44:45]
	v_pk_fma_f32 v[154:155], v[38:39], v[42:43], v[154:155]
	v_pk_fma_f32 v[138:139], v[38:39], v[46:47], v[138:139]
	v_pk_fma_f32 v[38:39], v[38:39], v[50:51], v[54:55]
	v_pk_fma_f32 v[44:45], v[104:105], v[58:59], v[44:45]
	v_pk_fma_f32 v[138:139], v[34:35], v[42:43], v[138:139]
	v_pk_fma_f32 v[38:39], v[34:35], v[46:47], v[38:39]
	v_pk_fma_f32 v[34:35], v[34:35], v[50:51], v[54:55]
	v_pk_fma_f32 v[48:49], v[66:67], v[90:91], v[70:71]
	v_pk_fma_f32 v[52:53], v[104:105], v[66:67], v[70:71]
	v_pk_fma_f32 v[56:57], v[102:103], v[66:67], v[70:71]
	v_mul_f32_e32 v66, 0xbfb8aa3b, v44
	v_pk_fma_f32 v[34:35], v[128:129], v[46:47], v[34:35]
	v_exp_f32_e32 v66, v66
	v_pk_fma_f32 v[38:39], v[128:129], v[42:43], v[38:39]
	v_pk_fma_f32 v[34:35], v[132:133], v[42:43], v[34:35]
	v_pk_fma_f32 v[42:43], v[68:69], v[96:97], v[72:73]
	v_pk_fma_f32 v[46:47], v[68:69], v[92:93], v[72:73]
	v_pk_fma_f32 v[50:51], v[100:101], v[68:69], v[72:73]
	v_pk_fma_f32 v[54:55], v[98:99], v[68:69], v[72:73]
	v_pk_fma_f32 v[42:43], v[64:65], v[92:93], v[42:43]
	v_pk_fma_f32 v[46:47], v[100:101], v[64:65], v[46:47]
	v_pk_fma_f32 v[50:51], v[98:99], v[64:65], v[50:51]
	v_pk_fma_f32 v[54:55], v[84:85], v[64:65], v[54:55]
	v_pk_fma_f32 v[42:43], v[100:101], v[60:61], v[42:43]
	v_pk_fma_f32 v[46:47], v[98:99], v[60:61], v[46:47]
	v_pk_fma_f32 v[50:51], v[84:85], v[60:61], v[50:51]
	v_pk_fma_f32 v[54:55], v[88:89], v[60:61], v[54:55]
	v_mul_f32_e32 v61, 0xbfb8aa3b, v45
	v_add_f32_e32 v60, 1.0, v66
	v_exp_f32_e32 v61, v61
	v_rcp_f32_e32 v60, v60
	v_pk_fma_f32 v[48:49], v[104:105], v[62:63], v[48:49]
	v_pk_fma_f32 v[52:53], v[102:103], v[62:63], v[52:53]
	v_pk_fma_f32 v[56:57], v[82:83], v[62:63], v[56:57]
	v_pk_fma_f32 v[48:49], v[102:103], v[58:59], v[48:49]
	v_pk_fma_f32 v[52:53], v[82:83], v[58:59], v[52:53]
	v_pk_fma_f32 v[56:57], v[86:87], v[58:59], v[56:57]
	v_add_f32_e32 v58, 1.0, v61
	v_mul_f32_e32 v59, 0xbfb8aa3b, v42
	v_mul_f32_e32 v44, v44, v60
	v_rcp_f32_e32 v58, v58
	v_exp_f32_e32 v59, v59
	v_mul_f32_e32 v60, 0xbfb8aa3b, v43
	v_exp_f32_e32 v60, v60
	v_mul_f32_e32 v45, v45, v58
	v_add_f32_e32 v58, 1.0, v59
	v_rcp_f32_e32 v58, v58
	v_add_f32_e32 v59, 1.0, v60
	v_rcp_f32_e32 v59, v59
	v_mul_f32_e32 v44, v44, v154
	v_mul_f32_e32 v42, v42, v58
	v_mul_f32_e32 v58, v42, v136
	v_mul_f32_e32 v42, v43, v59
	v_mul_f32_e32 v43, 0xbfb8aa3b, v48
	v_exp_f32_e32 v59, v43
	v_mul_f32_e32 v45, v45, v155
	v_mul_f32_e32 v43, v42, v137
	v_cvt_pk_bf16_f32 v42, v44, v45
	v_add_f32_e32 v44, 1.0, v59
	v_rcp_f32_e32 v44, v44
	v_mul_f32_e32 v45, 0xbfb8aa3b, v49
	v_cvt_pk_bf16_f32 v43, v58, v43
	v_exp_f32_e32 v45, v45
	v_mov_b32_e32 v210, v238
	v_mov_b32_e32 v211, v239
	v_mov_b32_e32 v212, v42
	v_mov_b32_e32 v213, v43
	global_store_dwordx4 v[110:111], v[210:213], off
	v_mul_f32_e32 v42, v48, v44
	v_mul_f32_e32 v44, 0xbfb8aa3b, v46
	v_exp_f32_e32 v44, v44
	v_add_f32_e32 v43, 1.0, v45
	v_mul_f32_e32 v45, 0xbfb8aa3b, v47
	v_exp_f32_e32 v45, v45
	v_add_f32_e32 v44, 1.0, v44
	v_rcp_f32_e32 v44, v44
	v_rcp_f32_e32 v43, v43
	v_add_f32_e32 v45, 1.0, v45
	v_rcp_f32_e32 v45, v45
	v_mul_f32_e32 v44, v46, v44
	v_mul_f32_e32 v46, 0xbfb8aa3b, v52
	v_exp_f32_e32 v46, v46
	v_mul_f32_e32 v43, v49, v43
	v_mul_f32_e32 v42, v42, v138
	v_mul_f32_e32 v43, v43, v139
	v_mul_f32_e32 v44, v44, v140
	v_mul_f32_e32 v45, v47, v45
	v_mul_f32_e32 v45, v45, v141
	v_cvt_pk_bf16_f32 v42, v42, v43
	v_cvt_pk_bf16_f32 v43, v44, v45
	v_add_f32_e32 v44, 1.0, v46
	v_rcp_f32_e32 v44, v44
	v_mul_f32_e32 v45, 0xbfb8aa3b, v53
	v_exp_f32_e32 v45, v45
	v_mov_b32_e32 v214, v240
	v_mov_b32_e32 v215, v241
	v_mov_b32_e32 v216, v42
	v_mov_b32_e32 v217, v43
	global_store_dwordx4 v[112:113], v[214:217], off
	v_mul_f32_e32 v43, 0xbfb8aa3b, v50
	v_exp_f32_e32 v43, v43
	v_mul_f32_e32 v42, v52, v44
	v_mul_f32_e32 v38, v42, v38
	v_add_f32_e32 v42, 1.0, v45
	v_mul_f32_e32 v44, 0xbfb8aa3b, v51
	v_rcp_f32_e32 v42, v42
	v_exp_f32_e32 v44, v44
	v_add_f32_e32 v43, 1.0, v43
	v_rcp_f32_e32 v43, v43
	v_mul_f32_e32 v42, v53, v42
	v_add_f32_e32 v44, 1.0, v44
	v_rcp_f32_e32 v44, v44
	v_mul_f32_e32 v39, v42, v39
	v_mul_f32_e32 v42, v50, v43
	v_mul_f32_e32 v43, 0xbfb8aa3b, v56
	v_exp_f32_e32 v43, v43
	v_mul_f32_e32 v40, v42, v40
	v_mul_f32_e32 v42, v51, v44
	v_mul_f32_e32 v41, v42, v41
	v_cvt_pk_bf16_f32 v38, v38, v39
	v_cvt_pk_bf16_f32 v39, v40, v41
	v_add_f32_e32 v40, 1.0, v43
	v_rcp_f32_e32 v40, v40
	v_mul_f32_e32 v41, 0xbfb8aa3b, v57
	v_exp_f32_e32 v41, v41
	v_mov_b32_e32 v210, v242
	v_mov_b32_e32 v211, v243
	v_mov_b32_e32 v212, v38
	v_mov_b32_e32 v213, v39
	global_store_dwordx4 v[118:119], v[210:213], off
	v_mul_f32_e32 v39, 0xbfb8aa3b, v54
	v_mul_f32_e32 v38, v56, v40
	v_exp_f32_e32 v39, v39
	v_mul_f32_e32 v40, 0xbfb8aa3b, v55
	v_exp_f32_e32 v40, v40
	v_mul_f32_e32 v34, v38, v34
	v_add_f32_e32 v38, 1.0, v41
	v_rcp_f32_e32 v38, v38
	v_add_f32_e32 v39, 1.0, v39
	v_rcp_f32_e32 v39, v39
	v_add_f32_e32 v40, 1.0, v40
	v_rcp_f32_e32 v40, v40
	v_mul_f32_e32 v38, v57, v38
	v_mul_f32_e32 v35, v38, v35
	v_mul_f32_e32 v38, v54, v39
	v_mul_f32_e32 v36, v38, v36
	v_mul_f32_e32 v38, v55, v40
	v_mul_f32_e32 v37, v38, v37
	v_cvt_pk_bf16_f32 v34, v34, v35
	v_cvt_pk_bf16_f32 v35, v36, v37
	v_mov_b32_e32 v214, v244
	v_mov_b32_e32 v215, v245
	v_mov_b32_e32 v216, v34
	v_mov_b32_e32 v217, v35
	global_store_dwordx4 v[124:125], v[214:217], off
	v_pk_mul_f32 v[44:45], v[32:33], v[114:115]
	v_pk_mul_f32 v[42:43], v[30:31], v[106:107]
	v_pk_mul_f32 v[48:49], v[28:29], v[116:117]
	v_pk_mul_f32 v[46:47], v[26:27], v[108:109]
	ds_read_b128 v[34:37], v0 offset:1040
	ds_read_b128 v[30:33], v0 offset:1552
	ds_read_b128 v[26:29], v0 offset:2064
	ds_read_b128 v[38:41], v0 offset:2576
	v_mov_b32_dpp v50, v46 row_shr:1 row_mask:0xf bank_mask:0xf bound_ctrl:1
	v_mov_b32_dpp v54, v42 row_shr:1 row_mask:0xf bank_mask:0xf bound_ctrl:1
	v_mov_b32_dpp v51, v47 row_shr:1 row_mask:0xf bank_mask:0xf bound_ctrl:1
	v_mov_b32_dpp v55, v43 row_shr:1 row_mask:0xf bank_mask:0xf bound_ctrl:1
	v_mov_b32_dpp v52, v48 row_shr:1 row_mask:0xf bank_mask:0xf bound_ctrl:1
	v_mov_b32_dpp v56, v44 row_shr:1 row_mask:0xf bank_mask:0xf bound_ctrl:1
	v_mov_b32_dpp v53, v49 row_shr:1 row_mask:0xf bank_mask:0xf bound_ctrl:1
	v_mov_b32_dpp v57, v45 row_shr:1 row_mask:0xf bank_mask:0xf bound_ctrl:1
	v_cmp_gt_i32_e32 vcc, 15, v225
	s_mov_b64 s[10:11], -1
	s_and_saveexec_b64 s[8:9], vcc
	v_cmp_eq_u32_e32 vcc, 0, v225
	s_orn2_b64 s[10:11], vcc, exec
	s_or_b64 exec, exec, s[8:9]
	v_mov_b32_e32 v58, v122
	v_mov_b32_e32 v59, v122
	v_pk_mul_f32 v[64:65], v[22:23], v[122:123]
	v_mov_b32_e32 v22, v120
	v_mov_b32_e32 v23, v120
	v_pk_mul_f32 v[60:61], v[24:25], v[58:59]
	v_pk_mul_f32 v[58:59], v[20:21], v[22:23]
	v_pk_mul_f32 v[62:63], v[18:19], v[120:121]
	v_lshl_add_u64 v[82:83], v[126:127], 0, 16
	s_and_saveexec_b64 s[8:9], s[10:11]
	s_cbranch_execz .LBB0_819
	v_cndmask_b32_e64 v21, v45, v61, s[4:5]
	v_cndmask_b32_e64 v20, v44, v60, s[4:5]
	v_cndmask_b32_e64 v19, v43, v65, s[4:5]
	v_cndmask_b32_e64 v18, v42, v64, s[4:5]
	v_add_co_u32_e32 v22, vcc, 0x5000, v82
	global_store_dwordx4 v[82:83], v[18:21], off
	s_nop 0
	v_addc_co_u32_e32 v23, vcc, 0, v83, vcc
	v_cndmask_b32_e64 v21, v49, v59, s[4:5]
	v_cndmask_b32_e64 v20, v48, v58, s[4:5]
	v_cndmask_b32_e64 v19, v47, v63, s[4:5]
	v_cndmask_b32_e64 v18, v46, v62, s[4:5]
	global_store_dwordx4 v[22:23], v[18:21], off offset:2048

.LBB0_823:
	s_or_b64 exec, exec, s[8:9]
	s_waitcnt lgkmcnt(0)
	v_pk_fma_f32 v[82:83], v[20:21], v[90:91], v[24:25]
	v_pk_fma_f32 v[88:89], v[18:19], v[88:89], v[22:23]
	v_pk_fma_f32 v[82:83], v[16:17], v[86:87], v[82:83]
	v_pk_fma_f32 v[86:87], v[20:21], v[86:87], v[24:25]
	v_pk_fma_f32 v[82:83], v[8:9], v[12:13], v[82:83]
	v_pk_fma_f32 v[86:87], v[8:9], v[16:17], v[86:87]
	v_pk_fma_f32 v[8:9], v[8:9], v[20:21], v[24:25]
	v_pk_fma_f32 v[86:87], v[4:5], v[12:13], v[86:87]
	v_pk_fma_f32 v[8:9], v[4:5], v[16:17], v[8:9]
	v_pk_fma_f32 v[4:5], v[4:5], v[20:21], v[24:25]
	v_pk_fma_f32 v[8:9], v[68:69], v[12:13], v[8:9]
	v_pk_fma_f32 v[4:5], v[68:69], v[16:17], v[4:5]
	v_pk_fma_f32 v[88:89], v[14:15], v[84:85], v[88:89]
	v_pk_fma_f32 v[4:5], v[72:73], v[12:13], v[4:5]
	v_pk_fma_f32 v[12:13], v[34:35], v[54:55], v[38:39]
	v_pk_fma_f32 v[84:85], v[18:19], v[84:85], v[22:23]
	v_pk_fma_f32 v[12:13], v[30:31], v[50:51], v[12:13]
	v_pk_fma_f32 v[88:89], v[6:7], v[10:11], v[88:89]
	v_pk_fma_f32 v[12:13], v[64:65], v[26:27], v[12:13]
	v_pk_fma_f32 v[84:85], v[6:7], v[14:15], v[84:85]
	v_pk_fma_f32 v[6:7], v[6:7], v[18:19], v[22:23]
	v_mul_f32_e32 v0, 0xbfb8aa3b, v12
	v_pk_fma_f32 v[84:85], v[2:3], v[10:11], v[84:85]
	v_pk_fma_f32 v[6:7], v[2:3], v[14:15], v[6:7]
	v_pk_fma_f32 v[2:3], v[2:3], v[18:19], v[22:23]
	v_exp_f32_e32 v0, v0
	v_pk_fma_f32 v[2:3], v[66:67], v[14:15], v[2:3]
	v_pk_fma_f32 v[6:7], v[66:67], v[10:11], v[6:7]
	v_pk_fma_f32 v[2:3], v[70:71], v[10:11], v[2:3]
	v_pk_fma_f32 v[10:11], v[36:37], v[56:57], v[40:41]
	v_pk_fma_f32 v[14:15], v[36:37], v[52:53], v[40:41]
	v_pk_fma_f32 v[18:19], v[60:61], v[36:37], v[40:41]
	v_pk_fma_f32 v[22:23], v[58:59], v[36:37], v[40:41]
	v_pk_fma_f32 v[10:11], v[32:33], v[52:53], v[10:11]
	v_pk_fma_f32 v[14:15], v[60:61], v[32:33], v[14:15]
	v_pk_fma_f32 v[18:19], v[58:59], v[32:33], v[18:19]
	v_pk_fma_f32 v[22:23], v[44:45], v[32:33], v[22:23]
	v_pk_fma_f32 v[10:11], v[60:61], v[28:29], v[10:11]
	v_pk_fma_f32 v[14:15], v[58:59], v[28:29], v[14:15]
	v_pk_fma_f32 v[18:19], v[44:45], v[28:29], v[18:19]
	v_pk_fma_f32 v[22:23], v[48:49], v[28:29], v[22:23]
	v_add_f32_e32 v0, 1.0, v0
	v_mul_f32_e32 v28, 0xbfb8aa3b, v13
	v_rcp_f32_e32 v0, v0
	v_exp_f32_e32 v28, v28
	v_pk_fma_f32 v[16:17], v[34:35], v[50:51], v[38:39]
	v_pk_fma_f32 v[20:21], v[64:65], v[34:35], v[38:39]
	v_pk_fma_f32 v[24:25], v[62:63], v[34:35], v[38:39]
	v_pk_fma_f32 v[16:17], v[64:65], v[30:31], v[16:17]
	v_pk_fma_f32 v[20:21], v[62:63], v[30:31], v[20:21]
	v_pk_fma_f32 v[24:25], v[42:43], v[30:31], v[24:25]
	v_pk_fma_f32 v[16:17], v[62:63], v[26:27], v[16:17]
	v_pk_fma_f32 v[20:21], v[42:43], v[26:27], v[20:21]
	v_pk_fma_f32 v[24:25], v[46:47], v[26:27], v[24:25]
	v_mul_f32_e32 v0, v12, v0
	v_add_f32_e32 v12, 1.0, v28
	v_mul_f32_e32 v26, 0xbfb8aa3b, v10
	v_rcp_f32_e32 v12, v12
	v_exp_f32_e32 v26, v26
	v_mul_f32_e32 v27, 0xbfb8aa3b, v11
	v_exp_f32_e32 v27, v27
	v_mul_f32_e32 v12, v13, v12
	v_add_f32_e32 v13, 1.0, v26
	v_rcp_f32_e32 v13, v13
	v_add_f32_e32 v26, 1.0, v27
	v_rcp_f32_e32 v26, v26
	v_mul_f32_e32 v12, v12, v89
	v_mul_f32_e32 v10, v10, v13
	v_mul_f32_e32 v13, v10, v82
	v_mul_f32_e32 v10, v11, v26
	v_mul_f32_e32 v11, 0xbfb8aa3b, v16
	v_mul_f32_e32 v0, v0, v88
	v_exp_f32_e32 v26, v11
	v_mul_f32_e32 v11, v10, v83
	v_cvt_pk_bf16_f32 v10, v0, v12
	v_mul_f32_e32 v12, 0xbfb8aa3b, v17
	v_exp_f32_e32 v12, v12
	v_cvt_pk_bf16_f32 v11, v13, v11
	v_mov_b32_e32 v210, v246
	v_mov_b32_e32 v211, v247
	v_mov_b32_e32 v212, v10
	v_mov_b32_e32 v213, v11
	global_store_dwordx4 v[74:75], v[210:213], off
	v_mul_f32_e32 v11, 0xbfb8aa3b, v14
	v_add_f32_e32 v10, 1.0, v12
	v_mul_f32_e32 v12, 0xbfb8aa3b, v15
	v_exp_f32_e32 v11, v11
	v_exp_f32_e32 v12, v12
	v_add_f32_e32 v0, 1.0, v26
	v_rcp_f32_e32 v0, v0
	v_rcp_f32_e32 v10, v10
	v_add_f32_e32 v11, 1.0, v11
	v_add_f32_e32 v12, 1.0, v12
	v_rcp_f32_e32 v11, v11
	v_rcp_f32_e32 v12, v12
	v_mul_f32_e32 v13, 0xbfb8aa3b, v20
	v_exp_f32_e32 v13, v13
	v_mul_f32_e32 v0, v16, v0
	v_mul_f32_e32 v10, v17, v10
	v_mul_f32_e32 v0, v0, v84
	v_mul_f32_e32 v10, v10, v85
	v_mul_f32_e32 v11, v14, v11
	v_mul_f32_e32 v12, v15, v12
	v_mul_f32_e32 v11, v11, v86
	v_mul_f32_e32 v12, v12, v87
	v_cvt_pk_bf16_f32 v10, v0, v10
	v_add_f32_e32 v0, 1.0, v13
	v_cvt_pk_bf16_f32 v11, v11, v12
	v_rcp_f32_e32 v0, v0
	v_mul_f32_e32 v12, 0xbfb8aa3b, v21
	v_exp_f32_e32 v12, v12
	v_mov_b32_e32 v214, v248
	v_mov_b32_e32 v215, v249
	v_mov_b32_e32 v216, v10
	v_mov_b32_e32 v217, v11
	global_store_dwordx4 v[76:77], v[214:217], off
	v_mul_f32_e32 v10, 0xbfb8aa3b, v18
	v_exp_f32_e32 v10, v10
	v_mul_f32_e32 v0, v20, v0
	v_mul_f32_e32 v0, v0, v6
	v_add_f32_e32 v6, 1.0, v12
	v_mul_f32_e32 v11, 0xbfb8aa3b, v19
	v_rcp_f32_e32 v6, v6
	v_exp_f32_e32 v11, v11
	v_add_f32_e32 v10, 1.0, v10
	v_rcp_f32_e32 v10, v10
	v_mul_f32_e32 v6, v21, v6
	v_add_f32_e32 v11, 1.0, v11
	v_rcp_f32_e32 v11, v11
	v_mul_f32_e32 v6, v6, v7
	v_mul_f32_e32 v7, v18, v10
	v_mul_f32_e32 v10, 0xbfb8aa3b, v24
	v_exp_f32_e32 v10, v10
	v_mul_f32_e32 v7, v7, v8
	v_mul_f32_e32 v8, v19, v11
	v_mul_f32_e32 v8, v8, v9
	v_cvt_pk_bf16_f32 v6, v0, v6
	v_add_f32_e32 v0, 1.0, v10
	v_cvt_pk_bf16_f32 v7, v7, v8
	v_rcp_f32_e32 v0, v0
	v_mul_f32_e32 v8, 0xbfb8aa3b, v25
	v_exp_f32_e32 v8, v8
	v_mov_b32_e32 v210, v250
	v_mov_b32_e32 v211, v251
	v_mov_b32_e32 v212, v6
	v_mov_b32_e32 v213, v7
	global_store_dwordx4 v[78:79], v[210:213], off
	v_mul_f32_e32 v6, 0xbfb8aa3b, v22
	v_exp_f32_e32 v6, v6
	v_mul_f32_e32 v7, 0xbfb8aa3b, v23
	v_exp_f32_e32 v7, v7
	v_mul_f32_e32 v0, v24, v0
	v_mul_f32_e32 v0, v0, v2
	v_add_f32_e32 v2, 1.0, v8
	v_rcp_f32_e32 v2, v2
	v_add_f32_e32 v6, 1.0, v6
	v_rcp_f32_e32 v6, v6
	v_add_f32_e32 v7, 1.0, v7
	v_rcp_f32_e32 v7, v7
	v_mul_f32_e32 v2, v25, v2
	v_mul_f32_e32 v2, v2, v3
	v_mul_f32_e32 v3, v22, v6
	v_mul_f32_e32 v3, v3, v4
	v_mul_f32_e32 v4, v23, v7
	v_mul_f32_e32 v4, v4, v5
	v_cvt_pk_bf16_f32 v2, v0, v2
	v_cvt_pk_bf16_f32 v3, v3, v4
	v_mov_b32_e32 v214, v236
	v_mov_b32_e32 v215, v237
	v_mov_b32_e32 v216, v2
	v_mov_b32_e32 v217, v3
	global_store_dwordx4 v[80:81], v[214:217], off
	s_waitcnt vmcnt(8)
	s_mov_b32 s98, 1
	s_andn2_b64 vcc, exec, s[6:7]
	s_mov_b64 s[6:7], -1
	s_cbranch_vccnz .LBB0_778
	s_andn2_b64 vcc, exec, s[12:13]
	s_cbranch_vccnz .LBB0_777
	s_barrier
	s_branch .LBB0_777

.LBB0_949:
	s_mov_b32 s98, 0
	s_or_b64 exec, exec, s[2:3]
	v_readlane_b32 s4, v253, 10
	s_mov_b64 s[2:3], s[84:85]
	v_mov_b32_e32 v0, v165
	v_mov_b32_e32 v18, v165
	v_readlane_b32 s5, v253, 11
	s_waitcnt lgkmcnt(0)
	s_barrier
	s_and_b64 vcc, exec, s[4:5]
	v_readfirstlane_b32 s6, v18
	s_cbranch_vccz .LBB0_989
	v_lshlrev_b32_e32 v0, 4, v18
	v_add_u32_e32 v2, 0x2000, v0
	v_ashrrev_i32_e32 v3, 31, v2
	v_lshrrev_b32_e32 v3, 22, v3
	v_add_u32_e32 v3, v2, v3
	s_load_dwordx2 s[4:5], s[2:3], 0x90
	v_ashrrev_i32_e32 v10, 10, v3
	v_mul_i32_i24_e32 v3, 0x400, v10
	v_sub_u32_e32 v2, v2, v3
	v_lshrrev_b32_e32 v3, 4, v2
	v_bitop3_b32 v2, v3, v2, 32 bitop3:0x6c
	v_readlane_b32 s2, v254, 28
	s_waitcnt lgkmcnt(0)
	s_add_u32 s26, s4, 0xb100000
	v_ashrrev_i32_e32 v3, 31, v2
	s_mul_i32 s2, s2, 0x580000
	s_addc_u32 s27, s5, 0
	v_lshrrev_b32_e32 v3, 26, v3
	s_add_u32 s2, s4, s2
	v_add_u32_e32 v3, v2, v3
	v_lshlrev_b32_e32 v4, 3, v10
	s_addc_u32 s3, s5, 0
	v_ashrrev_i32_e32 v11, 6, v3
	v_and_b32_e32 v4, -16, v4
	s_add_u32 s28, s2, 0x2700000
	v_add_u32_e32 v4, v11, v4
	s_addc_u32 s29, s3, 0
	v_and_b32_e32 v5, 3, v11
	s_mov_b32 s3, 0xffffe0
	v_lshrrev_b32_e32 v6, 2, v4
	v_lshlrev_b32_e32 v7, 1, v4
	v_and_or_b32 v5, v4, s3, v5
	v_and_b32_e32 v6, 4, v6
	v_and_b32_e32 v7, 24, v7
	v_or3_b32 v5, v5, v6, v7
	v_lshlrev_b32_e32 v6, 5, v10
	v_and_b32_e32 v3, 0xc0, v3
	v_and_b32_e32 v12, 32, v6
	v_sub_u32_e32 v2, v2, v3
	v_mov_b32_e32 v6, 1
	v_ashrrev_i16_sdwa v2, v6, sext(v2) dst_sel:DWORD dst_unused:UNUSED_PAD src0_sel:DWORD src1_sel:BYTE_0
	v_bfe_i32 v13, v2, 0, 16
	s_movk_i32 s2, 0xb00
	v_mul_u32_u24_e32 v5, 0xb00, v5
	v_add_u32_e32 v2, v12, v13
	v_mul_lo_u32 v3, v4, s2
	v_add_lshl_u32 v154, v5, v2, 1
	v_add_lshl_u32 v156, v2, v3, 1
	v_bfe_i32 v2, v18, 27, 1
	v_lshrrev_b32_e32 v2, 22, v2
	v_add_u32_e32 v2, v0, v2
	v_and_b32_e32 v2, 0xfffffc00, v2
	v_sub_u32_e32 v0, v0, v2
	v_lshrrev_b32_e32 v2, 4, v0
	v_bitop3_b32 v2, v2, v0, 32 bitop3:0x6c
	v_ashrrev_i32_e32 v0, 31, v0
	v_lshrrev_b32_e32 v0, 26, v0
	v_add_u32_e32 v0, v2, v0
	v_ashrrev_i32_e32 v14, 6, v0
	v_ashrrev_i32_e32 v0, 31, v18
	v_lshrrev_b32_e32 v0, 26, v0
	v_add_u32_e32 v0, v18, v0
	v_ashrrev_i32_e32 v15, 6, v0
	v_lshlrev_b32_e32 v0, 3, v15
	v_and_b32_e32 v0, -16, v0
	v_add_u32_e32 v3, v14, v0
	v_and_b32_e32 v0, 3, v14
	v_lshrrev_b32_e32 v4, 2, v3
	v_lshlrev_b32_e32 v5, 1, v3
	v_and_or_b32 v0, v3, s3, v0
	v_and_b32_e32 v4, 4, v4
	v_and_b32_e32 v5, 24, v5
	v_or3_b32 v0, v0, v4, v5
	v_lshlrev_b32_e32 v4, 5, v15
	v_and_b32_e32 v16, 32, v4
	v_mul_i32_i24_e32 v4, 64, v14
	s_ashr_i32 s7, s6, 6
	v_sub_u32_e32 v2, v2, v4
	v_readlane_b32 s3, v253, 20
	s_ashr_i32 s8, s6, 8
	s_lshl_b32 s30, s7, 10
	v_ashrrev_i16_sdwa v2, v6, sext(v2) dst_sel:DWORD dst_unused:UNUSED_PAD src0_sel:DWORD src1_sel:BYTE_0
	v_mul_lo_u32 v3, v3, s2
	s_mul_i32 s2, s3, 0x160000
	v_bfe_i32 v17, v2, 0, 16
	s_add_u32 s20, s28, s2
	s_mul_hi_i32 s2, s3, 0x160000
	v_mul_u32_u24_e32 v0, 0xb00, v0
	v_add_u32_e32 v2, v16, v17
	s_addc_u32 s21, s29, s2
	s_add_i32 s31, s30, 0
	v_add_lshl_u32 v0, v0, v2, 1
	s_add_i32 m0, s31, 0x10000
	v_add_lshl_u32 v166, v2, v3, 1
	global_load_lds_dwordx4 v0, s[20:21]
	s_add_i32 m0, s31, 0x12000
	s_add_u32 s2, s20, 0xb0000
	global_load_lds_dwordx4 v154, s[20:21]
	s_addc_u32 s3, s21, 0
	s_add_i32 m0, s31, 0x14000
	v_mov_b32_e32 v155, v1
	global_load_lds_dwordx4 v0, s[2:3]
	s_add_i32 m0, s31, 0x16000
	v_mov_b32_e32 v167, v1
	global_load_lds_dwordx4 v154, s[2:3]
	v_readlane_b32 s2, v253, 37
	s_mov_b32 s10, s2
	s_mul_i32 s2, s2, 0x160000
	s_add_u32 s18, s26, s2
	s_mul_hi_i32 s2, s10, 0x160000
	s_addc_u32 s19, s27, s2
	s_add_i32 s33, s31, 0x2000
	v_readlane_b32 s3, v253, 38
	s_mov_b32 m0, s31
	s_add_u32 s2, s18, 0xb0000
	global_load_lds_dwordx4 v166, s[18:19]
	s_mov_b32 m0, s33
	s_addc_u32 s3, s19, 0
	s_add_i32 s34, s31, 0x4000
	global_load_lds_dwordx4 v156, s[18:19]
	s_mov_b32 m0, s34
	s_add_i32 s35, s31, 0x6000
	global_load_lds_dwordx4 v166, s[2:3]
	s_mov_b32 m0, s35
	v_mov_b32_e32 v157, v1
	global_load_lds_dwordx4 v156, s[2:3]
	s_cmp_eq_u32 s8, 1
	v_mov_b32_e32 v252, 1
	v_lshl_add_u64 v[8:9], s[20:21], 0, v[0:1]
	v_lshl_add_u64 v[6:7], s[20:21], 0, v[154:155]
	v_lshl_add_u64 v[2:3], s[18:19], 0, v[166:167]
	s_cselect_b64 s[2:3], -1, 0
	s_cmp_lg_u32 s8, 1
	v_lshl_add_u64 v[4:5], s[18:19], 0, v[156:157]
	s_cbranch_scc1 .LBB0_952
	s_barrier

.LBB0_966:
	s_add_u32 s20, s18, 0x100
	s_addc_u32 s21, s19, 0
	s_add_i32 s46, 0, 0x10000
	s_cmp_eq_u32 s45, 40
	s_cselect_b32 s25, s9, s21
	s_cselect_b32 s24, s8, s20
	s_cselect_b32 s23, s17, s44
	s_cselect_b32 s22, s16, s43
	s_add_i32 s47, 0, 0x14000
	v_add_u32_e32 v134, s46, v191
	v_add_u32_e32 v158, s47, v191
	ds_read_b128 v[114:117], v134
	ds_read_b128 v[118:121], v134 offset:1024
	ds_read_b128 v[122:125], v134 offset:2048
	ds_read_b128 v[134:137], v134 offset:3072
	ds_read_b128 v[146:149], v158
	ds_read_b128 v[150:153], v158 offset:1024
	ds_read_b128 v[172:175], v158 offset:2048
	ds_read_b128 v[176:179], v158 offset:3072
	v_lshl_add_u64 v[158:159], s[18:19], 0, v[168:169]
	s_add_i32 m0, s31, 0xc000
	ds_read_b128 v[180:183], v193
	ds_read_b128 v[184:187], v193 offset:1024
	ds_read_b128 v[194:197], v193 offset:2048
	ds_read_b128 v[198:201], v193 offset:3072
	ds_read_b128 v[202:205], v193 offset:4096
	ds_read_b128 v[206:209], v193 offset:5120
	ds_read_b128 v[210:213], v193 offset:6144
	ds_read_b128 v[214:217], v193 offset:7168
	global_load_lds_dwordx4 v[158:159], off
	v_lshl_add_u64 v[158:159], s[18:19], 0, v[170:171]
	s_add_i32 m0, s31, 0xe000
	s_nop 0
	global_load_lds_dwordx4 v[158:159], off
	s_cmp_lg_u32 s98, 0
	s_cbranch_scc1 .Lrx_d_1
	s_waitcnt vmcnt(8)
.Lrx_d_1:
	s_waitcnt lgkmcnt(0)
	s_barrier
	s_setprio 1
	s_waitcnt lgkmcnt(0)
	v_mfma_f32_16x16x32_bf16 v[142:145], v[114:117], v[180:183], v[142:145]
	v_mfma_f32_16x16x32_bf16 v[138:141], v[122:125], v[180:183], v[138:141]
	v_mfma_f32_16x16x32_bf16 v[110:113], v[114:117], v[194:197], v[110:113]
	v_mfma_f32_16x16x32_bf16 v[106:109], v[122:125], v[194:197], v[106:109]
	v_mfma_f32_16x16x32_bf16 v[94:97], v[114:117], v[202:205], v[94:97]
	v_mfma_f32_16x16x32_bf16 v[90:93], v[122:125], v[202:205], v[90:93]
	v_mfma_f32_16x16x32_bf16 v[78:81], v[114:117], v[210:213], v[78:81]
	v_mfma_f32_16x16x32_bf16 v[74:77], v[122:125], v[210:213], v[74:77]
	v_mfma_f32_16x16x32_bf16 v[142:145], v[118:121], v[184:187], v[142:145]
	v_mfma_f32_16x16x32_bf16 v[138:141], v[134:137], v[184:187], v[138:141]
	v_mfma_f32_16x16x32_bf16 v[110:113], v[118:121], v[198:201], v[110:113]
	v_mfma_f32_16x16x32_bf16 v[106:109], v[134:137], v[198:201], v[106:109]
	v_mfma_f32_16x16x32_bf16 v[94:97], v[118:121], v[206:209], v[94:97]
	v_mfma_f32_16x16x32_bf16 v[90:93], v[134:137], v[206:209], v[90:93]
	v_mfma_f32_16x16x32_bf16 v[78:81], v[118:121], v[214:217], v[78:81]
	v_mfma_f32_16x16x32_bf16 v[74:77], v[134:137], v[214:217], v[74:77]
	s_setprio 0
	s_setprio 1
	v_mfma_f32_16x16x32_bf16 v[130:133], v[146:149], v[180:183], v[130:133]
	v_mfma_f32_16x16x32_bf16 v[126:129], v[172:175], v[180:183], v[126:129]
	v_mfma_f32_16x16x32_bf16 v[102:105], v[146:149], v[194:197], v[102:105]
	v_mfma_f32_16x16x32_bf16 v[98:101], v[172:175], v[194:197], v[98:101]
	v_mfma_f32_16x16x32_bf16 v[86:89], v[146:149], v[202:205], v[86:89]
	v_mfma_f32_16x16x32_bf16 v[82:85], v[172:175], v[202:205], v[82:85]
	v_mfma_f32_16x16x32_bf16 v[70:73], v[146:149], v[210:213], v[70:73]
	v_mfma_f32_16x16x32_bf16 v[66:69], v[172:175], v[210:213], v[66:69]
	v_mfma_f32_16x16x32_bf16 v[130:133], v[150:153], v[184:187], v[130:133]
	v_mfma_f32_16x16x32_bf16 v[126:129], v[176:179], v[184:187], v[126:129]
	v_mfma_f32_16x16x32_bf16 v[102:105], v[150:153], v[198:201], v[102:105]
	v_mfma_f32_16x16x32_bf16 v[98:101], v[176:179], v[198:201], v[98:101]
	v_mfma_f32_16x16x32_bf16 v[86:89], v[150:153], v[206:209], v[86:89]
	v_mfma_f32_16x16x32_bf16 v[82:85], v[176:179], v[206:209], v[82:85]
	v_mfma_f32_16x16x32_bf16 v[70:73], v[150:153], v[214:217], v[70:73]
	v_mfma_f32_16x16x32_bf16 v[66:69], v[176:179], v[214:217], v[66:69]
	s_setprio 0
	s_barrier
	s_add_i32 s18, s46, s30
	v_lshl_add_u64 v[158:159], s[22:23], 0, v[0:1]
	s_mov_b32 m0, s18
	ds_read_b128 v[180:183], v193 offset:16384
	ds_read_b128 v[184:187], v193 offset:17408
	ds_read_b128 v[194:197], v193 offset:18432
	ds_read_b128 v[198:201], v193 offset:19456
	ds_read_b128 v[202:205], v193 offset:20480
	ds_read_b128 v[206:209], v193 offset:21504
	ds_read_b128 v[210:213], v193 offset:22528
	ds_read_b128 v[214:217], v193 offset:23552
	global_load_lds_dwordx4 v[158:159], off
	s_add_i32 m0, s18, 0x2000
	s_add_u32 s18, s22, 0xb0000
	v_lshl_add_u64 v[162:163], s[22:23], 0, v[154:155]
	s_addc_u32 s19, s23, 0
	s_add_i32 s46, s47, s30
	global_load_lds_dwordx4 v[162:163], off
	v_lshl_add_u64 v[188:189], s[18:19], 0, v[0:1]
	s_mov_b32 m0, s46
	v_lshl_add_u64 v[218:219], s[24:25], 0, v[156:157]
	global_load_lds_dwordx4 v[188:189], off
	v_lshl_add_u64 v[188:189], s[18:19], 0, v[154:155]
	s_add_i32 m0, s46, 0x2000
	s_nop 0
	global_load_lds_dwordx4 v[188:189], off
	v_lshl_add_u64 v[188:189], s[24:25], 0, v[166:167]
	s_mov_b32 m0, s31
	s_nop 0
	global_load_lds_dwordx4 v[188:189], off
	s_mov_b32 m0, s33
	s_nop 0
	global_load_lds_dwordx4 v[218:219], off
	s_cmp_lg_u32 s98, 0
	s_cbranch_scc1 .Lrx_d_2
	s_waitcnt vmcnt(8)
.Lrx_d_2:
	s_mov_b32 s98, 0
	s_waitcnt lgkmcnt(0)
	s_barrier
	s_setprio 1
	s_waitcnt lgkmcnt(0)
	v_mfma_f32_16x16x32_bf16 v[62:65], v[114:117], v[180:183], v[62:65]
	v_mfma_f32_16x16x32_bf16 v[58:61], v[122:125], v[180:183], v[58:61]
	v_mfma_f32_16x16x32_bf16 v[46:49], v[114:117], v[194:197], v[46:49]
	v_mfma_f32_16x16x32_bf16 v[42:45], v[122:125], v[194:197], v[42:45]
	v_mfma_f32_16x16x32_bf16 v[30:33], v[114:117], v[202:205], v[30:33]
	v_mfma_f32_16x16x32_bf16 v[26:29], v[122:125], v[202:205], v[26:29]
	v_mfma_f32_16x16x32_bf16 v[14:17], v[114:117], v[210:213], v[14:17]
	v_mfma_f32_16x16x32_bf16 v[10:13], v[122:125], v[210:213], v[10:13]
	v_mfma_f32_16x16x32_bf16 v[62:65], v[118:121], v[184:187], v[62:65]
	v_mfma_f32_16x16x32_bf16 v[58:61], v[134:137], v[184:187], v[58:61]
	v_mfma_f32_16x16x32_bf16 v[46:49], v[118:121], v[198:201], v[46:49]
	v_mfma_f32_16x16x32_bf16 v[42:45], v[134:137], v[198:201], v[42:45]
	v_mfma_f32_16x16x32_bf16 v[30:33], v[118:121], v[206:209], v[30:33]
	v_mfma_f32_16x16x32_bf16 v[26:29], v[134:137], v[206:209], v[26:29]
	v_mfma_f32_16x16x32_bf16 v[14:17], v[118:121], v[214:217], v[14:17]
	v_mfma_f32_16x16x32_bf16 v[10:13], v[134:137], v[214:217], v[10:13]
	s_setprio 0
	s_setprio 1
	v_mfma_f32_16x16x32_bf16 v[54:57], v[146:149], v[180:183], v[54:57]
	v_mfma_f32_16x16x32_bf16 v[50:53], v[172:175], v[180:183], v[50:53]
	v_mfma_f32_16x16x32_bf16 v[38:41], v[146:149], v[194:197], v[38:41]
	v_mfma_f32_16x16x32_bf16 v[34:37], v[172:175], v[194:197], v[34:37]
	v_mfma_f32_16x16x32_bf16 v[22:25], v[146:149], v[202:205], v[22:25]
	v_mfma_f32_16x16x32_bf16 v[18:21], v[172:175], v[202:205], v[18:21]
	v_mfma_f32_16x16x32_bf16 v[6:9], v[146:149], v[210:213], v[6:9]
	v_mfma_f32_16x16x32_bf16 v[2:5], v[172:175], v[210:213], v[2:5]
	v_mfma_f32_16x16x32_bf16 v[54:57], v[150:153], v[184:187], v[54:57]
	v_mfma_f32_16x16x32_bf16 v[50:53], v[176:179], v[184:187], v[50:53]
	v_mfma_f32_16x16x32_bf16 v[38:41], v[150:153], v[198:201], v[38:41]
	v_mfma_f32_16x16x32_bf16 v[34:37], v[176:179], v[198:201], v[34:37]
	v_mfma_f32_16x16x32_bf16 v[22:25], v[150:153], v[206:209], v[22:25]
	v_mfma_f32_16x16x32_bf16 v[18:21], v[176:179], v[206:209], v[18:21]
	v_mfma_f32_16x16x32_bf16 v[6:9], v[150:153], v[214:217], v[6:9]
	v_mfma_f32_16x16x32_bf16 v[2:5], v[176:179], v[214:217], v[2:5]
	s_setprio 0
	s_barrier
	s_add_i32 s46, 0, 0x18000
	s_add_i32 s47, 0, 0x1c000
	v_add_u32_e32 v134, s46, v191
	v_add_u32_e32 v176, s47, v191
	ds_read_b128 v[114:117], v134
	ds_read_b128 v[118:121], v134 offset:1024
	ds_read_b128 v[122:125], v134 offset:2048
	ds_read_b128 v[134:137], v134 offset:3072
	ds_read_b128 v[146:149], v176
	ds_read_b128 v[150:153], v176 offset:1024
	ds_read_b128 v[172:175], v176 offset:2048
	ds_read_b128 v[176:179], v176 offset:3072
	s_add_u32 s18, s24, 0xb0000
	s_addc_u32 s19, s25, 0
	s_mov_b32 m0, s34
	v_lshl_add_u64 v[220:221], s[18:19], 0, v[166:167]
	ds_read_b128 v[180:183], v193 offset:32768
	ds_read_b128 v[184:187], v193 offset:33792
	ds_read_b128 v[194:197], v193 offset:34816
	ds_read_b128 v[198:201], v193 offset:35840
	ds_read_b128 v[202:205], v193 offset:36864
	ds_read_b128 v[206:209], v193 offset:37888
	ds_read_b128 v[210:213], v193 offset:38912
	ds_read_b128 v[214:217], v193 offset:39936
	global_load_lds_dwordx4 v[220:221], off
	v_lshl_add_u64 v[220:221], s[18:19], 0, v[156:157]
	s_mov_b32 m0, s35
	s_nop 0
	global_load_lds_dwordx4 v[220:221], off
	s_waitcnt vmcnt(8)
	s_waitcnt lgkmcnt(0)
	s_barrier
	s_setprio 1
	s_waitcnt lgkmcnt(0)
	v_mfma_f32_16x16x32_bf16 v[142:145], v[114:117], v[180:183], v[142:145]
	v_mfma_f32_16x16x32_bf16 v[138:141], v[122:125], v[180:183], v[138:141]
	v_mfma_f32_16x16x32_bf16 v[110:113], v[114:117], v[194:197], v[110:113]
	v_mfma_f32_16x16x32_bf16 v[106:109], v[122:125], v[194:197], v[106:109]
	v_mfma_f32_16x16x32_bf16 v[94:97], v[114:117], v[202:205], v[94:97]
	v_mfma_f32_16x16x32_bf16 v[90:93], v[122:125], v[202:205], v[90:93]
	v_mfma_f32_16x16x32_bf16 v[78:81], v[114:117], v[210:213], v[78:81]
	v_mfma_f32_16x16x32_bf16 v[74:77], v[122:125], v[210:213], v[74:77]
	v_mfma_f32_16x16x32_bf16 v[142:145], v[118:121], v[184:187], v[142:145]
	v_mfma_f32_16x16x32_bf16 v[138:141], v[134:137], v[184:187], v[138:141]
	v_mfma_f32_16x16x32_bf16 v[110:113], v[118:121], v[198:201], v[110:113]
	v_mfma_f32_16x16x32_bf16 v[106:109], v[134:137], v[198:201], v[106:109]
	v_mfma_f32_16x16x32_bf16 v[94:97], v[118:121], v[206:209], v[94:97]
	v_mfma_f32_16x16x32_bf16 v[90:93], v[134:137], v[206:209], v[90:93]
	v_mfma_f32_16x16x32_bf16 v[78:81], v[118:121], v[214:217], v[78:81]
	v_mfma_f32_16x16x32_bf16 v[74:77], v[134:137], v[214:217], v[74:77]
	s_setprio 0
	s_setprio 1
	v_mfma_f32_16x16x32_bf16 v[130:133], v[146:149], v[180:183], v[130:133]
	v_mfma_f32_16x16x32_bf16 v[126:129], v[172:175], v[180:183], v[126:129]
	v_mfma_f32_16x16x32_bf16 v[102:105], v[146:149], v[194:197], v[102:105]
	v_mfma_f32_16x16x32_bf16 v[98:101], v[172:175], v[194:197], v[98:101]
	v_mfma_f32_16x16x32_bf16 v[86:89], v[146:149], v[202:205], v[86:89]
	v_mfma_f32_16x16x32_bf16 v[82:85], v[172:175], v[202:205], v[82:85]
	v_mfma_f32_16x16x32_bf16 v[70:73], v[146:149], v[210:213], v[70:73]
	v_mfma_f32_16x16x32_bf16 v[66:69], v[172:175], v[210:213], v[66:69]
	v_mfma_f32_16x16x32_bf16 v[130:133], v[150:153], v[184:187], v[130:133]
	v_mfma_f32_16x16x32_bf16 v[126:129], v[176:179], v[184:187], v[126:129]
	v_mfma_f32_16x16x32_bf16 v[102:105], v[150:153], v[198:201], v[102:105]
	v_mfma_f32_16x16x32_bf16 v[98:101], v[176:179], v[198:201], v[98:101]
	v_mfma_f32_16x16x32_bf16 v[86:89], v[150:153], v[206:209], v[86:89]
	v_mfma_f32_16x16x32_bf16 v[82:85], v[176:179], v[206:209], v[82:85]
	v_mfma_f32_16x16x32_bf16 v[70:73], v[150:153], v[214:217], v[70:73]
	v_mfma_f32_16x16x32_bf16 v[66:69], v[176:179], v[214:217], v[66:69]
	s_setprio 0
	s_barrier
	s_add_i32 s18, s46, s30
	v_lshl_add_u64 v[158:159], v[158:159], 0, s[82:83]
	s_mov_b32 m0, s18
	ds_read_b128 v[180:183], v193 offset:49152
	ds_read_b128 v[184:187], v193 offset:50176
	ds_read_b128 v[194:197], v193 offset:51200
	ds_read_b128 v[198:201], v193 offset:52224
	ds_read_b128 v[202:205], v193 offset:53248
	ds_read_b128 v[206:209], v193 offset:54272
	ds_read_b128 v[210:213], v193 offset:55296
	ds_read_b128 v[214:217], v193 offset:56320
	global_load_lds_dwordx4 v[158:159], off
	s_add_i32 m0, s18, 0x2000
	s_add_u32 s18, s22, 0xb0080
	v_lshl_add_u64 v[158:159], v[162:163], 0, s[82:83]
	s_addc_u32 s19, s23, 0
	s_add_i32 s22, s47, s30
	global_load_lds_dwordx4 v[158:159], off
	v_lshl_add_u64 v[158:159], s[18:19], 0, v[0:1]
	s_mov_b32 m0, s22
	s_nop 0
	global_load_lds_dwordx4 v[158:159], off
	v_lshl_add_u64 v[158:159], s[18:19], 0, v[154:155]
	s_add_i32 m0, s22, 0x2000
	s_nop 0
	global_load_lds_dwordx4 v[158:159], off
	v_lshl_add_u64 v[158:159], v[188:189], 0, s[82:83]
	s_mov_b32 m0, s36
	s_nop 0
	global_load_lds_dwordx4 v[158:159], off
	v_lshl_add_u64 v[158:159], v[218:219], 0, s[82:83]
	s_mov_b32 m0, s37
	s_nop 0
	global_load_lds_dwordx4 v[158:159], off
	s_waitcnt vmcnt(8)
	s_waitcnt lgkmcnt(0)
	s_barrier
	s_setprio 1
	s_waitcnt lgkmcnt(0)
	v_mfma_f32_16x16x32_bf16 v[62:65], v[114:117], v[180:183], v[62:65]
	v_mfma_f32_16x16x32_bf16 v[58:61], v[122:125], v[180:183], v[58:61]
	v_mfma_f32_16x16x32_bf16 v[46:49], v[114:117], v[194:197], v[46:49]
	v_mfma_f32_16x16x32_bf16 v[42:45], v[122:125], v[194:197], v[42:45]
	v_mfma_f32_16x16x32_bf16 v[30:33], v[114:117], v[202:205], v[30:33]
	v_mfma_f32_16x16x32_bf16 v[26:29], v[122:125], v[202:205], v[26:29]
	v_mfma_f32_16x16x32_bf16 v[14:17], v[114:117], v[210:213], v[14:17]
	v_mfma_f32_16x16x32_bf16 v[10:13], v[122:125], v[210:213], v[10:13]
	v_mfma_f32_16x16x32_bf16 v[62:65], v[118:121], v[184:187], v[62:65]
	v_mfma_f32_16x16x32_bf16 v[58:61], v[134:137], v[184:187], v[58:61]
	v_mfma_f32_16x16x32_bf16 v[46:49], v[118:121], v[198:201], v[46:49]
	v_mfma_f32_16x16x32_bf16 v[42:45], v[134:137], v[198:201], v[42:45]
	v_mfma_f32_16x16x32_bf16 v[30:33], v[118:121], v[206:209], v[30:33]
	v_mfma_f32_16x16x32_bf16 v[26:29], v[134:137], v[206:209], v[26:29]
	v_mfma_f32_16x16x32_bf16 v[14:17], v[118:121], v[214:217], v[14:17]
	v_mfma_f32_16x16x32_bf16 v[10:13], v[134:137], v[214:217], v[10:13]
	s_setprio 0
	s_setprio 1
	v_mfma_f32_16x16x32_bf16 v[54:57], v[146:149], v[180:183], v[54:57]
	v_mfma_f32_16x16x32_bf16 v[50:53], v[172:175], v[180:183], v[50:53]
	v_mfma_f32_16x16x32_bf16 v[38:41], v[146:149], v[194:197], v[38:41]
	v_mfma_f32_16x16x32_bf16 v[34:37], v[172:175], v[194:197], v[34:37]
	v_mfma_f32_16x16x32_bf16 v[22:25], v[146:149], v[202:205], v[22:25]
	v_mfma_f32_16x16x32_bf16 v[18:21], v[172:175], v[202:205], v[18:21]
	v_mfma_f32_16x16x32_bf16 v[6:9], v[146:149], v[210:213], v[6:9]
	v_mfma_f32_16x16x32_bf16 v[2:5], v[172:175], v[210:213], v[2:5]
	v_mfma_f32_16x16x32_bf16 v[54:57], v[150:153], v[184:187], v[54:57]
	v_mfma_f32_16x16x32_bf16 v[50:53], v[176:179], v[184:187], v[50:53]
	v_mfma_f32_16x16x32_bf16 v[38:41], v[150:153], v[198:201], v[38:41]
	v_mfma_f32_16x16x32_bf16 v[34:37], v[176:179], v[198:201], v[34:37]
	v_mfma_f32_16x16x32_bf16 v[22:25], v[150:153], v[206:209], v[22:25]
	v_mfma_f32_16x16x32_bf16 v[18:21], v[176:179], v[206:209], v[18:21]
	v_mfma_f32_16x16x32_bf16 v[6:9], v[150:153], v[214:217], v[6:9]
	v_mfma_f32_16x16x32_bf16 v[2:5], v[176:179], v[214:217], v[2:5]
	s_setprio 0
	s_barrier
	s_add_i32 s45, s45, 2
	s_add_u32 s43, s43, 0x100
	s_addc_u32 s44, s44, 0
	s_cmp_gt_u32 s45, 41
	s_mov_b64 s[18:19], s[20:21]
	s_cbranch_scc0 .LBB0_966
	s_and_b64 vcc, exec, s[14:15]
	s_cbranch_vccz .LBB0_969
	s_barrier
.LBB0_969:
	v_lshl_or_b32 v172, s41, 8, v192
	v_lshl_add_u32 v176, s42, 8, v190
	v_ashrrev_i32_e32 v173, 31, v172
	v_lshlrev_b64 v[158:159], 1, v[172:173]
	v_ashrrev_i32_e32 v177, 31, v176
	v_lshl_add_u64 v[174:175], s[10:11], 0, v[158:159]
	v_lshlrev_b64 v[162:163], 11, v[176:177]
	v_lshl_add_u64 v[114:115], v[174:175], 0, v[162:163]
	global_load_dwordx4 v[194:197], v[114:115], off
	global_load_dwordx4 v[198:201], v[114:115], off offset:256
	v_or_b32_e32 v186, 16, v176
	v_ashrrev_i32_e32 v187, 31, v186
	v_or_b32_e32 v182, 32, v176
	v_lshlrev_b64 v[188:189], 11, v[186:187]
	v_ashrrev_i32_e32 v183, 31, v182
	v_or_b32_e32 v178, 48, v176
	v_lshl_add_u64 v[114:115], v[174:175], 0, v[188:189]
	v_lshlrev_b64 v[184:185], 11, v[182:183]
	v_ashrrev_i32_e32 v179, 31, v178
	global_load_dwordx4 v[150:153], v[114:115], off
	global_load_dwordx4 v[146:149], v[114:115], off offset:256
	v_lshl_add_u64 v[114:115], v[174:175], 0, v[184:185]
	v_lshlrev_b64 v[180:181], 11, v[178:179]
	global_load_dwordx4 v[134:137], v[114:115], off
	global_load_dwordx4 v[122:125], v[114:115], off offset:256
	v_lshl_add_u64 v[114:115], v[174:175], 0, v[180:181]
	global_load_dwordx4 v[118:121], v[114:115], off
	s_nop 0
	global_load_dwordx4 v[114:117], v[114:115], off offset:256
	s_waitcnt vmcnt(0)
	v_lshlrev_b32_e32 v202, 16, v194
	v_and_b32_e32 v203, 0xffff0000, v194
	v_lshlrev_b32_e32 v194, 16, v195
	v_and_b32_e32 v195, 0xffff0000, v195
	v_lshlrev_b32_e32 v204, 16, v196
	v_and_b32_e32 v205, 0xffff0000, v196
	v_lshlrev_b32_e32 v196, 16, v197
	v_and_b32_e32 v197, 0xffff0000, v197
	v_pk_add_f32 v[144:145], v[144:145], v[194:195]
	v_pk_add_f32 v[142:143], v[142:143], v[202:203]
	v_pk_add_f32 v[194:195], v[140:141], v[196:197]
	v_pk_add_f32 v[140:141], v[138:139], v[204:205]
	v_mul_f32_e32 v138, v143, v143
	v_mul_f32_e32 v139, v145, v145
	v_fmac_f32_e32 v138, v142, v142
	v_fmac_f32_e32 v139, v144, v144
	v_add_f32_e32 v138, v138, v139
	v_mul_f32_e32 v139, v141, v141
	v_mul_f32_e32 v196, v195, v195
	v_fmac_f32_e32 v139, v140, v140
	v_fmac_f32_e32 v196, v194, v194
	v_add_f32_e32 v139, v139, v196
	v_add_f32_e32 v196, v138, v139
	v_cvt_pk_bf16_f32 v138, v142, v143
	v_lshl_add_u64 v[142:143], s[10:11], 0, v[162:163]
	v_cvt_pk_bf16_f32 v139, v144, v145
	v_cvt_pk_bf16_f32 v140, v140, v141
	v_cvt_pk_bf16_f32 v141, v194, v195
	v_lshl_add_u64 v[142:143], v[142:143], 0, v[158:159]
	global_store_dwordx4 v[142:143], v[138:141], off
	v_lshlrev_b32_e32 v144, 16, v200
	v_and_b32_e32 v145, 0xffff0000, v200
	v_lshlrev_b32_e32 v138, 16, v198
	v_and_b32_e32 v139, 0xffff0000, v198
	v_lshlrev_b32_e32 v140, 16, v199
	v_and_b32_e32 v141, 0xffff0000, v199
	v_lshlrev_b32_e32 v158, 16, v201
	v_and_b32_e32 v159, 0xffff0000, v201
	v_pk_add_f32 v[132:133], v[132:133], v[140:141]
	v_pk_add_f32 v[130:131], v[130:131], v[138:139]
	v_pk_add_f32 v[138:139], v[128:129], v[158:159]
	v_pk_add_f32 v[128:129], v[126:127], v[144:145]
	v_mul_f32_e32 v126, v131, v131
	v_mul_f32_e32 v127, v133, v133
	v_fmac_f32_e32 v126, v130, v130
	v_fmac_f32_e32 v127, v132, v132
	v_add_f32_e32 v126, v126, v127
	v_mul_f32_e32 v127, v129, v129
	v_mul_f32_e32 v140, v139, v139
	v_fmac_f32_e32 v127, v128, v128
	v_fmac_f32_e32 v140, v138, v138
	v_add_f32_e32 v127, v127, v140
	v_add_f32_e32 v126, v126, v127
	v_add_f32_e32 v140, v196, v126
	v_cvt_pk_bf16_f32 v126, v130, v131
	v_cvt_pk_bf16_f32 v127, v132, v133
	v_cvt_pk_bf16_f32 v128, v128, v129
	v_cvt_pk_bf16_f32 v129, v138, v139
	global_store_dwordx4 v[142:143], v[126:129], off offset:256
	s_nop 1
	v_and_b32_e32 v127, 64, v222
	v_xor_b32_e32 v126, 16, v222
	v_add_u32_e32 v127, 64, v127
	v_cmp_lt_i32_e32 vcc, v126, v127
	v_xor_b32_e32 v129, 32, v222
	s_nop 0
	v_cndmask_b32_e32 v126, v222, v126, vcc
	v_lshlrev_b32_e32 v126, 2, v126
	ds_bpermute_b32 v128, v126, v140
	v_cmp_lt_i32_e32 vcc, v129, v127
	s_waitcnt lgkmcnt(0)
	v_add_f32_e32 v128, v140, v128
	v_cndmask_b32_e32 v127, v222, v129, vcc
	v_lshlrev_b32_e32 v127, 2, v127
	ds_bpermute_b32 v129, v127, v128
	s_waitcnt lgkmcnt(0)
	v_add_f32_e32 v226, v128, v129
.LBB0_971:
	v_lshlrev_b32_e32 v128, 16, v150
	s_waitcnt lgkmcnt(0)
	v_and_b32_e32 v129, 0xffff0000, v150
	v_lshlrev_b32_e32 v130, 16, v151
	v_and_b32_e32 v131, 0xffff0000, v151
	v_lshlrev_b32_e32 v132, 16, v152
	v_and_b32_e32 v133, 0xffff0000, v152
	v_lshlrev_b32_e32 v138, 16, v153
	v_and_b32_e32 v139, 0xffff0000, v153
	v_pk_add_f32 v[112:113], v[112:113], v[130:131]
	v_pk_add_f32 v[110:111], v[110:111], v[128:129]
	v_pk_add_f32 v[128:129], v[108:109], v[138:139]
	v_pk_add_f32 v[108:109], v[106:107], v[132:133]
	v_mul_f32_e32 v106, v111, v111
	v_mul_f32_e32 v107, v113, v113
	v_fmac_f32_e32 v106, v110, v110
	v_fmac_f32_e32 v107, v112, v112
	v_add_f32_e32 v106, v106, v107
	v_mul_f32_e32 v107, v109, v109
	v_mul_f32_e32 v130, v129, v129
	v_fmac_f32_e32 v107, v108, v108
	v_fmac_f32_e32 v130, v128, v128
	v_add_f32_e32 v107, v107, v130
	v_add_f32_e32 v132, v106, v107
	v_cvt_pk_bf16_f32 v106, v110, v111
	v_cvt_pk_bf16_f32 v107, v112, v113
	v_lshlrev_b32_e32 v110, 16, v146
	v_and_b32_e32 v111, 0xffff0000, v146
	v_lshlrev_b32_e32 v112, 16, v147
	v_and_b32_e32 v113, 0xffff0000, v147
	v_cvt_pk_bf16_f32 v108, v108, v109
	v_cvt_pk_bf16_f32 v109, v128, v129
	v_lshlrev_b32_e32 v128, 16, v148
	v_and_b32_e32 v129, 0xffff0000, v148
	v_pk_add_f32 v[104:105], v[104:105], v[112:113]
	v_pk_add_f32 v[102:103], v[102:103], v[110:111]
	v_lshlrev_b32_e32 v130, 16, v149
	v_and_b32_e32 v131, 0xffff0000, v149
	v_pk_add_f32 v[112:113], v[98:99], v[128:129]
	v_mul_f32_e32 v98, v103, v103
	v_mul_f32_e32 v99, v105, v105
	v_pk_add_f32 v[110:111], v[100:101], v[130:131]
	v_fmac_f32_e32 v98, v102, v102
	v_fmac_f32_e32 v99, v104, v104
	v_add_f32_e32 v98, v98, v99
	v_mul_f32_e32 v99, v113, v113
	v_mul_f32_e32 v100, v111, v111
	v_fmac_f32_e32 v99, v112, v112
	v_fmac_f32_e32 v100, v110, v110
	v_add_f32_e32 v99, v99, v100
	v_add_f32_e32 v98, v98, v99
	v_add_f32_e32 v101, v132, v98
	ds_bpermute_b32 v130, v126, v101
	v_lshl_add_u64 v[98:99], s[10:11], 0, v[188:189]
	v_lshl_add_u64 v[128:129], v[172:173], 1, v[98:99]
	global_store_dwordx4 v[128:129], v[106:109], off
	v_cvt_pk_bf16_f32 v100, v102, v103
	s_waitcnt lgkmcnt(0)
	v_add_f32_e32 v98, v101, v130
	ds_bpermute_b32 v99, v127, v98
	v_cvt_pk_bf16_f32 v101, v104, v105
	v_cvt_pk_bf16_f32 v102, v112, v113
	v_cvt_pk_bf16_f32 v103, v110, v111
	global_store_dwordx4 v[128:129], v[100:103], off offset:256
	s_waitcnt lgkmcnt(0)
	v_add_f32_e32 v227, v98, v99
.LBB0_973:
	v_lshlrev_b32_e32 v98, 16, v134
	s_waitcnt lgkmcnt(0)
	v_and_b32_e32 v99, 0xffff0000, v134
	v_lshlrev_b32_e32 v100, 16, v135
	v_and_b32_e32 v101, 0xffff0000, v135
	v_lshlrev_b32_e32 v102, 16, v136
	v_and_b32_e32 v103, 0xffff0000, v136
	v_lshlrev_b32_e32 v104, 16, v137
	v_and_b32_e32 v105, 0xffff0000, v137
	v_pk_add_f32 v[96:97], v[96:97], v[100:101]
	v_pk_add_f32 v[94:95], v[94:95], v[98:99]
	v_pk_add_f32 v[98:99], v[92:93], v[104:105]
	v_pk_add_f32 v[92:93], v[90:91], v[102:103]
	v_mul_f32_e32 v90, v95, v95
	v_mul_f32_e32 v91, v97, v97
	v_fmac_f32_e32 v90, v94, v94
	v_fmac_f32_e32 v91, v96, v96
	v_add_f32_e32 v90, v90, v91
	v_mul_f32_e32 v91, v93, v93
	v_mul_f32_e32 v100, v99, v99
	v_fmac_f32_e32 v91, v92, v92
	v_fmac_f32_e32 v100, v98, v98
	v_add_f32_e32 v91, v91, v100
	v_add_f32_e32 v102, v90, v91
	v_cvt_pk_bf16_f32 v90, v94, v95
	v_cvt_pk_bf16_f32 v91, v96, v97
	v_lshlrev_b32_e32 v94, 16, v122
	v_and_b32_e32 v95, 0xffff0000, v122
	v_lshlrev_b32_e32 v96, 16, v123
	v_and_b32_e32 v97, 0xffff0000, v123
	v_cvt_pk_bf16_f32 v92, v92, v93
	v_cvt_pk_bf16_f32 v93, v98, v99
	v_lshlrev_b32_e32 v98, 16, v124
	v_and_b32_e32 v99, 0xffff0000, v124
	v_pk_add_f32 v[88:89], v[88:89], v[96:97]
	v_pk_add_f32 v[86:87], v[86:87], v[94:95]
	v_lshlrev_b32_e32 v100, 16, v125
	v_and_b32_e32 v101, 0xffff0000, v125
	v_pk_add_f32 v[96:97], v[82:83], v[98:99]
	v_mul_f32_e32 v82, v87, v87
	v_mul_f32_e32 v83, v89, v89
	v_pk_add_f32 v[94:95], v[84:85], v[100:101]
	v_fmac_f32_e32 v82, v86, v86
	v_fmac_f32_e32 v83, v88, v88
	v_add_f32_e32 v82, v82, v83
	v_mul_f32_e32 v83, v97, v97
	v_mul_f32_e32 v84, v95, v95
	v_fmac_f32_e32 v83, v96, v96
	v_fmac_f32_e32 v84, v94, v94
	v_add_f32_e32 v83, v83, v84
	v_add_f32_e32 v82, v82, v83
	v_add_f32_e32 v85, v102, v82
	ds_bpermute_b32 v100, v126, v85
	v_lshl_add_u64 v[82:83], s[10:11], 0, v[184:185]
	v_lshl_add_u64 v[98:99], v[172:173], 1, v[82:83]
	global_store_dwordx4 v[98:99], v[90:93], off
	v_cvt_pk_bf16_f32 v84, v86, v87
	s_waitcnt lgkmcnt(0)
	v_add_f32_e32 v82, v85, v100
	ds_bpermute_b32 v83, v127, v82
	v_cvt_pk_bf16_f32 v85, v88, v89
	v_cvt_pk_bf16_f32 v86, v96, v97
	v_cvt_pk_bf16_f32 v87, v94, v95
	global_store_dwordx4 v[98:99], v[84:87], off offset:256
	s_waitcnt lgkmcnt(0)
	v_add_f32_e32 v228, v82, v83
.LBB0_975:
	v_lshlrev_b32_e32 v82, 16, v118
	s_waitcnt lgkmcnt(0)
	v_and_b32_e32 v83, 0xffff0000, v118
	v_lshlrev_b32_e32 v84, 16, v119
	v_and_b32_e32 v85, 0xffff0000, v119
	v_lshlrev_b32_e32 v86, 16, v120
	v_and_b32_e32 v87, 0xffff0000, v120
	v_lshlrev_b32_e32 v88, 16, v121
	v_and_b32_e32 v89, 0xffff0000, v121
	v_pk_add_f32 v[80:81], v[80:81], v[84:85]
	v_pk_add_f32 v[78:79], v[78:79], v[82:83]
	v_pk_add_f32 v[82:83], v[76:77], v[88:89]
	v_pk_add_f32 v[76:77], v[74:75], v[86:87]
	v_mul_f32_e32 v74, v79, v79
	v_mul_f32_e32 v75, v81, v81
	v_fmac_f32_e32 v74, v78, v78
	v_fmac_f32_e32 v75, v80, v80
	v_add_f32_e32 v74, v74, v75
	v_mul_f32_e32 v75, v77, v77
	v_mul_f32_e32 v84, v83, v83
	v_fmac_f32_e32 v75, v76, v76
	v_fmac_f32_e32 v84, v82, v82
	v_add_f32_e32 v75, v75, v84
	v_add_f32_e32 v86, v74, v75
	v_cvt_pk_bf16_f32 v74, v78, v79
	v_cvt_pk_bf16_f32 v75, v80, v81
	v_lshlrev_b32_e32 v78, 16, v114
	v_and_b32_e32 v79, 0xffff0000, v114
	v_lshlrev_b32_e32 v80, 16, v115
	v_and_b32_e32 v81, 0xffff0000, v115
	v_cvt_pk_bf16_f32 v76, v76, v77
	v_cvt_pk_bf16_f32 v77, v82, v83
	v_lshlrev_b32_e32 v82, 16, v116
	v_and_b32_e32 v83, 0xffff0000, v116
	v_pk_add_f32 v[72:73], v[72:73], v[80:81]
	v_pk_add_f32 v[70:71], v[70:71], v[78:79]
	v_lshlrev_b32_e32 v84, 16, v117
	v_and_b32_e32 v85, 0xffff0000, v117
	v_pk_add_f32 v[80:81], v[66:67], v[82:83]
	v_mul_f32_e32 v66, v71, v71
	v_mul_f32_e32 v67, v73, v73
	v_pk_add_f32 v[78:79], v[68:69], v[84:85]
	v_fmac_f32_e32 v66, v70, v70
	v_fmac_f32_e32 v67, v72, v72
	v_add_f32_e32 v66, v66, v67
	v_mul_f32_e32 v67, v81, v81
	v_mul_f32_e32 v68, v79, v79
	v_fmac_f32_e32 v67, v80, v80
	v_fmac_f32_e32 v68, v78, v78
	v_add_f32_e32 v67, v67, v68
	v_add_f32_e32 v66, v66, v67
	v_add_f32_e32 v69, v86, v66
	ds_bpermute_b32 v84, v126, v69
	v_lshl_add_u64 v[66:67], s[10:11], 0, v[180:181]
	v_lshl_add_u64 v[82:83], v[172:173], 1, v[66:67]
	global_store_dwordx4 v[82:83], v[74:77], off
	v_cvt_pk_bf16_f32 v68, v70, v71
	s_waitcnt lgkmcnt(0)
	v_add_f32_e32 v66, v69, v84
	ds_bpermute_b32 v67, v127, v66
	v_cvt_pk_bf16_f32 v69, v72, v73
	v_cvt_pk_bf16_f32 v70, v80, v81
	v_cvt_pk_bf16_f32 v71, v78, v79
	global_store_dwordx4 v[82:83], v[68:71], off offset:256
	s_waitcnt lgkmcnt(0)
	v_add_f32_e32 v229, v66, v67
	v_mbcnt_lo_u32_b32 v230, -1, 0
	v_mbcnt_hi_u32_b32 v230, -1, v230
	v_bfe_u32 v230, v230, 4, 2
	v_cmp_eq_u32_e64 s[18:19], 0, v230
	v_lshl_add_u32 v232, v230, 4, v178
	v_subrev_u32_e32 v232, 48, v232
	v_cndmask_b32_e64 v229, v229, v226, s[18:19]
	v_cmp_eq_u32_e64 s[18:19], 1, v230
	v_ashrrev_i32_e32 v233, 31, v232
	v_lshl_add_u64 v[234:235], v[232:233], 2, s[12:13]
	v_cndmask_b32_e64 v229, v229, v227, s[18:19]
	v_cmp_eq_u32_e64 s[18:19], 2, v230
	s_nop 1
	v_cndmask_b32_e64 v229, v229, v228, s[18:19]
	global_atomic_add_f32 v[234:235], v229, off
.LBB0_977:
	v_add_u32_e32 v106, 0x80, v176
	v_ashrrev_i32_e32 v107, 31, v106
	v_lshlrev_b64 v[112:113], 11, v[106:107]
	s_waitcnt lgkmcnt(0)
	v_lshl_add_u64 v[66:67], v[174:175], 0, v[112:113]
	global_load_dwordx4 v[108:111], v[66:67], off
	global_load_dwordx4 v[90:93], v[66:67], off offset:256
	v_add_u32_e32 v102, 0x90, v176
	v_ashrrev_i32_e32 v103, 31, v102
	v_add_u32_e32 v98, 0xa0, v176
	v_lshlrev_b64 v[104:105], 11, v[102:103]
	v_ashrrev_i32_e32 v99, 31, v98
	v_add_u32_e32 v94, 0xb0, v176
	v_lshl_add_u64 v[66:67], v[174:175], 0, v[104:105]
	v_lshlrev_b64 v[100:101], 11, v[98:99]
	v_ashrrev_i32_e32 v95, 31, v94
	global_load_dwordx4 v[86:89], v[66:67], off
	global_load_dwordx4 v[82:85], v[66:67], off offset:256
	v_lshl_add_u64 v[66:67], v[174:175], 0, v[100:101]
	v_lshlrev_b64 v[96:97], 11, v[94:95]
	global_load_dwordx4 v[78:81], v[66:67], off
	global_load_dwordx4 v[74:77], v[66:67], off offset:256
	v_lshl_add_u64 v[66:67], v[174:175], 0, v[96:97]
	global_load_dwordx4 v[70:73], v[66:67], off
	s_nop 0
	global_load_dwordx4 v[66:69], v[66:67], off offset:256
	s_waitcnt vmcnt(7)
	v_lshlrev_b32_e32 v114, 16, v108
	v_and_b32_e32 v115, 0xffff0000, v108
	v_lshlrev_b32_e32 v108, 16, v109
	v_and_b32_e32 v109, 0xffff0000, v109
	v_lshlrev_b32_e32 v116, 16, v110
	v_and_b32_e32 v117, 0xffff0000, v110
	v_lshlrev_b32_e32 v110, 16, v111
	v_and_b32_e32 v111, 0xffff0000, v111
	v_pk_add_f32 v[64:65], v[64:65], v[108:109]
	v_pk_add_f32 v[62:63], v[62:63], v[114:115]
	v_pk_add_f32 v[108:109], v[60:61], v[110:111]
	v_mul_f32_e32 v60, v63, v63
	v_mul_f32_e32 v61, v65, v65
	v_pk_add_f32 v[58:59], v[58:59], v[116:117]
	v_fmac_f32_e32 v60, v62, v62
	v_fmac_f32_e32 v61, v64, v64
	v_add_f32_e32 v60, v60, v61
	v_mul_f32_e32 v61, v59, v59
	v_mul_f32_e32 v110, v109, v109
	v_fmac_f32_e32 v61, v58, v58
	v_fmac_f32_e32 v110, v108, v108
	v_add_f32_e32 v61, v61, v110
	v_add_f32_e32 v110, v60, v61
	v_cvt_pk_bf16_f32 v60, v62, v63
	v_cvt_pk_bf16_f32 v61, v64, v65
	v_cvt_pk_bf16_f32 v62, v58, v59
	v_lshl_add_u64 v[58:59], s[10:11], 0, v[112:113]
	v_cvt_pk_bf16_f32 v63, v108, v109
	v_lshl_add_u64 v[58:59], v[172:173], 1, v[58:59]
	global_store_dwordx4 v[58:59], v[60:63], off
	s_waitcnt vmcnt(7)
	v_lshlrev_b32_e32 v64, 16, v92
	v_and_b32_e32 v65, 0xffff0000, v92
	v_lshlrev_b32_e32 v60, 16, v90
	v_and_b32_e32 v61, 0xffff0000, v90
	v_lshlrev_b32_e32 v62, 16, v91
	v_and_b32_e32 v63, 0xffff0000, v91
	v_lshlrev_b32_e32 v90, 16, v93
	v_and_b32_e32 v91, 0xffff0000, v93
	v_pk_add_f32 v[56:57], v[56:57], v[62:63]
	v_pk_add_f32 v[54:55], v[54:55], v[60:61]
	v_pk_add_f32 v[60:61], v[52:53], v[90:91]
	v_pk_add_f32 v[52:53], v[50:51], v[64:65]
	v_mul_f32_e32 v50, v55, v55
	v_mul_f32_e32 v51, v57, v57
	v_fmac_f32_e32 v50, v54, v54
	v_fmac_f32_e32 v51, v56, v56
	v_add_f32_e32 v50, v50, v51
	v_mul_f32_e32 v51, v53, v53
	v_mul_f32_e32 v62, v61, v61
	v_fmac_f32_e32 v51, v52, v52
	v_fmac_f32_e32 v62, v60, v60
	v_add_f32_e32 v51, v51, v62
	v_add_f32_e32 v50, v50, v51
	v_add_f32_e32 v62, v110, v50
	v_cvt_pk_bf16_f32 v50, v54, v55
	v_cvt_pk_bf16_f32 v51, v56, v57
	v_cvt_pk_bf16_f32 v52, v52, v53
	v_cvt_pk_bf16_f32 v53, v60, v61
	global_store_dwordx4 v[58:59], v[50:53], off offset:256
	ds_bpermute_b32 v50, v126, v62
	s_waitcnt lgkmcnt(0)
	v_add_f32_e32 v50, v62, v50
	ds_bpermute_b32 v51, v127, v50
	s_waitcnt lgkmcnt(0)
	v_add_f32_e32 v226, v50, v51
.LBB0_979:
	s_waitcnt vmcnt(7)
	v_lshlrev_b32_e32 v50, 16, v86
	s_waitcnt lgkmcnt(0)
	v_and_b32_e32 v51, 0xffff0000, v86
	v_lshlrev_b32_e32 v52, 16, v87
	v_and_b32_e32 v53, 0xffff0000, v87
	v_lshlrev_b32_e32 v54, 16, v88
	v_and_b32_e32 v55, 0xffff0000, v88
	v_lshlrev_b32_e32 v56, 16, v89
	v_and_b32_e32 v57, 0xffff0000, v89
	v_pk_add_f32 v[48:49], v[48:49], v[52:53]
	v_pk_add_f32 v[46:47], v[46:47], v[50:51]
	v_pk_add_f32 v[50:51], v[44:45], v[56:57]
	v_pk_add_f32 v[44:45], v[42:43], v[54:55]
	v_mul_f32_e32 v42, v47, v47
	v_mul_f32_e32 v43, v49, v49
	v_fmac_f32_e32 v42, v46, v46
	v_fmac_f32_e32 v43, v48, v48
	v_add_f32_e32 v42, v42, v43
	v_mul_f32_e32 v43, v45, v45
	v_mul_f32_e32 v52, v51, v51
	v_fmac_f32_e32 v43, v44, v44
	v_fmac_f32_e32 v52, v50, v50
	v_add_f32_e32 v43, v43, v52
	v_add_f32_e32 v54, v42, v43
	v_cvt_pk_bf16_f32 v42, v46, v47
	v_cvt_pk_bf16_f32 v43, v48, v49
	s_waitcnt vmcnt(6)
	v_lshlrev_b32_e32 v46, 16, v82
	v_and_b32_e32 v47, 0xffff0000, v82
	v_lshlrev_b32_e32 v48, 16, v83
	v_and_b32_e32 v49, 0xffff0000, v83
	v_cvt_pk_bf16_f32 v44, v44, v45
	v_cvt_pk_bf16_f32 v45, v50, v51
	v_lshlrev_b32_e32 v50, 16, v84
	v_and_b32_e32 v51, 0xffff0000, v84
	v_pk_add_f32 v[40:41], v[40:41], v[48:49]
	v_pk_add_f32 v[38:39], v[38:39], v[46:47]
	v_lshlrev_b32_e32 v52, 16, v85
	v_and_b32_e32 v53, 0xffff0000, v85
	v_pk_add_f32 v[48:49], v[34:35], v[50:51]
	v_mul_f32_e32 v34, v39, v39
	v_mul_f32_e32 v35, v41, v41
	v_pk_add_f32 v[46:47], v[36:37], v[52:53]
	v_fmac_f32_e32 v34, v38, v38
	v_fmac_f32_e32 v35, v40, v40
	v_add_f32_e32 v34, v34, v35
	v_mul_f32_e32 v35, v49, v49
	v_mul_f32_e32 v36, v47, v47
	v_fmac_f32_e32 v35, v48, v48
	v_fmac_f32_e32 v36, v46, v46
	v_add_f32_e32 v35, v35, v36
	v_add_f32_e32 v34, v34, v35
	v_add_f32_e32 v37, v54, v34
	ds_bpermute_b32 v52, v126, v37
	v_lshl_add_u64 v[34:35], s[10:11], 0, v[104:105]
	v_lshl_add_u64 v[50:51], v[172:173], 1, v[34:35]
	global_store_dwordx4 v[50:51], v[42:45], off
	v_cvt_pk_bf16_f32 v36, v38, v39
	s_waitcnt lgkmcnt(0)
	v_add_f32_e32 v34, v37, v52
	ds_bpermute_b32 v35, v127, v34
	v_cvt_pk_bf16_f32 v37, v40, v41
	v_cvt_pk_bf16_f32 v38, v48, v49
	v_cvt_pk_bf16_f32 v39, v46, v47
	global_store_dwordx4 v[50:51], v[36:39], off offset:256
	s_waitcnt lgkmcnt(0)
	v_add_f32_e32 v227, v34, v35
.LBB0_981:
	s_waitcnt vmcnt(7)
	v_lshlrev_b32_e32 v34, 16, v78
	s_waitcnt lgkmcnt(0)
	v_and_b32_e32 v35, 0xffff0000, v78
	v_lshlrev_b32_e32 v36, 16, v79
	v_and_b32_e32 v37, 0xffff0000, v79
	v_lshlrev_b32_e32 v38, 16, v80
	v_and_b32_e32 v39, 0xffff0000, v80
	v_lshlrev_b32_e32 v40, 16, v81
	v_and_b32_e32 v41, 0xffff0000, v81
	v_pk_add_f32 v[32:33], v[32:33], v[36:37]
	v_pk_add_f32 v[30:31], v[30:31], v[34:35]
	v_pk_add_f32 v[34:35], v[28:29], v[40:41]
	v_pk_add_f32 v[28:29], v[26:27], v[38:39]
	v_mul_f32_e32 v26, v31, v31
	v_mul_f32_e32 v27, v33, v33
	v_fmac_f32_e32 v26, v30, v30
	v_fmac_f32_e32 v27, v32, v32
	v_add_f32_e32 v26, v26, v27
	v_mul_f32_e32 v27, v29, v29
	v_mul_f32_e32 v36, v35, v35
	v_fmac_f32_e32 v27, v28, v28
	v_fmac_f32_e32 v36, v34, v34
	v_add_f32_e32 v27, v27, v36
	v_add_f32_e32 v38, v26, v27
	v_cvt_pk_bf16_f32 v26, v30, v31
	v_cvt_pk_bf16_f32 v27, v32, v33
	s_waitcnt vmcnt(6)
	v_lshlrev_b32_e32 v30, 16, v74
	v_and_b32_e32 v31, 0xffff0000, v74
	v_lshlrev_b32_e32 v32, 16, v75
	v_and_b32_e32 v33, 0xffff0000, v75
	v_cvt_pk_bf16_f32 v28, v28, v29
	v_cvt_pk_bf16_f32 v29, v34, v35
	v_lshlrev_b32_e32 v34, 16, v76
	v_and_b32_e32 v35, 0xffff0000, v76
	v_pk_add_f32 v[24:25], v[24:25], v[32:33]
	v_pk_add_f32 v[22:23], v[22:23], v[30:31]
	v_lshlrev_b32_e32 v36, 16, v77
	v_and_b32_e32 v37, 0xffff0000, v77
	v_pk_add_f32 v[32:33], v[18:19], v[34:35]
	v_mul_f32_e32 v18, v23, v23
	v_mul_f32_e32 v19, v25, v25
	v_pk_add_f32 v[30:31], v[20:21], v[36:37]
	v_fmac_f32_e32 v18, v22, v22
	v_fmac_f32_e32 v19, v24, v24
	v_add_f32_e32 v18, v18, v19
	v_mul_f32_e32 v19, v33, v33
	v_mul_f32_e32 v20, v31, v31
	v_fmac_f32_e32 v19, v32, v32
	v_fmac_f32_e32 v20, v30, v30
	v_add_f32_e32 v19, v19, v20
	v_add_f32_e32 v18, v18, v19
	v_add_f32_e32 v21, v38, v18
	ds_bpermute_b32 v36, v126, v21
	v_lshl_add_u64 v[18:19], s[10:11], 0, v[100:101]
	v_lshl_add_u64 v[34:35], v[172:173], 1, v[18:19]
	global_store_dwordx4 v[34:35], v[26:29], off
	v_cvt_pk_bf16_f32 v20, v22, v23
	s_waitcnt lgkmcnt(0)
	v_add_f32_e32 v18, v21, v36
	ds_bpermute_b32 v19, v127, v18
	v_cvt_pk_bf16_f32 v21, v24, v25
	v_cvt_pk_bf16_f32 v22, v32, v33
	v_cvt_pk_bf16_f32 v23, v30, v31
	global_store_dwordx4 v[34:35], v[20:23], off offset:256
	s_waitcnt lgkmcnt(0)
	v_add_f32_e32 v228, v18, v19
.LBB0_983:
	s_waitcnt vmcnt(7)
	v_lshlrev_b32_e32 v18, 16, v70
	s_waitcnt lgkmcnt(0)
	v_and_b32_e32 v19, 0xffff0000, v70
	v_lshlrev_b32_e32 v20, 16, v71
	v_and_b32_e32 v21, 0xffff0000, v71
	v_lshlrev_b32_e32 v22, 16, v72
	v_and_b32_e32 v23, 0xffff0000, v72
	v_lshlrev_b32_e32 v24, 16, v73
	v_and_b32_e32 v25, 0xffff0000, v73
	v_pk_add_f32 v[16:17], v[16:17], v[20:21]
	v_pk_add_f32 v[14:15], v[14:15], v[18:19]
	v_pk_add_f32 v[18:19], v[12:13], v[24:25]
	v_pk_add_f32 v[12:13], v[10:11], v[22:23]
	v_mul_f32_e32 v10, v15, v15
	v_mul_f32_e32 v11, v17, v17
	v_fmac_f32_e32 v10, v14, v14
	v_fmac_f32_e32 v11, v16, v16
	v_add_f32_e32 v10, v10, v11
	v_mul_f32_e32 v11, v13, v13
	v_mul_f32_e32 v20, v19, v19
	v_fmac_f32_e32 v11, v12, v12
	v_fmac_f32_e32 v20, v18, v18
	v_add_f32_e32 v11, v11, v20
	v_add_f32_e32 v22, v10, v11
	v_cvt_pk_bf16_f32 v10, v14, v15
	v_cvt_pk_bf16_f32 v11, v16, v17
	s_waitcnt vmcnt(6)
	v_lshlrev_b32_e32 v14, 16, v66
	v_and_b32_e32 v15, 0xffff0000, v66
	v_lshlrev_b32_e32 v16, 16, v67
	v_and_b32_e32 v17, 0xffff0000, v67
	v_cvt_pk_bf16_f32 v12, v12, v13
	v_cvt_pk_bf16_f32 v13, v18, v19
	v_lshlrev_b32_e32 v18, 16, v68
	v_and_b32_e32 v19, 0xffff0000, v68
	v_pk_add_f32 v[8:9], v[8:9], v[16:17]
	v_pk_add_f32 v[6:7], v[6:7], v[14:15]
	v_lshlrev_b32_e32 v20, 16, v69
	v_and_b32_e32 v21, 0xffff0000, v69
	v_pk_add_f32 v[16:17], v[2:3], v[18:19]
	v_mul_f32_e32 v2, v7, v7
	v_mul_f32_e32 v3, v9, v9
	v_pk_add_f32 v[14:15], v[4:5], v[20:21]
	v_fmac_f32_e32 v2, v6, v6
	v_fmac_f32_e32 v3, v8, v8
	v_add_f32_e32 v2, v2, v3
	v_mul_f32_e32 v3, v17, v17
	v_mul_f32_e32 v4, v15, v15
	v_fmac_f32_e32 v3, v16, v16
	v_fmac_f32_e32 v4, v14, v14
	v_add_f32_e32 v3, v3, v4
	v_add_f32_e32 v2, v2, v3
	v_add_f32_e32 v5, v22, v2
	ds_bpermute_b32 v20, v126, v5
	v_lshl_add_u64 v[2:3], s[10:11], 0, v[96:97]
	v_lshl_add_u64 v[18:19], v[172:173], 1, v[2:3]
	global_store_dwordx4 v[18:19], v[10:13], off
	v_cvt_pk_bf16_f32 v4, v6, v7
	s_waitcnt lgkmcnt(0)
	v_add_f32_e32 v2, v5, v20
	ds_bpermute_b32 v3, v127, v2
	v_cvt_pk_bf16_f32 v5, v8, v9
	v_cvt_pk_bf16_f32 v6, v16, v17
	v_cvt_pk_bf16_f32 v7, v14, v15
	global_store_dwordx4 v[18:19], v[4:7], off offset:256
	s_waitcnt lgkmcnt(0)
	v_add_f32_e32 v229, v2, v3
	v_mbcnt_lo_u32_b32 v230, -1, 0
	v_mbcnt_hi_u32_b32 v230, -1, v230
	v_bfe_u32 v230, v230, 4, 2
	v_cmp_eq_u32_e64 s[18:19], 0, v230
	v_lshl_add_u32 v232, v230, 4, v94
	v_subrev_u32_e32 v232, 48, v232
	v_cndmask_b32_e64 v229, v229, v226, s[18:19]
	v_cmp_eq_u32_e64 s[18:19], 1, v230
	v_ashrrev_i32_e32 v233, 31, v232
	v_lshl_add_u64 v[234:235], v[232:233], 2, s[12:13]
	v_cndmask_b32_e64 v229, v229, v227, s[18:19]
	v_cmp_eq_u32_e64 s[18:19], 2, v230
	s_nop 1
	v_cndmask_b32_e64 v229, v229, v228, s[18:19]
	global_atomic_add_f32 v[234:235], v229, off
.LBB0_985:
	s_mov_b32 s98, 1
	s_and_b64 vcc, exec, s[6:7]
	s_mov_b64 s[6:7], -1
	s_cbranch_vccnz .LBB0_954
	s_andn2_b64 vcc, exec, s[2:3]
	s_cbranch_vccnz .LBB0_953
	s_barrier
	s_branch .LBB0_953

	.amdhsa_kernel _Z8yoco_fwd4Args
		.amdhsa_group_segment_fixed_size 0
		.amdhsa_private_segment_fixed_size 0
		.amdhsa_kernarg_size 408
		.amdhsa_user_sgpr_count 2
		.amdhsa_user_sgpr_dispatch_ptr 0
		.amdhsa_user_sgpr_queue_ptr 0
		.amdhsa_user_sgpr_kernarg_segment_ptr 1
		.amdhsa_user_sgpr_dispatch_id 0
		.amdhsa_user_sgpr_kernarg_preload_length 0
		.amdhsa_user_sgpr_kernarg_preload_offset 0
		.amdhsa_user_sgpr_private_segment_size 0
		.amdhsa_uses_dynamic_stack 0
		.amdhsa_enable_private_segment 0
		.amdhsa_system_sgpr_workgroup_id_x 1
		.amdhsa_system_sgpr_workgroup_id_y 0
		.amdhsa_system_sgpr_workgroup_id_z 0
		.amdhsa_system_sgpr_workgroup_info 0
		.amdhsa_system_vgpr_workitem_id 2
		.amdhsa_next_free_vgpr 256
		.amdhsa_next_free_sgpr 102
		.amdhsa_accum_offset 256
		.amdhsa_reserve_vcc 1
		.amdhsa_float_round_mode_32 0
		.amdhsa_float_round_mode_16_64 0
		.amdhsa_float_denorm_mode_32 3
		.amdhsa_float_denorm_mode_16_64 3
		.amdhsa_dx10_clamp 1
		.amdhsa_ieee_mode 1
		.amdhsa_fp16_overflow 0
		.amdhsa_tg_split 0
		.amdhsa_exception_fp_ieee_invalid_op 0
		.amdhsa_exception_fp_denorm_src 0
		.amdhsa_exception_fp_ieee_div_zero 0
		.amdhsa_exception_fp_ieee_overflow 0
		.amdhsa_exception_fp_ieee_underflow 0
		.amdhsa_exception_fp_ieee_inexact 0
		.amdhsa_exception_int_div_zero 0
	.end_amdhsa_kernel

amdhsa.kernels:
  - .agpr_count:     0
    .args:
      - .offset:         0
        .size:           152
        .value_kind:     by_value
      - .offset:         152
        .size:           4
        .value_kind:     hidden_block_count_x
      - .offset:         156
        .size:           4
        .value_kind:     hidden_block_count_y
      - .offset:         160
        .size:           4
        .value_kind:     hidden_block_count_z
      - .offset:         164
        .size:           2
        .value_kind:     hidden_group_size_x
      - .offset:         166
        .size:           2
        .value_kind:     hidden_group_size_y
      - .offset:         168
        .size:           2
        .value_kind:     hidden_group_size_z
      - .offset:         170
        .size:           2
        .value_kind:     hidden_remainder_x
      - .offset:         172
        .size:           2
        .value_kind:     hidden_remainder_y
      - .offset:         174
        .size:           2
        .value_kind:     hidden_remainder_z
      - .offset:         192
        .size:           8
        .value_kind:     hidden_global_offset_x
      - .offset:         200
        .size:           8
        .value_kind:     hidden_global_offset_y
      - .offset:         208
        .size:           8
        .value_kind:     hidden_global_offset_z
      - .offset:         216
        .size:           2
        .value_kind:     hidden_grid_dims
      - .offset:         240
        .size:           8
        .value_kind:     hidden_multigrid_sync_arg
      - .offset:         272
        .size:           4
        .value_kind:     hidden_dynamic_lds_size
    .group_segment_fixed_size: 0
    .kernarg_segment_align: 8
    .kernarg_segment_size: 408
    .language:       OpenCL C
    .language_version:
      - 2
      - 0
    .max_flat_workgroup_size: 512
    .name:           _Z8yoco_fwd4Args
    .private_segment_fixed_size: 0
    .sgpr_count:     108
    .sgpr_spill_count: 134
    .symbol:         _Z8yoco_fwd4Args.kd
    .uniform_work_group_size: 1
    .uses_dynamic_stack: false
    .vgpr_count:     256
    .vgpr_spill_count: 0
    .wavefront_size: 64
